# v15 + snake MFMA order inside each 8-group (consecutive MFMAs share an operand)
# speedup vs baseline: 1.0003x; 1.0003x over previous
.LBB0_422:
	ds_read_b128 v[146:149], v154
	ds_read_b128 v[158:161], v154 offset:1024
	ds_read_b128 v[162:165], v154 offset:2048
	ds_read_b128 v[166:169], v154 offset:3072
	ds_read_b128 v[170:173], v155
	ds_read_b128 v[178:181], v155 offset:1024
	ds_read_b128 v[182:185], v155 offset:2048
	ds_read_b128 v[186:189], v155 offset:3072
	s_add_u32 s30, s28, 0xfc000
	s_addc_u32 s31, s29, 0
	s_cmp_eq_u32 s53, 60
	s_cselect_b32 s36, s21, s30
	s_cselect_b32 s37, s9, s31
	s_cselect_b32 s34, s50, s51
	s_cselect_b32 s35, s19, s52
	s_add_u32 s30, s36, 0x100000
	s_addc_u32 s31, s37, 0
	s_add_i32 m0, s1, 0xc000
	ds_read_b128 v[190:193], v156
	ds_read_b128 v[194:197], v156 offset:1024
	ds_read_b128 v[198:201], v156 offset:2048
	ds_read_b128 v[202:205], v156 offset:3072
	ds_read_b128 v[206:209], v156 offset:4096
	ds_read_b128 v[210:213], v156 offset:5120
	ds_read_b128 v[214:217], v156 offset:6144
	ds_read_b128 v[218:221], v156 offset:7168
	global_load_lds_dwordx4 v138, s[28:29]
	s_add_i32 m0, s1, 0xe000
	s_nop 0
	global_load_lds_dwordx4 v140, s[28:29]
	s_waitcnt vmcnt(8)
	s_waitcnt lgkmcnt(0)
	s_setprio 1
	s_barrier
	v_mfma_f32_16x16x32_bf16 v[126:129], v[146:149], v[190:193], v[126:129]
	v_mfma_f32_16x16x32_bf16 v[122:125], v[162:165], v[190:193], v[122:125]
	v_mfma_f32_16x16x32_bf16 v[106:109], v[162:165], v[198:201], v[106:109]
	v_mfma_f32_16x16x32_bf16 v[110:113], v[146:149], v[198:201], v[110:113]
	v_mfma_f32_16x16x32_bf16 v[94:97], v[146:149], v[206:209], v[94:97]
	v_mfma_f32_16x16x32_bf16 v[90:93], v[162:165], v[206:209], v[90:93]
	v_mfma_f32_16x16x32_bf16 v[74:77], v[162:165], v[214:217], v[74:77]
	v_mfma_f32_16x16x32_bf16 v[78:81], v[146:149], v[214:217], v[78:81]
	v_mfma_f32_16x16x32_bf16 v[126:129], v[158:161], v[194:197], v[126:129]
	v_mfma_f32_16x16x32_bf16 v[122:125], v[166:169], v[194:197], v[122:125]
	v_mfma_f32_16x16x32_bf16 v[106:109], v[166:169], v[202:205], v[106:109]
	v_mfma_f32_16x16x32_bf16 v[110:113], v[158:161], v[202:205], v[110:113]
	v_mfma_f32_16x16x32_bf16 v[94:97], v[158:161], v[210:213], v[94:97]
	v_mfma_f32_16x16x32_bf16 v[90:93], v[166:169], v[210:213], v[90:93]
	v_mfma_f32_16x16x32_bf16 v[74:77], v[166:169], v[218:221], v[74:77]
	v_mfma_f32_16x16x32_bf16 v[78:81], v[158:161], v[218:221], v[78:81]
	s_setprio 0
	s_setprio 1
	v_mfma_f32_16x16x32_bf16 v[118:121], v[170:173], v[190:193], v[118:121]
	v_mfma_f32_16x16x32_bf16 v[114:117], v[182:185], v[190:193], v[114:117]
	v_mfma_f32_16x16x32_bf16 v[98:101], v[182:185], v[198:201], v[98:101]
	v_mfma_f32_16x16x32_bf16 v[102:105], v[170:173], v[198:201], v[102:105]
	v_mfma_f32_16x16x32_bf16 v[86:89], v[170:173], v[206:209], v[86:89]
	v_mfma_f32_16x16x32_bf16 v[82:85], v[182:185], v[206:209], v[82:85]
	v_mfma_f32_16x16x32_bf16 v[66:69], v[182:185], v[214:217], v[66:69]
	v_mfma_f32_16x16x32_bf16 v[70:73], v[170:173], v[214:217], v[70:73]
	v_mfma_f32_16x16x32_bf16 v[118:121], v[178:181], v[194:197], v[118:121]
	v_mfma_f32_16x16x32_bf16 v[114:117], v[186:189], v[194:197], v[114:117]
	v_mfma_f32_16x16x32_bf16 v[98:101], v[186:189], v[202:205], v[98:101]
	v_mfma_f32_16x16x32_bf16 v[102:105], v[178:181], v[202:205], v[102:105]
	v_mfma_f32_16x16x32_bf16 v[86:89], v[178:181], v[210:213], v[86:89]
	v_mfma_f32_16x16x32_bf16 v[82:85], v[186:189], v[210:213], v[82:85]
	v_mfma_f32_16x16x32_bf16 v[66:69], v[186:189], v[218:221], v[66:69]
	v_mfma_f32_16x16x32_bf16 v[70:73], v[178:181], v[218:221], v[70:73]
	s_barrier
	s_setprio 0
	s_add_i32 s54, s48, s0
	s_mov_b32 m0, s54
	ds_read_b128 v[190:193], v156 offset:16384
	ds_read_b128 v[194:197], v156 offset:17408
	ds_read_b128 v[198:201], v156 offset:18432
	ds_read_b128 v[202:205], v156 offset:19456
	ds_read_b128 v[206:209], v156 offset:20480
	ds_read_b128 v[210:213], v156 offset:21504
	ds_read_b128 v[214:217], v156 offset:22528
	ds_read_b128 v[218:221], v156 offset:23552
	global_load_lds_dwordx4 v132, s[34:35]
	s_add_i32 m0, s54, 0x2000
	s_add_u32 s54, s34, 0x4000
	s_addc_u32 s55, s35, 0
	s_add_i32 s56, s49, s0
	global_load_lds_dwordx4 v136, s[34:35]
	s_mov_b32 m0, s56
	s_nop 0
	global_load_lds_dwordx4 v132, s[54:55]
	s_add_i32 m0, s56, 0x2000
	s_nop 0
	global_load_lds_dwordx4 v136, s[54:55]
	s_mov_b32 m0, s1
	s_nop 0
	global_load_lds_dwordx4 v130, s[36:37]
	s_mov_b32 m0, s27
	s_nop 0
	global_load_lds_dwordx4 v134, s[36:37]
	s_waitcnt vmcnt(8)
	s_waitcnt lgkmcnt(0)
	s_setprio 1
	s_barrier
	v_mfma_f32_16x16x32_bf16 v[62:65], v[146:149], v[190:193], v[62:65]
	v_mfma_f32_16x16x32_bf16 v[58:61], v[162:165], v[190:193], v[58:61]
	v_mfma_f32_16x16x32_bf16 v[42:45], v[162:165], v[198:201], v[42:45]
	v_mfma_f32_16x16x32_bf16 v[46:49], v[146:149], v[198:201], v[46:49]
	v_mfma_f32_16x16x32_bf16 v[30:33], v[146:149], v[206:209], v[30:33]
	v_mfma_f32_16x16x32_bf16 v[26:29], v[162:165], v[206:209], v[26:29]
	v_mfma_f32_16x16x32_bf16 v[10:13], v[162:165], v[214:217], v[10:13]
	v_mfma_f32_16x16x32_bf16 v[14:17], v[146:149], v[214:217], v[14:17]
	v_mfma_f32_16x16x32_bf16 v[62:65], v[158:161], v[194:197], v[62:65]
	v_mfma_f32_16x16x32_bf16 v[58:61], v[166:169], v[194:197], v[58:61]
	v_mfma_f32_16x16x32_bf16 v[42:45], v[166:169], v[202:205], v[42:45]
	v_mfma_f32_16x16x32_bf16 v[46:49], v[158:161], v[202:205], v[46:49]
	v_mfma_f32_16x16x32_bf16 v[30:33], v[158:161], v[210:213], v[30:33]
	v_mfma_f32_16x16x32_bf16 v[26:29], v[166:169], v[210:213], v[26:29]
	v_mfma_f32_16x16x32_bf16 v[10:13], v[166:169], v[218:221], v[10:13]
	v_mfma_f32_16x16x32_bf16 v[14:17], v[158:161], v[218:221], v[14:17]
	s_setprio 0
	s_setprio 1
	v_mfma_f32_16x16x32_bf16 v[54:57], v[170:173], v[190:193], v[54:57]
	v_mfma_f32_16x16x32_bf16 v[50:53], v[182:185], v[190:193], v[50:53]
	v_mfma_f32_16x16x32_bf16 v[34:37], v[182:185], v[198:201], v[34:37]
	v_mfma_f32_16x16x32_bf16 v[38:41], v[170:173], v[198:201], v[38:41]
	v_mfma_f32_16x16x32_bf16 v[22:25], v[170:173], v[206:209], v[22:25]
	v_mfma_f32_16x16x32_bf16 v[18:21], v[182:185], v[206:209], v[18:21]
	v_mfma_f32_16x16x32_bf16 v[2:5], v[182:185], v[214:217], v[2:5]
	v_mfma_f32_16x16x32_bf16 v[6:9], v[170:173], v[214:217], v[6:9]
	v_mfma_f32_16x16x32_bf16 v[54:57], v[178:181], v[194:197], v[54:57]
	v_mfma_f32_16x16x32_bf16 v[50:53], v[186:189], v[194:197], v[50:53]
	v_mfma_f32_16x16x32_bf16 v[34:37], v[186:189], v[202:205], v[34:37]
	v_mfma_f32_16x16x32_bf16 v[38:41], v[178:181], v[202:205], v[38:41]
	v_mfma_f32_16x16x32_bf16 v[22:25], v[178:181], v[210:213], v[22:25]
	v_mfma_f32_16x16x32_bf16 v[18:21], v[186:189], v[210:213], v[18:21]
	v_mfma_f32_16x16x32_bf16 v[2:5], v[186:189], v[218:221], v[2:5]
	v_mfma_f32_16x16x32_bf16 v[6:9], v[178:181], v[218:221], v[6:9]
	s_barrier
	s_setprio 0
	s_add_i32 s54, 0, 0x18000
	v_add_u32_e32 v150, s54, v153
	s_add_i32 s55, 0, 0x1c000
	ds_read_b128 v[146:149], v150
	ds_read_b128 v[158:161], v150 offset:1024
	ds_read_b128 v[162:165], v150 offset:2048
	ds_read_b128 v[166:169], v150 offset:3072
	v_add_u32_e32 v150, s55, v153
	ds_read_b128 v[170:173], v150
	ds_read_b128 v[178:181], v150 offset:1024
	ds_read_b128 v[182:185], v150 offset:2048
	ds_read_b128 v[186:189], v150 offset:3072
	s_add_u32 s36, s36, 0x4000
	s_addc_u32 s37, s37, 0
	s_mov_b32 m0, s33
	ds_read_b128 v[190:193], v156 offset:32768
	ds_read_b128 v[194:197], v156 offset:33792
	ds_read_b128 v[198:201], v156 offset:34816
	ds_read_b128 v[202:205], v156 offset:35840
	ds_read_b128 v[206:209], v156 offset:36864
	ds_read_b128 v[210:213], v156 offset:37888
	ds_read_b128 v[214:217], v156 offset:38912
	ds_read_b128 v[218:221], v156 offset:39936
	global_load_lds_dwordx4 v130, s[36:37]
	s_mov_b32 m0, s38
	s_nop 0
	global_load_lds_dwordx4 v134, s[36:37]
	s_waitcnt vmcnt(8)
	s_waitcnt lgkmcnt(0)
	s_setprio 1
	s_barrier
	v_mfma_f32_16x16x32_bf16 v[126:129], v[146:149], v[190:193], v[126:129]
	v_mfma_f32_16x16x32_bf16 v[122:125], v[162:165], v[190:193], v[122:125]
	v_mfma_f32_16x16x32_bf16 v[106:109], v[162:165], v[198:201], v[106:109]
	v_mfma_f32_16x16x32_bf16 v[110:113], v[146:149], v[198:201], v[110:113]
	v_mfma_f32_16x16x32_bf16 v[94:97], v[146:149], v[206:209], v[94:97]
	v_mfma_f32_16x16x32_bf16 v[90:93], v[162:165], v[206:209], v[90:93]
	v_mfma_f32_16x16x32_bf16 v[74:77], v[162:165], v[214:217], v[74:77]
	v_mfma_f32_16x16x32_bf16 v[78:81], v[146:149], v[214:217], v[78:81]
	v_mfma_f32_16x16x32_bf16 v[126:129], v[158:161], v[194:197], v[126:129]
	v_mfma_f32_16x16x32_bf16 v[122:125], v[166:169], v[194:197], v[122:125]
	v_mfma_f32_16x16x32_bf16 v[106:109], v[166:169], v[202:205], v[106:109]
	v_mfma_f32_16x16x32_bf16 v[110:113], v[158:161], v[202:205], v[110:113]
	v_mfma_f32_16x16x32_bf16 v[94:97], v[158:161], v[210:213], v[94:97]
	v_mfma_f32_16x16x32_bf16 v[90:93], v[166:169], v[210:213], v[90:93]
	v_mfma_f32_16x16x32_bf16 v[74:77], v[166:169], v[218:221], v[74:77]
	v_mfma_f32_16x16x32_bf16 v[78:81], v[158:161], v[218:221], v[78:81]
	s_setprio 0
	s_setprio 1
	v_mfma_f32_16x16x32_bf16 v[118:121], v[170:173], v[190:193], v[118:121]
	v_mfma_f32_16x16x32_bf16 v[114:117], v[182:185], v[190:193], v[114:117]
	v_mfma_f32_16x16x32_bf16 v[98:101], v[182:185], v[198:201], v[98:101]
	v_mfma_f32_16x16x32_bf16 v[102:105], v[170:173], v[198:201], v[102:105]
	v_mfma_f32_16x16x32_bf16 v[86:89], v[170:173], v[206:209], v[86:89]
	v_mfma_f32_16x16x32_bf16 v[82:85], v[182:185], v[206:209], v[82:85]
	v_mfma_f32_16x16x32_bf16 v[66:69], v[182:185], v[214:217], v[66:69]
	v_mfma_f32_16x16x32_bf16 v[70:73], v[170:173], v[214:217], v[70:73]
	v_mfma_f32_16x16x32_bf16 v[118:121], v[178:181], v[194:197], v[118:121]
	v_mfma_f32_16x16x32_bf16 v[114:117], v[186:189], v[194:197], v[114:117]
	v_mfma_f32_16x16x32_bf16 v[98:101], v[186:189], v[202:205], v[98:101]
	v_mfma_f32_16x16x32_bf16 v[102:105], v[178:181], v[202:205], v[102:105]
	v_mfma_f32_16x16x32_bf16 v[86:89], v[178:181], v[210:213], v[86:89]
	v_mfma_f32_16x16x32_bf16 v[82:85], v[186:189], v[210:213], v[82:85]
	v_mfma_f32_16x16x32_bf16 v[66:69], v[186:189], v[218:221], v[66:69]
	v_mfma_f32_16x16x32_bf16 v[70:73], v[178:181], v[218:221], v[70:73]
	s_barrier
	s_setprio 0
	s_add_u32 s36, s34, 0x380000
	s_addc_u32 s37, s35, 0
	s_add_i32 s54, s54, s0
	s_mov_b32 m0, s54
	ds_read_b128 v[190:193], v156 offset:49152
	ds_read_b128 v[194:197], v156 offset:50176
	ds_read_b128 v[198:201], v156 offset:51200
	ds_read_b128 v[202:205], v156 offset:52224
	ds_read_b128 v[206:209], v156 offset:53248
	ds_read_b128 v[210:213], v156 offset:54272
	ds_read_b128 v[214:217], v156 offset:55296
	ds_read_b128 v[218:221], v156 offset:56320
	global_load_lds_dwordx4 v132, s[36:37]
	s_add_i32 m0, s54, 0x2000
	s_add_u32 s34, s34, 0x384000
	s_addc_u32 s35, s35, 0
	global_load_lds_dwordx4 v136, s[36:37]
	s_add_i32 s36, s55, s0
	s_mov_b32 m0, s36
	s_nop 0
	global_load_lds_dwordx4 v132, s[34:35]
	s_add_i32 m0, s36, 0x2000
	s_nop 0
	global_load_lds_dwordx4 v136, s[34:35]
	s_mov_b32 m0, s44
	s_nop 0
	global_load_lds_dwordx4 v130, s[30:31]
	s_mov_b32 m0, s45
	s_nop 0
	global_load_lds_dwordx4 v134, s[30:31]
	s_waitcnt vmcnt(8)
	s_waitcnt lgkmcnt(0)
	s_setprio 1
	s_barrier
	v_mfma_f32_16x16x32_bf16 v[62:65], v[146:149], v[190:193], v[62:65]
	v_mfma_f32_16x16x32_bf16 v[58:61], v[162:165], v[190:193], v[58:61]
	v_mfma_f32_16x16x32_bf16 v[42:45], v[162:165], v[198:201], v[42:45]
	v_mfma_f32_16x16x32_bf16 v[46:49], v[146:149], v[198:201], v[46:49]
	v_mfma_f32_16x16x32_bf16 v[30:33], v[146:149], v[206:209], v[30:33]
	v_mfma_f32_16x16x32_bf16 v[26:29], v[162:165], v[206:209], v[26:29]
	v_mfma_f32_16x16x32_bf16 v[10:13], v[162:165], v[214:217], v[10:13]
	v_mfma_f32_16x16x32_bf16 v[14:17], v[146:149], v[214:217], v[14:17]
	v_mfma_f32_16x16x32_bf16 v[62:65], v[158:161], v[194:197], v[62:65]
	v_mfma_f32_16x16x32_bf16 v[58:61], v[166:169], v[194:197], v[58:61]
	v_mfma_f32_16x16x32_bf16 v[42:45], v[166:169], v[202:205], v[42:45]
	v_mfma_f32_16x16x32_bf16 v[46:49], v[158:161], v[202:205], v[46:49]
	v_mfma_f32_16x16x32_bf16 v[30:33], v[158:161], v[210:213], v[30:33]
	v_mfma_f32_16x16x32_bf16 v[26:29], v[166:169], v[210:213], v[26:29]
	v_mfma_f32_16x16x32_bf16 v[10:13], v[166:169], v[218:221], v[10:13]
	v_mfma_f32_16x16x32_bf16 v[14:17], v[158:161], v[218:221], v[14:17]
	s_setprio 0
	s_setprio 1
	v_mfma_f32_16x16x32_bf16 v[54:57], v[170:173], v[190:193], v[54:57]
	v_mfma_f32_16x16x32_bf16 v[50:53], v[182:185], v[190:193], v[50:53]
	v_mfma_f32_16x16x32_bf16 v[34:37], v[182:185], v[198:201], v[34:37]
	v_mfma_f32_16x16x32_bf16 v[38:41], v[170:173], v[198:201], v[38:41]
	v_mfma_f32_16x16x32_bf16 v[22:25], v[170:173], v[206:209], v[22:25]
	v_mfma_f32_16x16x32_bf16 v[18:21], v[182:185], v[206:209], v[18:21]
	v_mfma_f32_16x16x32_bf16 v[2:5], v[182:185], v[214:217], v[2:5]
	v_mfma_f32_16x16x32_bf16 v[6:9], v[170:173], v[214:217], v[6:9]
	v_mfma_f32_16x16x32_bf16 v[54:57], v[178:181], v[194:197], v[54:57]
	v_mfma_f32_16x16x32_bf16 v[50:53], v[186:189], v[194:197], v[50:53]
	v_mfma_f32_16x16x32_bf16 v[34:37], v[186:189], v[202:205], v[34:37]
	v_mfma_f32_16x16x32_bf16 v[38:41], v[178:181], v[202:205], v[38:41]
	v_mfma_f32_16x16x32_bf16 v[22:25], v[178:181], v[210:213], v[22:25]
	v_mfma_f32_16x16x32_bf16 v[18:21], v[186:189], v[210:213], v[18:21]
	v_mfma_f32_16x16x32_bf16 v[2:5], v[186:189], v[218:221], v[2:5]
	v_mfma_f32_16x16x32_bf16 v[6:9], v[178:181], v[218:221], v[6:9]
	s_barrier
	s_setprio 0
	s_add_i32 s53, s53, 2
	s_add_u32 s51, s51, 0x700000
	s_addc_u32 s52, s52, 0
	s_add_u32 s28, s28, 0x200000
	s_addc_u32 s29, s29, 0
	s_cmp_gt_u32 s53, 61
	s_cbranch_scc0 .LBB0_422
	s_and_b64 vcc, exec, s[16:17]
	s_cbranch_vccz .LBB0_425
	s_barrier

.LBB0_501:
	ds_read_b128 v[146:149], v152
	ds_read_b128 v[156:159], v152 offset:1024
	ds_read_b128 v[160:163], v152 offset:2048
	ds_read_b128 v[164:167], v152 offset:3072
	ds_read_b128 v[168:171], v153
	ds_read_b128 v[172:175], v153 offset:1024
	ds_read_b128 v[178:181], v153 offset:2048
	ds_read_b128 v[182:185], v153 offset:3072
	s_add_u32 s26, s10, 0xfc000
	s_addc_u32 s27, s11, 0
	s_cmpk_eq_i32 s47, 0xdc
	s_cselect_b32 s30, s21, s26
	s_cselect_b32 s31, s5, s27
	s_cselect_b32 s28, s44, s45
	s_cselect_b32 s29, s19, s46
	s_add_u32 s26, s30, 0x100000
	s_addc_u32 s27, s31, 0
	s_add_i32 m0, s1, 0xc000
	ds_read_b128 v[186:189], v154
	ds_read_b128 v[190:193], v154 offset:1024
	ds_read_b128 v[194:197], v154 offset:2048
	ds_read_b128 v[198:201], v154 offset:3072
	ds_read_b128 v[202:205], v154 offset:4096
	ds_read_b128 v[206:209], v154 offset:5120
	ds_read_b128 v[210:213], v154 offset:6144
	ds_read_b128 v[214:217], v154 offset:7168
	global_load_lds_dwordx4 v138, s[10:11]
	s_add_i32 m0, s1, 0xe000
	s_nop 0
	global_load_lds_dwordx4 v140, s[10:11]
	s_waitcnt vmcnt(8)
	s_waitcnt lgkmcnt(0)
	s_setprio 1
	s_barrier
	v_mfma_f32_16x16x32_bf16 v[126:129], v[146:149], v[186:189], v[126:129]
	v_mfma_f32_16x16x32_bf16 v[122:125], v[160:163], v[186:189], v[122:125]
	v_mfma_f32_16x16x32_bf16 v[106:109], v[160:163], v[194:197], v[106:109]
	v_mfma_f32_16x16x32_bf16 v[110:113], v[146:149], v[194:197], v[110:113]
	v_mfma_f32_16x16x32_bf16 v[94:97], v[146:149], v[202:205], v[94:97]
	v_mfma_f32_16x16x32_bf16 v[90:93], v[160:163], v[202:205], v[90:93]
	v_mfma_f32_16x16x32_bf16 v[74:77], v[160:163], v[210:213], v[74:77]
	v_mfma_f32_16x16x32_bf16 v[78:81], v[146:149], v[210:213], v[78:81]
	v_mfma_f32_16x16x32_bf16 v[126:129], v[156:159], v[190:193], v[126:129]
	v_mfma_f32_16x16x32_bf16 v[122:125], v[164:167], v[190:193], v[122:125]
	v_mfma_f32_16x16x32_bf16 v[106:109], v[164:167], v[198:201], v[106:109]
	v_mfma_f32_16x16x32_bf16 v[110:113], v[156:159], v[198:201], v[110:113]
	v_mfma_f32_16x16x32_bf16 v[94:97], v[156:159], v[206:209], v[94:97]
	v_mfma_f32_16x16x32_bf16 v[90:93], v[164:167], v[206:209], v[90:93]
	v_mfma_f32_16x16x32_bf16 v[74:77], v[164:167], v[214:217], v[74:77]
	v_mfma_f32_16x16x32_bf16 v[78:81], v[156:159], v[214:217], v[78:81]
	s_setprio 0
	s_setprio 1
	v_mfma_f32_16x16x32_bf16 v[118:121], v[168:171], v[186:189], v[118:121]
	v_mfma_f32_16x16x32_bf16 v[114:117], v[178:181], v[186:189], v[114:117]
	v_mfma_f32_16x16x32_bf16 v[98:101], v[178:181], v[194:197], v[98:101]
	v_mfma_f32_16x16x32_bf16 v[102:105], v[168:171], v[194:197], v[102:105]
	v_mfma_f32_16x16x32_bf16 v[86:89], v[168:171], v[202:205], v[86:89]
	v_mfma_f32_16x16x32_bf16 v[82:85], v[178:181], v[202:205], v[82:85]
	v_mfma_f32_16x16x32_bf16 v[66:69], v[178:181], v[210:213], v[66:69]
	v_mfma_f32_16x16x32_bf16 v[70:73], v[168:171], v[210:213], v[70:73]
	v_mfma_f32_16x16x32_bf16 v[118:121], v[172:175], v[190:193], v[118:121]
	v_mfma_f32_16x16x32_bf16 v[114:117], v[182:185], v[190:193], v[114:117]
	v_mfma_f32_16x16x32_bf16 v[98:101], v[182:185], v[198:201], v[98:101]
	v_mfma_f32_16x16x32_bf16 v[102:105], v[172:175], v[198:201], v[102:105]
	v_mfma_f32_16x16x32_bf16 v[86:89], v[172:175], v[206:209], v[86:89]
	v_mfma_f32_16x16x32_bf16 v[82:85], v[182:185], v[206:209], v[82:85]
	v_mfma_f32_16x16x32_bf16 v[66:69], v[182:185], v[214:217], v[66:69]
	v_mfma_f32_16x16x32_bf16 v[70:73], v[172:175], v[214:217], v[70:73]
	s_barrier
	s_setprio 0
	s_add_i32 s48, s41, s0
	s_mov_b32 m0, s48
	ds_read_b128 v[186:189], v154 offset:16384
	ds_read_b128 v[190:193], v154 offset:17408
	ds_read_b128 v[194:197], v154 offset:18432
	ds_read_b128 v[198:201], v154 offset:19456
	ds_read_b128 v[202:205], v154 offset:20480
	ds_read_b128 v[206:209], v154 offset:21504
	ds_read_b128 v[210:213], v154 offset:22528
	ds_read_b128 v[214:217], v154 offset:23552
	global_load_lds_dwordx4 v132, s[28:29]
	s_add_i32 m0, s48, 0x2000
	s_add_u32 s48, s28, 0x4000
	s_addc_u32 s49, s29, 0
	s_add_i32 s50, s42, s0
	global_load_lds_dwordx4 v136, s[28:29]
	s_mov_b32 m0, s50
	s_nop 0
	global_load_lds_dwordx4 v132, s[48:49]
	s_add_i32 m0, s50, 0x2000
	s_nop 0
	global_load_lds_dwordx4 v136, s[48:49]
	s_mov_b32 m0, s1
	s_nop 0
	global_load_lds_dwordx4 v130, s[30:31]
	s_mov_b32 m0, s33
	s_nop 0
	global_load_lds_dwordx4 v134, s[30:31]
	s_waitcnt vmcnt(8)
	s_waitcnt lgkmcnt(0)
	s_setprio 1
	s_barrier
	v_mfma_f32_16x16x32_bf16 v[62:65], v[146:149], v[186:189], v[62:65]
	v_mfma_f32_16x16x32_bf16 v[58:61], v[160:163], v[186:189], v[58:61]
	v_mfma_f32_16x16x32_bf16 v[42:45], v[160:163], v[194:197], v[42:45]
	v_mfma_f32_16x16x32_bf16 v[46:49], v[146:149], v[194:197], v[46:49]
	v_mfma_f32_16x16x32_bf16 v[30:33], v[146:149], v[202:205], v[30:33]
	v_mfma_f32_16x16x32_bf16 v[26:29], v[160:163], v[202:205], v[26:29]
	v_mfma_f32_16x16x32_bf16 v[10:13], v[160:163], v[210:213], v[10:13]
	v_mfma_f32_16x16x32_bf16 v[14:17], v[146:149], v[210:213], v[14:17]
	v_mfma_f32_16x16x32_bf16 v[62:65], v[156:159], v[190:193], v[62:65]
	v_mfma_f32_16x16x32_bf16 v[58:61], v[164:167], v[190:193], v[58:61]
	v_mfma_f32_16x16x32_bf16 v[42:45], v[164:167], v[198:201], v[42:45]
	v_mfma_f32_16x16x32_bf16 v[46:49], v[156:159], v[198:201], v[46:49]
	v_mfma_f32_16x16x32_bf16 v[30:33], v[156:159], v[206:209], v[30:33]
	v_mfma_f32_16x16x32_bf16 v[26:29], v[164:167], v[206:209], v[26:29]
	v_mfma_f32_16x16x32_bf16 v[10:13], v[164:167], v[214:217], v[10:13]
	v_mfma_f32_16x16x32_bf16 v[14:17], v[156:159], v[214:217], v[14:17]
	s_setprio 0
	s_setprio 1
	v_mfma_f32_16x16x32_bf16 v[54:57], v[168:171], v[186:189], v[54:57]
	v_mfma_f32_16x16x32_bf16 v[50:53], v[178:181], v[186:189], v[50:53]
	v_mfma_f32_16x16x32_bf16 v[34:37], v[178:181], v[194:197], v[34:37]
	v_mfma_f32_16x16x32_bf16 v[38:41], v[168:171], v[194:197], v[38:41]
	v_mfma_f32_16x16x32_bf16 v[22:25], v[168:171], v[202:205], v[22:25]
	v_mfma_f32_16x16x32_bf16 v[18:21], v[178:181], v[202:205], v[18:21]
	v_mfma_f32_16x16x32_bf16 v[2:5], v[178:181], v[210:213], v[2:5]
	v_mfma_f32_16x16x32_bf16 v[6:9], v[168:171], v[210:213], v[6:9]
	v_mfma_f32_16x16x32_bf16 v[54:57], v[172:175], v[190:193], v[54:57]
	v_mfma_f32_16x16x32_bf16 v[50:53], v[182:185], v[190:193], v[50:53]
	v_mfma_f32_16x16x32_bf16 v[34:37], v[182:185], v[198:201], v[34:37]
	v_mfma_f32_16x16x32_bf16 v[38:41], v[172:175], v[198:201], v[38:41]
	v_mfma_f32_16x16x32_bf16 v[22:25], v[172:175], v[206:209], v[22:25]
	v_mfma_f32_16x16x32_bf16 v[18:21], v[182:185], v[206:209], v[18:21]
	v_mfma_f32_16x16x32_bf16 v[2:5], v[182:185], v[214:217], v[2:5]
	v_mfma_f32_16x16x32_bf16 v[6:9], v[172:175], v[214:217], v[6:9]
	s_barrier
	s_setprio 0
	s_add_i32 s48, 0, 0x18000
	s_add_i32 s49, 0, 0x1c000
	v_add_u32_e32 v164, s48, v151
	v_add_u32_e32 v176, s49, v151
	ds_read_b128 v[146:149], v164
	ds_read_b128 v[156:159], v164 offset:1024
	ds_read_b128 v[160:163], v164 offset:2048
	ds_read_b128 v[164:167], v164 offset:3072
	ds_read_b128 v[168:171], v176
	ds_read_b128 v[172:175], v176 offset:1024
	ds_read_b128 v[178:181], v176 offset:2048
	ds_read_b128 v[182:185], v176 offset:3072
	s_add_u32 s30, s30, 0x4000
	s_addc_u32 s31, s31, 0
	s_mov_b32 m0, s34
	ds_read_b128 v[186:189], v154 offset:32768
	ds_read_b128 v[190:193], v154 offset:33792
	ds_read_b128 v[194:197], v154 offset:34816
	ds_read_b128 v[198:201], v154 offset:35840
	ds_read_b128 v[202:205], v154 offset:36864
	ds_read_b128 v[206:209], v154 offset:37888
	ds_read_b128 v[210:213], v154 offset:38912
	ds_read_b128 v[214:217], v154 offset:39936
	global_load_lds_dwordx4 v130, s[30:31]
	s_mov_b32 m0, s35
	s_nop 0
	global_load_lds_dwordx4 v134, s[30:31]
	s_waitcnt vmcnt(8)
	s_waitcnt lgkmcnt(0)
	s_setprio 1
	s_barrier
	v_mfma_f32_16x16x32_bf16 v[126:129], v[146:149], v[186:189], v[126:129]
	v_mfma_f32_16x16x32_bf16 v[122:125], v[160:163], v[186:189], v[122:125]
	v_mfma_f32_16x16x32_bf16 v[106:109], v[160:163], v[194:197], v[106:109]
	v_mfma_f32_16x16x32_bf16 v[110:113], v[146:149], v[194:197], v[110:113]
	v_mfma_f32_16x16x32_bf16 v[94:97], v[146:149], v[202:205], v[94:97]
	v_mfma_f32_16x16x32_bf16 v[90:93], v[160:163], v[202:205], v[90:93]
	v_mfma_f32_16x16x32_bf16 v[74:77], v[160:163], v[210:213], v[74:77]
	v_mfma_f32_16x16x32_bf16 v[78:81], v[146:149], v[210:213], v[78:81]
	v_mfma_f32_16x16x32_bf16 v[126:129], v[156:159], v[190:193], v[126:129]
	v_mfma_f32_16x16x32_bf16 v[122:125], v[164:167], v[190:193], v[122:125]
	v_mfma_f32_16x16x32_bf16 v[106:109], v[164:167], v[198:201], v[106:109]
	v_mfma_f32_16x16x32_bf16 v[110:113], v[156:159], v[198:201], v[110:113]
	v_mfma_f32_16x16x32_bf16 v[94:97], v[156:159], v[206:209], v[94:97]
	v_mfma_f32_16x16x32_bf16 v[90:93], v[164:167], v[206:209], v[90:93]
	v_mfma_f32_16x16x32_bf16 v[74:77], v[164:167], v[214:217], v[74:77]
	v_mfma_f32_16x16x32_bf16 v[78:81], v[156:159], v[214:217], v[78:81]
	s_setprio 0
	s_setprio 1
	v_mfma_f32_16x16x32_bf16 v[118:121], v[168:171], v[186:189], v[118:121]
	v_mfma_f32_16x16x32_bf16 v[114:117], v[178:181], v[186:189], v[114:117]
	v_mfma_f32_16x16x32_bf16 v[98:101], v[178:181], v[194:197], v[98:101]
	v_mfma_f32_16x16x32_bf16 v[102:105], v[168:171], v[194:197], v[102:105]
	v_mfma_f32_16x16x32_bf16 v[86:89], v[168:171], v[202:205], v[86:89]
	v_mfma_f32_16x16x32_bf16 v[82:85], v[178:181], v[202:205], v[82:85]
	v_mfma_f32_16x16x32_bf16 v[66:69], v[178:181], v[210:213], v[66:69]
	v_mfma_f32_16x16x32_bf16 v[70:73], v[168:171], v[210:213], v[70:73]
	v_mfma_f32_16x16x32_bf16 v[118:121], v[172:175], v[190:193], v[118:121]
	v_mfma_f32_16x16x32_bf16 v[114:117], v[182:185], v[190:193], v[114:117]
	v_mfma_f32_16x16x32_bf16 v[98:101], v[182:185], v[198:201], v[98:101]
	v_mfma_f32_16x16x32_bf16 v[102:105], v[172:175], v[198:201], v[102:105]
	v_mfma_f32_16x16x32_bf16 v[86:89], v[172:175], v[206:209], v[86:89]
	v_mfma_f32_16x16x32_bf16 v[82:85], v[182:185], v[206:209], v[82:85]
	v_mfma_f32_16x16x32_bf16 v[66:69], v[182:185], v[214:217], v[66:69]
	v_mfma_f32_16x16x32_bf16 v[70:73], v[172:175], v[214:217], v[70:73]
	s_barrier
	s_setprio 0
	s_add_u32 s30, s28, 0x80000
	s_addc_u32 s31, s29, 0
	s_add_i32 s48, s48, s0
	s_mov_b32 m0, s48
	ds_read_b128 v[186:189], v154 offset:49152
	ds_read_b128 v[190:193], v154 offset:50176
	ds_read_b128 v[194:197], v154 offset:51200
	ds_read_b128 v[198:201], v154 offset:52224
	ds_read_b128 v[202:205], v154 offset:53248
	ds_read_b128 v[206:209], v154 offset:54272
	ds_read_b128 v[210:213], v154 offset:55296
	ds_read_b128 v[214:217], v154 offset:56320
	global_load_lds_dwordx4 v132, s[30:31]
	s_add_i32 m0, s48, 0x2000
	s_add_u32 s28, s28, 0x84000
	s_addc_u32 s29, s29, 0
	global_load_lds_dwordx4 v136, s[30:31]
	s_add_i32 s30, s49, s0
	s_mov_b32 m0, s30
	s_nop 0
	global_load_lds_dwordx4 v132, s[28:29]
	s_add_i32 m0, s30, 0x2000
	s_nop 0
	global_load_lds_dwordx4 v136, s[28:29]
	s_mov_b32 m0, s39
	s_nop 0
	global_load_lds_dwordx4 v130, s[26:27]
	s_mov_b32 m0, s40
	s_nop 0
	global_load_lds_dwordx4 v134, s[26:27]
	s_waitcnt vmcnt(8)
	s_waitcnt lgkmcnt(0)
	s_setprio 1
	s_barrier
	v_mfma_f32_16x16x32_bf16 v[62:65], v[146:149], v[186:189], v[62:65]
	v_mfma_f32_16x16x32_bf16 v[58:61], v[160:163], v[186:189], v[58:61]
	v_mfma_f32_16x16x32_bf16 v[42:45], v[160:163], v[194:197], v[42:45]
	v_mfma_f32_16x16x32_bf16 v[46:49], v[146:149], v[194:197], v[46:49]
	v_mfma_f32_16x16x32_bf16 v[30:33], v[146:149], v[202:205], v[30:33]
	v_mfma_f32_16x16x32_bf16 v[26:29], v[160:163], v[202:205], v[26:29]
	v_mfma_f32_16x16x32_bf16 v[10:13], v[160:163], v[210:213], v[10:13]
	v_mfma_f32_16x16x32_bf16 v[14:17], v[146:149], v[210:213], v[14:17]
	v_mfma_f32_16x16x32_bf16 v[62:65], v[156:159], v[190:193], v[62:65]
	v_mfma_f32_16x16x32_bf16 v[58:61], v[164:167], v[190:193], v[58:61]
	v_mfma_f32_16x16x32_bf16 v[42:45], v[164:167], v[198:201], v[42:45]
	v_mfma_f32_16x16x32_bf16 v[46:49], v[156:159], v[198:201], v[46:49]
	v_mfma_f32_16x16x32_bf16 v[30:33], v[156:159], v[206:209], v[30:33]
	v_mfma_f32_16x16x32_bf16 v[26:29], v[164:167], v[206:209], v[26:29]
	v_mfma_f32_16x16x32_bf16 v[10:13], v[164:167], v[214:217], v[10:13]
	v_mfma_f32_16x16x32_bf16 v[14:17], v[156:159], v[214:217], v[14:17]
	s_setprio 0
	s_setprio 1
	v_mfma_f32_16x16x32_bf16 v[54:57], v[168:171], v[186:189], v[54:57]
	v_mfma_f32_16x16x32_bf16 v[50:53], v[178:181], v[186:189], v[50:53]
	v_mfma_f32_16x16x32_bf16 v[34:37], v[178:181], v[194:197], v[34:37]
	v_mfma_f32_16x16x32_bf16 v[38:41], v[168:171], v[194:197], v[38:41]
	v_mfma_f32_16x16x32_bf16 v[22:25], v[168:171], v[202:205], v[22:25]
	v_mfma_f32_16x16x32_bf16 v[18:21], v[178:181], v[202:205], v[18:21]
	v_mfma_f32_16x16x32_bf16 v[2:5], v[178:181], v[210:213], v[2:5]
	v_mfma_f32_16x16x32_bf16 v[6:9], v[168:171], v[210:213], v[6:9]
	v_mfma_f32_16x16x32_bf16 v[54:57], v[172:175], v[190:193], v[54:57]
	v_mfma_f32_16x16x32_bf16 v[50:53], v[182:185], v[190:193], v[50:53]
	v_mfma_f32_16x16x32_bf16 v[34:37], v[182:185], v[198:201], v[34:37]
	v_mfma_f32_16x16x32_bf16 v[38:41], v[172:175], v[198:201], v[38:41]
	v_mfma_f32_16x16x32_bf16 v[22:25], v[172:175], v[206:209], v[22:25]
	v_mfma_f32_16x16x32_bf16 v[18:21], v[182:185], v[206:209], v[18:21]
	v_mfma_f32_16x16x32_bf16 v[2:5], v[182:185], v[214:217], v[2:5]
	v_mfma_f32_16x16x32_bf16 v[6:9], v[172:175], v[214:217], v[6:9]
	s_barrier
	s_setprio 0
	s_add_i32 s47, s47, 2
	s_add_u32 s45, s45, 0x100000
	s_addc_u32 s46, s46, 0
	s_add_u32 s10, s10, 0x200000
	s_addc_u32 s11, s11, 0
	s_cmpk_gt_u32 s47, 0xdd
	s_cbranch_scc0 .LBB0_501
	s_and_b64 vcc, exec, s[16:17]
	s_cbranch_vccz .LBB0_504
	s_barrier

.LBB0_801:
	ds_read_b128 v[130:133], v179
	ds_read_b128 v[134:137], v179 offset:1024
	ds_read_b128 v[156:159], v179 offset:2048
	ds_read_b128 v[160:163], v179 offset:3072
	ds_read_b128 v[164:167], v180
	ds_read_b128 v[168:171], v180 offset:1024
	ds_read_b128 v[172:175], v180 offset:2048
	ds_read_b128 v[186:189], v180 offset:3072
	s_add_u32 s26, s12, 0xfc000
	s_addc_u32 s27, s13, 0
	s_cmp_eq_u32 s47, 60
	s_cselect_b32 s30, s5, s26
	s_cselect_b32 s31, s3, s27
	s_cselect_b32 s28, s21, s45
	s_cselect_b32 s29, s19, s46
	s_add_u32 s26, s30, 0x100000
	s_addc_u32 s27, s31, 0
	s_add_i32 m0, s1, 0xc000
	ds_read_b128 v[190:193], v181
	ds_read_b128 v[194:197], v181 offset:1024
	ds_read_b128 v[198:201], v181 offset:2048
	ds_read_b128 v[202:205], v181 offset:3072
	ds_read_b128 v[206:209], v181 offset:4096
	ds_read_b128 v[210:213], v181 offset:5120
	ds_read_b128 v[214:217], v181 offset:6144
	ds_read_b128 v[218:221], v181 offset:7168
	global_load_lds_dwordx4 v148, s[12:13]
	s_add_i32 m0, s1, 0xe000
	s_nop 0
	global_load_lds_dwordx4 v150, s[12:13]
	s_waitcnt vmcnt(8)
	s_waitcnt lgkmcnt(0)
	s_setprio 1
	s_barrier
	v_mfma_f32_16x16x32_bf16 v[126:129], v[130:133], v[190:193], v[126:129]
	v_mfma_f32_16x16x32_bf16 v[122:125], v[156:159], v[190:193], v[122:125]
	v_mfma_f32_16x16x32_bf16 v[106:109], v[156:159], v[198:201], v[106:109]
	v_mfma_f32_16x16x32_bf16 v[110:113], v[130:133], v[198:201], v[110:113]
	v_mfma_f32_16x16x32_bf16 v[94:97], v[130:133], v[206:209], v[94:97]
	v_mfma_f32_16x16x32_bf16 v[90:93], v[156:159], v[206:209], v[90:93]
	v_mfma_f32_16x16x32_bf16 v[74:77], v[156:159], v[214:217], v[74:77]
	v_mfma_f32_16x16x32_bf16 v[78:81], v[130:133], v[214:217], v[78:81]
	v_mfma_f32_16x16x32_bf16 v[126:129], v[134:137], v[194:197], v[126:129]
	v_mfma_f32_16x16x32_bf16 v[122:125], v[160:163], v[194:197], v[122:125]
	v_mfma_f32_16x16x32_bf16 v[106:109], v[160:163], v[202:205], v[106:109]
	v_mfma_f32_16x16x32_bf16 v[110:113], v[134:137], v[202:205], v[110:113]
	v_mfma_f32_16x16x32_bf16 v[94:97], v[134:137], v[210:213], v[94:97]
	v_mfma_f32_16x16x32_bf16 v[90:93], v[160:163], v[210:213], v[90:93]
	v_mfma_f32_16x16x32_bf16 v[74:77], v[160:163], v[218:221], v[74:77]
	v_mfma_f32_16x16x32_bf16 v[78:81], v[134:137], v[218:221], v[78:81]
	s_setprio 0
	s_setprio 1
	v_mfma_f32_16x16x32_bf16 v[118:121], v[164:167], v[190:193], v[118:121]
	v_mfma_f32_16x16x32_bf16 v[114:117], v[172:175], v[190:193], v[114:117]
	v_mfma_f32_16x16x32_bf16 v[98:101], v[172:175], v[198:201], v[98:101]
	v_mfma_f32_16x16x32_bf16 v[102:105], v[164:167], v[198:201], v[102:105]
	v_mfma_f32_16x16x32_bf16 v[86:89], v[164:167], v[206:209], v[86:89]
	v_mfma_f32_16x16x32_bf16 v[82:85], v[172:175], v[206:209], v[82:85]
	v_mfma_f32_16x16x32_bf16 v[66:69], v[172:175], v[214:217], v[66:69]
	v_mfma_f32_16x16x32_bf16 v[70:73], v[164:167], v[214:217], v[70:73]
	v_mfma_f32_16x16x32_bf16 v[118:121], v[168:171], v[194:197], v[118:121]
	v_mfma_f32_16x16x32_bf16 v[114:117], v[186:189], v[194:197], v[114:117]
	v_mfma_f32_16x16x32_bf16 v[98:101], v[186:189], v[202:205], v[98:101]
	v_mfma_f32_16x16x32_bf16 v[102:105], v[168:171], v[202:205], v[102:105]
	v_mfma_f32_16x16x32_bf16 v[86:89], v[168:171], v[210:213], v[86:89]
	v_mfma_f32_16x16x32_bf16 v[82:85], v[186:189], v[210:213], v[82:85]
	v_mfma_f32_16x16x32_bf16 v[66:69], v[186:189], v[218:221], v[66:69]
	v_mfma_f32_16x16x32_bf16 v[70:73], v[168:171], v[218:221], v[70:73]
	s_barrier
	s_setprio 0
	s_add_i32 s48, s42, s0
	s_mov_b32 m0, s48
	ds_read_b128 v[190:193], v181 offset:16384
	ds_read_b128 v[194:197], v181 offset:17408
	ds_read_b128 v[198:201], v181 offset:18432
	ds_read_b128 v[202:205], v181 offset:19456
	ds_read_b128 v[206:209], v181 offset:20480
	ds_read_b128 v[210:213], v181 offset:21504
	ds_read_b128 v[214:217], v181 offset:22528
	ds_read_b128 v[218:221], v181 offset:23552
	global_load_lds_dwordx4 v140, s[28:29]
	s_add_i32 m0, s48, 0x2000
	s_add_u32 s48, s28, 0x4000
	s_addc_u32 s49, s29, 0
	s_add_i32 s50, s43, s0
	global_load_lds_dwordx4 v144, s[28:29]
	s_mov_b32 m0, s50
	s_nop 0
	global_load_lds_dwordx4 v140, s[48:49]
	s_add_i32 m0, s50, 0x2000
	s_nop 0
	global_load_lds_dwordx4 v144, s[48:49]
	s_mov_b32 m0, s1
	s_nop 0
	global_load_lds_dwordx4 v138, s[30:31]
	s_mov_b32 m0, s33
	s_nop 0
	global_load_lds_dwordx4 v142, s[30:31]
	s_waitcnt vmcnt(8)
	s_waitcnt lgkmcnt(0)
	s_setprio 1
	s_barrier
	v_mfma_f32_16x16x32_bf16 v[62:65], v[130:133], v[190:193], v[62:65]
	v_mfma_f32_16x16x32_bf16 v[58:61], v[156:159], v[190:193], v[58:61]
	v_mfma_f32_16x16x32_bf16 v[42:45], v[156:159], v[198:201], v[42:45]
	v_mfma_f32_16x16x32_bf16 v[46:49], v[130:133], v[198:201], v[46:49]
	v_mfma_f32_16x16x32_bf16 v[30:33], v[130:133], v[206:209], v[30:33]
	v_mfma_f32_16x16x32_bf16 v[26:29], v[156:159], v[206:209], v[26:29]
	v_mfma_f32_16x16x32_bf16 v[10:13], v[156:159], v[214:217], v[10:13]
	v_mfma_f32_16x16x32_bf16 v[14:17], v[130:133], v[214:217], v[14:17]
	v_mfma_f32_16x16x32_bf16 v[62:65], v[134:137], v[194:197], v[62:65]
	v_mfma_f32_16x16x32_bf16 v[58:61], v[160:163], v[194:197], v[58:61]
	v_mfma_f32_16x16x32_bf16 v[42:45], v[160:163], v[202:205], v[42:45]
	v_mfma_f32_16x16x32_bf16 v[46:49], v[134:137], v[202:205], v[46:49]
	v_mfma_f32_16x16x32_bf16 v[30:33], v[134:137], v[210:213], v[30:33]
	v_mfma_f32_16x16x32_bf16 v[26:29], v[160:163], v[210:213], v[26:29]
	v_mfma_f32_16x16x32_bf16 v[10:13], v[160:163], v[218:221], v[10:13]
	v_mfma_f32_16x16x32_bf16 v[14:17], v[134:137], v[218:221], v[14:17]
	s_setprio 0
	s_setprio 1
	v_mfma_f32_16x16x32_bf16 v[54:57], v[164:167], v[190:193], v[54:57]
	v_mfma_f32_16x16x32_bf16 v[50:53], v[172:175], v[190:193], v[50:53]
	v_mfma_f32_16x16x32_bf16 v[34:37], v[172:175], v[198:201], v[34:37]
	v_mfma_f32_16x16x32_bf16 v[38:41], v[164:167], v[198:201], v[38:41]
	v_mfma_f32_16x16x32_bf16 v[22:25], v[164:167], v[206:209], v[22:25]
	v_mfma_f32_16x16x32_bf16 v[18:21], v[172:175], v[206:209], v[18:21]
	v_mfma_f32_16x16x32_bf16 v[2:5], v[172:175], v[214:217], v[2:5]
	v_mfma_f32_16x16x32_bf16 v[6:9], v[164:167], v[214:217], v[6:9]
	v_mfma_f32_16x16x32_bf16 v[54:57], v[168:171], v[194:197], v[54:57]
	v_mfma_f32_16x16x32_bf16 v[50:53], v[186:189], v[194:197], v[50:53]
	v_mfma_f32_16x16x32_bf16 v[34:37], v[186:189], v[202:205], v[34:37]
	v_mfma_f32_16x16x32_bf16 v[38:41], v[168:171], v[202:205], v[38:41]
	v_mfma_f32_16x16x32_bf16 v[22:25], v[168:171], v[210:213], v[22:25]
	v_mfma_f32_16x16x32_bf16 v[18:21], v[186:189], v[210:213], v[18:21]
	v_mfma_f32_16x16x32_bf16 v[2:5], v[186:189], v[218:221], v[2:5]
	v_mfma_f32_16x16x32_bf16 v[6:9], v[168:171], v[218:221], v[6:9]
	s_barrier
	s_setprio 0
	s_add_i32 s48, 0, 0x18000
	v_add_u32_e32 v146, s48, v178
	s_add_i32 s49, 0, 0x1c000
	ds_read_b128 v[130:133], v146
	ds_read_b128 v[134:137], v146 offset:1024
	ds_read_b128 v[156:159], v146 offset:2048
	ds_read_b128 v[160:163], v146 offset:3072
	v_add_u32_e32 v146, s49, v178
	ds_read_b128 v[164:167], v146
	ds_read_b128 v[168:171], v146 offset:1024
	ds_read_b128 v[172:175], v146 offset:2048
	ds_read_b128 v[186:189], v146 offset:3072
	s_add_u32 s30, s30, 0x4000
	s_addc_u32 s31, s31, 0
	s_mov_b32 m0, s34
	ds_read_b128 v[190:193], v181 offset:32768
	ds_read_b128 v[194:197], v181 offset:33792
	ds_read_b128 v[198:201], v181 offset:34816
	ds_read_b128 v[202:205], v181 offset:35840
	ds_read_b128 v[206:209], v181 offset:36864
	ds_read_b128 v[210:213], v181 offset:37888
	ds_read_b128 v[214:217], v181 offset:38912
	ds_read_b128 v[218:221], v181 offset:39936
	global_load_lds_dwordx4 v138, s[30:31]
	s_mov_b32 m0, s35
	s_nop 0
	global_load_lds_dwordx4 v142, s[30:31]
	s_waitcnt vmcnt(8)
	s_waitcnt lgkmcnt(0)
	s_setprio 1
	s_barrier
	v_mfma_f32_16x16x32_bf16 v[126:129], v[130:133], v[190:193], v[126:129]
	v_mfma_f32_16x16x32_bf16 v[122:125], v[156:159], v[190:193], v[122:125]
	v_mfma_f32_16x16x32_bf16 v[106:109], v[156:159], v[198:201], v[106:109]
	v_mfma_f32_16x16x32_bf16 v[110:113], v[130:133], v[198:201], v[110:113]
	v_mfma_f32_16x16x32_bf16 v[94:97], v[130:133], v[206:209], v[94:97]
	v_mfma_f32_16x16x32_bf16 v[90:93], v[156:159], v[206:209], v[90:93]
	v_mfma_f32_16x16x32_bf16 v[74:77], v[156:159], v[214:217], v[74:77]
	v_mfma_f32_16x16x32_bf16 v[78:81], v[130:133], v[214:217], v[78:81]
	v_mfma_f32_16x16x32_bf16 v[126:129], v[134:137], v[194:197], v[126:129]
	v_mfma_f32_16x16x32_bf16 v[122:125], v[160:163], v[194:197], v[122:125]
	v_mfma_f32_16x16x32_bf16 v[106:109], v[160:163], v[202:205], v[106:109]
	v_mfma_f32_16x16x32_bf16 v[110:113], v[134:137], v[202:205], v[110:113]
	v_mfma_f32_16x16x32_bf16 v[94:97], v[134:137], v[210:213], v[94:97]
	v_mfma_f32_16x16x32_bf16 v[90:93], v[160:163], v[210:213], v[90:93]
	v_mfma_f32_16x16x32_bf16 v[74:77], v[160:163], v[218:221], v[74:77]
	v_mfma_f32_16x16x32_bf16 v[78:81], v[134:137], v[218:221], v[78:81]
	s_setprio 0
	s_setprio 1
	v_mfma_f32_16x16x32_bf16 v[118:121], v[164:167], v[190:193], v[118:121]
	v_mfma_f32_16x16x32_bf16 v[114:117], v[172:175], v[190:193], v[114:117]
	v_mfma_f32_16x16x32_bf16 v[98:101], v[172:175], v[198:201], v[98:101]
	v_mfma_f32_16x16x32_bf16 v[102:105], v[164:167], v[198:201], v[102:105]
	v_mfma_f32_16x16x32_bf16 v[86:89], v[164:167], v[206:209], v[86:89]
	v_mfma_f32_16x16x32_bf16 v[82:85], v[172:175], v[206:209], v[82:85]
	v_mfma_f32_16x16x32_bf16 v[66:69], v[172:175], v[214:217], v[66:69]
	v_mfma_f32_16x16x32_bf16 v[70:73], v[164:167], v[214:217], v[70:73]
	v_mfma_f32_16x16x32_bf16 v[118:121], v[168:171], v[194:197], v[118:121]
	v_mfma_f32_16x16x32_bf16 v[114:117], v[186:189], v[194:197], v[114:117]
	v_mfma_f32_16x16x32_bf16 v[98:101], v[186:189], v[202:205], v[98:101]
	v_mfma_f32_16x16x32_bf16 v[102:105], v[168:171], v[202:205], v[102:105]
	v_mfma_f32_16x16x32_bf16 v[86:89], v[168:171], v[210:213], v[86:89]
	v_mfma_f32_16x16x32_bf16 v[82:85], v[186:189], v[210:213], v[82:85]
	v_mfma_f32_16x16x32_bf16 v[66:69], v[186:189], v[218:221], v[66:69]
	v_mfma_f32_16x16x32_bf16 v[70:73], v[168:171], v[218:221], v[70:73]
	s_barrier
	s_setprio 0
	s_add_u32 s30, s28, 0x180000
	s_addc_u32 s31, s29, 0
	s_add_i32 s48, s48, s0
	s_mov_b32 m0, s48
	ds_read_b128 v[190:193], v181 offset:49152
	ds_read_b128 v[194:197], v181 offset:50176
	ds_read_b128 v[198:201], v181 offset:51200
	ds_read_b128 v[202:205], v181 offset:52224
	ds_read_b128 v[206:209], v181 offset:53248
	ds_read_b128 v[210:213], v181 offset:54272
	ds_read_b128 v[214:217], v181 offset:55296
	ds_read_b128 v[218:221], v181 offset:56320
	global_load_lds_dwordx4 v140, s[30:31]
	s_add_i32 m0, s48, 0x2000
	s_add_u32 s28, s28, 0x184000
	s_addc_u32 s29, s29, 0
	global_load_lds_dwordx4 v144, s[30:31]
	s_add_i32 s30, s49, s0
	s_mov_b32 m0, s30
	s_nop 0
	global_load_lds_dwordx4 v140, s[28:29]
	s_add_i32 m0, s30, 0x2000
	s_nop 0
	global_load_lds_dwordx4 v144, s[28:29]
	s_mov_b32 m0, s38
	s_nop 0
	global_load_lds_dwordx4 v138, s[26:27]
	s_mov_b32 m0, s39
	s_nop 0
	global_load_lds_dwordx4 v142, s[26:27]
	s_waitcnt vmcnt(8)
	s_waitcnt lgkmcnt(0)
	s_setprio 1
	s_barrier
	v_mfma_f32_16x16x32_bf16 v[62:65], v[130:133], v[190:193], v[62:65]
	v_mfma_f32_16x16x32_bf16 v[58:61], v[156:159], v[190:193], v[58:61]
	v_mfma_f32_16x16x32_bf16 v[42:45], v[156:159], v[198:201], v[42:45]
	v_mfma_f32_16x16x32_bf16 v[46:49], v[130:133], v[198:201], v[46:49]
	v_mfma_f32_16x16x32_bf16 v[30:33], v[130:133], v[206:209], v[30:33]
	v_mfma_f32_16x16x32_bf16 v[26:29], v[156:159], v[206:209], v[26:29]
	v_mfma_f32_16x16x32_bf16 v[10:13], v[156:159], v[214:217], v[10:13]
	v_mfma_f32_16x16x32_bf16 v[14:17], v[130:133], v[214:217], v[14:17]
	v_mfma_f32_16x16x32_bf16 v[62:65], v[134:137], v[194:197], v[62:65]
	v_mfma_f32_16x16x32_bf16 v[58:61], v[160:163], v[194:197], v[58:61]
	v_mfma_f32_16x16x32_bf16 v[42:45], v[160:163], v[202:205], v[42:45]
	v_mfma_f32_16x16x32_bf16 v[46:49], v[134:137], v[202:205], v[46:49]
	v_mfma_f32_16x16x32_bf16 v[30:33], v[134:137], v[210:213], v[30:33]
	v_mfma_f32_16x16x32_bf16 v[26:29], v[160:163], v[210:213], v[26:29]
	v_mfma_f32_16x16x32_bf16 v[10:13], v[160:163], v[218:221], v[10:13]
	v_mfma_f32_16x16x32_bf16 v[14:17], v[134:137], v[218:221], v[14:17]
	s_setprio 0
	s_setprio 1
	v_mfma_f32_16x16x32_bf16 v[54:57], v[164:167], v[190:193], v[54:57]
	v_mfma_f32_16x16x32_bf16 v[50:53], v[172:175], v[190:193], v[50:53]
	v_mfma_f32_16x16x32_bf16 v[34:37], v[172:175], v[198:201], v[34:37]
	v_mfma_f32_16x16x32_bf16 v[38:41], v[164:167], v[198:201], v[38:41]
	v_mfma_f32_16x16x32_bf16 v[22:25], v[164:167], v[206:209], v[22:25]
	v_mfma_f32_16x16x32_bf16 v[18:21], v[172:175], v[206:209], v[18:21]
	v_mfma_f32_16x16x32_bf16 v[2:5], v[172:175], v[214:217], v[2:5]
	v_mfma_f32_16x16x32_bf16 v[6:9], v[164:167], v[214:217], v[6:9]
	v_mfma_f32_16x16x32_bf16 v[54:57], v[168:171], v[194:197], v[54:57]
	v_mfma_f32_16x16x32_bf16 v[50:53], v[186:189], v[194:197], v[50:53]
	v_mfma_f32_16x16x32_bf16 v[34:37], v[186:189], v[202:205], v[34:37]
	v_mfma_f32_16x16x32_bf16 v[38:41], v[168:171], v[202:205], v[38:41]
	v_mfma_f32_16x16x32_bf16 v[22:25], v[168:171], v[210:213], v[22:25]
	v_mfma_f32_16x16x32_bf16 v[18:21], v[186:189], v[210:213], v[18:21]
	v_mfma_f32_16x16x32_bf16 v[2:5], v[186:189], v[218:221], v[2:5]
	v_mfma_f32_16x16x32_bf16 v[6:9], v[168:171], v[218:221], v[6:9]
	s_barrier
	s_setprio 0
	s_add_i32 s47, s47, 2
	s_add_u32 s45, s45, 0x300000
	s_addc_u32 s46, s46, 0
	s_add_u32 s12, s12, 0x200000
	s_addc_u32 s13, s13, 0
	s_cmp_gt_u32 s47, 61
	s_cbranch_scc0 .LBB0_801
	s_and_b64 vcc, exec, s[8:9]
	s_cbranch_vccz .LBB0_804
	s_barrier

.LBB0_1217:
	ds_read_b128 v[146:149], v152
	ds_read_b128 v[156:159], v152 offset:1024
	ds_read_b128 v[160:163], v152 offset:2048
	ds_read_b128 v[164:167], v152 offset:3072
	ds_read_b128 v[168:171], v153
	ds_read_b128 v[172:175], v153 offset:1024
	ds_read_b128 v[176:179], v153 offset:2048
	ds_read_b128 v[180:183], v153 offset:3072
	s_add_u32 s22, s20, 0xfc000
	s_addc_u32 s23, s21, 0
	s_cmp_eq_u32 s43, 60
	s_cselect_b32 s26, s15, s22
	s_cselect_b32 s27, s5, s23
	s_cselect_b32 s24, s40, s41
	s_cselect_b32 s25, s13, s42
	s_add_u32 s22, s26, 0x100000
	s_addc_u32 s23, s27, 0
	s_add_i32 m0, s1, 0xc000
	ds_read_b128 v[184:187], v154
	ds_read_b128 v[188:191], v154 offset:1024
	ds_read_b128 v[192:195], v154 offset:2048
	ds_read_b128 v[196:199], v154 offset:3072
	ds_read_b128 v[206:209], v154 offset:4096
	ds_read_b128 v[212:215], v154 offset:5120
	ds_read_b128 v[220:223], v154 offset:6144
	ds_read_b128 v[224:227], v154 offset:7168
	global_load_lds_dwordx4 v138, s[20:21]
	s_add_i32 m0, s1, 0xe000
	s_nop 0
	global_load_lds_dwordx4 v140, s[20:21]
	s_waitcnt vmcnt(8)
	s_waitcnt lgkmcnt(0)
	s_setprio 1
	s_barrier
	v_mfma_f32_16x16x32_bf16 v[126:129], v[146:149], v[184:187], v[126:129]
	v_mfma_f32_16x16x32_bf16 v[122:125], v[160:163], v[184:187], v[122:125]
	v_mfma_f32_16x16x32_bf16 v[106:109], v[160:163], v[192:195], v[106:109]
	v_mfma_f32_16x16x32_bf16 v[110:113], v[146:149], v[192:195], v[110:113]
	v_mfma_f32_16x16x32_bf16 v[94:97], v[146:149], v[206:209], v[94:97]
	v_mfma_f32_16x16x32_bf16 v[90:93], v[160:163], v[206:209], v[90:93]
	v_mfma_f32_16x16x32_bf16 v[74:77], v[160:163], v[220:223], v[74:77]
	v_mfma_f32_16x16x32_bf16 v[78:81], v[146:149], v[220:223], v[78:81]
	v_mfma_f32_16x16x32_bf16 v[126:129], v[156:159], v[188:191], v[126:129]
	v_mfma_f32_16x16x32_bf16 v[122:125], v[164:167], v[188:191], v[122:125]
	v_mfma_f32_16x16x32_bf16 v[106:109], v[164:167], v[196:199], v[106:109]
	v_mfma_f32_16x16x32_bf16 v[110:113], v[156:159], v[196:199], v[110:113]
	v_mfma_f32_16x16x32_bf16 v[94:97], v[156:159], v[212:215], v[94:97]
	v_mfma_f32_16x16x32_bf16 v[90:93], v[164:167], v[212:215], v[90:93]
	v_mfma_f32_16x16x32_bf16 v[74:77], v[164:167], v[224:227], v[74:77]
	v_mfma_f32_16x16x32_bf16 v[78:81], v[156:159], v[224:227], v[78:81]
	s_setprio 0
	s_setprio 1
	v_mfma_f32_16x16x32_bf16 v[118:121], v[168:171], v[184:187], v[118:121]
	v_mfma_f32_16x16x32_bf16 v[114:117], v[176:179], v[184:187], v[114:117]
	v_mfma_f32_16x16x32_bf16 v[98:101], v[176:179], v[192:195], v[98:101]
	v_mfma_f32_16x16x32_bf16 v[102:105], v[168:171], v[192:195], v[102:105]
	v_mfma_f32_16x16x32_bf16 v[86:89], v[168:171], v[206:209], v[86:89]
	v_mfma_f32_16x16x32_bf16 v[82:85], v[176:179], v[206:209], v[82:85]
	v_mfma_f32_16x16x32_bf16 v[66:69], v[176:179], v[220:223], v[66:69]
	v_mfma_f32_16x16x32_bf16 v[70:73], v[168:171], v[220:223], v[70:73]
	v_mfma_f32_16x16x32_bf16 v[118:121], v[172:175], v[188:191], v[118:121]
	v_mfma_f32_16x16x32_bf16 v[114:117], v[180:183], v[188:191], v[114:117]
	v_mfma_f32_16x16x32_bf16 v[98:101], v[180:183], v[196:199], v[98:101]
	v_mfma_f32_16x16x32_bf16 v[102:105], v[172:175], v[196:199], v[102:105]
	v_mfma_f32_16x16x32_bf16 v[86:89], v[172:175], v[212:215], v[86:89]
	v_mfma_f32_16x16x32_bf16 v[82:85], v[180:183], v[212:215], v[82:85]
	v_mfma_f32_16x16x32_bf16 v[66:69], v[180:183], v[224:227], v[66:69]
	v_mfma_f32_16x16x32_bf16 v[70:73], v[172:175], v[224:227], v[70:73]
	s_barrier
	s_setprio 0
	s_add_i32 s44, s37, s0
	s_mov_b32 m0, s44
	ds_read_b128 v[184:187], v154 offset:16384
	ds_read_b128 v[188:191], v154 offset:17408
	ds_read_b128 v[192:195], v154 offset:18432
	ds_read_b128 v[196:199], v154 offset:19456
	ds_read_b128 v[206:209], v154 offset:20480
	ds_read_b128 v[212:215], v154 offset:21504
	ds_read_b128 v[220:223], v154 offset:22528
	ds_read_b128 v[224:227], v154 offset:23552
	global_load_lds_dwordx4 v132, s[24:25]
	s_add_i32 m0, s44, 0x2000
	s_add_u32 s44, s24, 0x4000
	s_addc_u32 s45, s25, 0
	s_add_i32 s46, s38, s0
	global_load_lds_dwordx4 v136, s[24:25]
	s_mov_b32 m0, s46
	s_nop 0
	global_load_lds_dwordx4 v132, s[44:45]
	s_add_i32 m0, s46, 0x2000
	s_nop 0
	global_load_lds_dwordx4 v136, s[44:45]
	s_mov_b32 m0, s1
	s_nop 0
	global_load_lds_dwordx4 v130, s[26:27]
	s_mov_b32 m0, s28
	s_nop 0
	global_load_lds_dwordx4 v134, s[26:27]
	s_waitcnt vmcnt(8)
	s_waitcnt lgkmcnt(0)
	s_setprio 1
	s_barrier
	v_mfma_f32_16x16x32_bf16 v[62:65], v[146:149], v[184:187], v[62:65]
	v_mfma_f32_16x16x32_bf16 v[58:61], v[160:163], v[184:187], v[58:61]
	v_mfma_f32_16x16x32_bf16 v[42:45], v[160:163], v[192:195], v[42:45]
	v_mfma_f32_16x16x32_bf16 v[46:49], v[146:149], v[192:195], v[46:49]
	v_mfma_f32_16x16x32_bf16 v[30:33], v[146:149], v[206:209], v[30:33]
	v_mfma_f32_16x16x32_bf16 v[26:29], v[160:163], v[206:209], v[26:29]
	v_mfma_f32_16x16x32_bf16 v[10:13], v[160:163], v[220:223], v[10:13]
	v_mfma_f32_16x16x32_bf16 v[14:17], v[146:149], v[220:223], v[14:17]
	v_mfma_f32_16x16x32_bf16 v[62:65], v[156:159], v[188:191], v[62:65]
	v_mfma_f32_16x16x32_bf16 v[58:61], v[164:167], v[188:191], v[58:61]
	v_mfma_f32_16x16x32_bf16 v[42:45], v[164:167], v[196:199], v[42:45]
	v_mfma_f32_16x16x32_bf16 v[46:49], v[156:159], v[196:199], v[46:49]
	v_mfma_f32_16x16x32_bf16 v[30:33], v[156:159], v[212:215], v[30:33]
	v_mfma_f32_16x16x32_bf16 v[26:29], v[164:167], v[212:215], v[26:29]
	v_mfma_f32_16x16x32_bf16 v[10:13], v[164:167], v[224:227], v[10:13]
	v_mfma_f32_16x16x32_bf16 v[14:17], v[156:159], v[224:227], v[14:17]
	s_setprio 0
	s_setprio 1
	v_mfma_f32_16x16x32_bf16 v[54:57], v[168:171], v[184:187], v[54:57]
	v_mfma_f32_16x16x32_bf16 v[50:53], v[176:179], v[184:187], v[50:53]
	v_mfma_f32_16x16x32_bf16 v[34:37], v[176:179], v[192:195], v[34:37]
	v_mfma_f32_16x16x32_bf16 v[38:41], v[168:171], v[192:195], v[38:41]
	v_mfma_f32_16x16x32_bf16 v[22:25], v[168:171], v[206:209], v[22:25]
	v_mfma_f32_16x16x32_bf16 v[18:21], v[176:179], v[206:209], v[18:21]
	v_mfma_f32_16x16x32_bf16 v[2:5], v[176:179], v[220:223], v[2:5]
	v_mfma_f32_16x16x32_bf16 v[6:9], v[168:171], v[220:223], v[6:9]
	v_mfma_f32_16x16x32_bf16 v[54:57], v[172:175], v[188:191], v[54:57]
	v_mfma_f32_16x16x32_bf16 v[50:53], v[180:183], v[188:191], v[50:53]
	v_mfma_f32_16x16x32_bf16 v[34:37], v[180:183], v[196:199], v[34:37]
	v_mfma_f32_16x16x32_bf16 v[38:41], v[172:175], v[196:199], v[38:41]
	v_mfma_f32_16x16x32_bf16 v[22:25], v[172:175], v[212:215], v[22:25]
	v_mfma_f32_16x16x32_bf16 v[18:21], v[180:183], v[212:215], v[18:21]
	v_mfma_f32_16x16x32_bf16 v[2:5], v[180:183], v[224:227], v[2:5]
	v_mfma_f32_16x16x32_bf16 v[6:9], v[172:175], v[224:227], v[6:9]
	s_barrier
	s_setprio 0
	s_add_i32 s44, 0, 0x18000
	v_add_u32_e32 v155, s44, v151
	s_add_i32 s45, 0, 0x1c000
	ds_read_b128 v[146:149], v155
	ds_read_b128 v[156:159], v155 offset:1024
	ds_read_b128 v[160:163], v155 offset:2048
	ds_read_b128 v[164:167], v155 offset:3072
	v_add_u32_e32 v155, s45, v151
	ds_read_b128 v[168:171], v155
	ds_read_b128 v[172:175], v155 offset:1024
	ds_read_b128 v[176:179], v155 offset:2048
	ds_read_b128 v[180:183], v155 offset:3072
	s_add_u32 s26, s26, 0x4000
	s_addc_u32 s27, s27, 0
	s_mov_b32 m0, s29
	ds_read_b128 v[184:187], v154 offset:32768
	ds_read_b128 v[188:191], v154 offset:33792
	ds_read_b128 v[192:195], v154 offset:34816
	ds_read_b128 v[196:199], v154 offset:35840
	ds_read_b128 v[206:209], v154 offset:36864
	ds_read_b128 v[212:215], v154 offset:37888
	ds_read_b128 v[220:223], v154 offset:38912
	ds_read_b128 v[224:227], v154 offset:39936
	global_load_lds_dwordx4 v130, s[26:27]
	s_mov_b32 m0, s30
	s_nop 0
	global_load_lds_dwordx4 v134, s[26:27]
	s_waitcnt vmcnt(8)
	s_waitcnt lgkmcnt(0)
	s_setprio 1
	s_barrier
	v_mfma_f32_16x16x32_bf16 v[126:129], v[146:149], v[184:187], v[126:129]
	v_mfma_f32_16x16x32_bf16 v[122:125], v[160:163], v[184:187], v[122:125]
	v_mfma_f32_16x16x32_bf16 v[106:109], v[160:163], v[192:195], v[106:109]
	v_mfma_f32_16x16x32_bf16 v[110:113], v[146:149], v[192:195], v[110:113]
	v_mfma_f32_16x16x32_bf16 v[94:97], v[146:149], v[206:209], v[94:97]
	v_mfma_f32_16x16x32_bf16 v[90:93], v[160:163], v[206:209], v[90:93]
	v_mfma_f32_16x16x32_bf16 v[74:77], v[160:163], v[220:223], v[74:77]
	v_mfma_f32_16x16x32_bf16 v[78:81], v[146:149], v[220:223], v[78:81]
	v_mfma_f32_16x16x32_bf16 v[126:129], v[156:159], v[188:191], v[126:129]
	v_mfma_f32_16x16x32_bf16 v[122:125], v[164:167], v[188:191], v[122:125]
	v_mfma_f32_16x16x32_bf16 v[106:109], v[164:167], v[196:199], v[106:109]
	v_mfma_f32_16x16x32_bf16 v[110:113], v[156:159], v[196:199], v[110:113]
	v_mfma_f32_16x16x32_bf16 v[94:97], v[156:159], v[212:215], v[94:97]
	v_mfma_f32_16x16x32_bf16 v[90:93], v[164:167], v[212:215], v[90:93]
	v_mfma_f32_16x16x32_bf16 v[74:77], v[164:167], v[224:227], v[74:77]
	v_mfma_f32_16x16x32_bf16 v[78:81], v[156:159], v[224:227], v[78:81]
	s_setprio 0
	s_setprio 1
	v_mfma_f32_16x16x32_bf16 v[118:121], v[168:171], v[184:187], v[118:121]
	v_mfma_f32_16x16x32_bf16 v[114:117], v[176:179], v[184:187], v[114:117]
	v_mfma_f32_16x16x32_bf16 v[98:101], v[176:179], v[192:195], v[98:101]
	v_mfma_f32_16x16x32_bf16 v[102:105], v[168:171], v[192:195], v[102:105]
	v_mfma_f32_16x16x32_bf16 v[86:89], v[168:171], v[206:209], v[86:89]
	v_mfma_f32_16x16x32_bf16 v[82:85], v[176:179], v[206:209], v[82:85]
	v_mfma_f32_16x16x32_bf16 v[66:69], v[176:179], v[220:223], v[66:69]
	v_mfma_f32_16x16x32_bf16 v[70:73], v[168:171], v[220:223], v[70:73]
	v_mfma_f32_16x16x32_bf16 v[118:121], v[172:175], v[188:191], v[118:121]
	v_mfma_f32_16x16x32_bf16 v[114:117], v[180:183], v[188:191], v[114:117]
	v_mfma_f32_16x16x32_bf16 v[98:101], v[180:183], v[196:199], v[98:101]
	v_mfma_f32_16x16x32_bf16 v[102:105], v[172:175], v[196:199], v[102:105]
	v_mfma_f32_16x16x32_bf16 v[86:89], v[172:175], v[212:215], v[86:89]
	v_mfma_f32_16x16x32_bf16 v[82:85], v[180:183], v[212:215], v[82:85]
	v_mfma_f32_16x16x32_bf16 v[66:69], v[180:183], v[224:227], v[66:69]
	v_mfma_f32_16x16x32_bf16 v[70:73], v[172:175], v[224:227], v[70:73]
	s_barrier
	s_setprio 0
	s_add_u32 s26, s24, 0x80000
	s_addc_u32 s27, s25, 0
	s_add_i32 s44, s44, s0
	s_mov_b32 m0, s44
	ds_read_b128 v[184:187], v154 offset:49152
	ds_read_b128 v[188:191], v154 offset:50176
	ds_read_b128 v[192:195], v154 offset:51200
	ds_read_b128 v[196:199], v154 offset:52224
	ds_read_b128 v[206:209], v154 offset:53248
	ds_read_b128 v[212:215], v154 offset:54272
	ds_read_b128 v[220:223], v154 offset:55296
	ds_read_b128 v[224:227], v154 offset:56320
	global_load_lds_dwordx4 v132, s[26:27]
	s_add_i32 m0, s44, 0x2000
	s_add_u32 s24, s24, 0x84000
	s_addc_u32 s25, s25, 0
	global_load_lds_dwordx4 v136, s[26:27]
	s_add_i32 s26, s45, s0
	s_mov_b32 m0, s26
	s_nop 0
	global_load_lds_dwordx4 v132, s[24:25]
	s_add_i32 m0, s26, 0x2000
	s_nop 0
	global_load_lds_dwordx4 v136, s[24:25]
	s_mov_b32 m0, s35
	s_nop 0
	global_load_lds_dwordx4 v130, s[22:23]
	s_mov_b32 m0, s36
	s_nop 0
	global_load_lds_dwordx4 v134, s[22:23]
	s_waitcnt vmcnt(8)
	s_waitcnt lgkmcnt(0)
	s_setprio 1
	s_barrier
	v_mfma_f32_16x16x32_bf16 v[62:65], v[146:149], v[184:187], v[62:65]
	v_mfma_f32_16x16x32_bf16 v[58:61], v[160:163], v[184:187], v[58:61]
	v_mfma_f32_16x16x32_bf16 v[42:45], v[160:163], v[192:195], v[42:45]
	v_mfma_f32_16x16x32_bf16 v[46:49], v[146:149], v[192:195], v[46:49]
	v_mfma_f32_16x16x32_bf16 v[30:33], v[146:149], v[206:209], v[30:33]
	v_mfma_f32_16x16x32_bf16 v[26:29], v[160:163], v[206:209], v[26:29]
	v_mfma_f32_16x16x32_bf16 v[10:13], v[160:163], v[220:223], v[10:13]
	v_mfma_f32_16x16x32_bf16 v[14:17], v[146:149], v[220:223], v[14:17]
	v_mfma_f32_16x16x32_bf16 v[62:65], v[156:159], v[188:191], v[62:65]
	v_mfma_f32_16x16x32_bf16 v[58:61], v[164:167], v[188:191], v[58:61]
	v_mfma_f32_16x16x32_bf16 v[42:45], v[164:167], v[196:199], v[42:45]
	v_mfma_f32_16x16x32_bf16 v[46:49], v[156:159], v[196:199], v[46:49]
	v_mfma_f32_16x16x32_bf16 v[30:33], v[156:159], v[212:215], v[30:33]
	v_mfma_f32_16x16x32_bf16 v[26:29], v[164:167], v[212:215], v[26:29]
	v_mfma_f32_16x16x32_bf16 v[10:13], v[164:167], v[224:227], v[10:13]
	v_mfma_f32_16x16x32_bf16 v[14:17], v[156:159], v[224:227], v[14:17]
	s_setprio 0
	s_setprio 1
	v_mfma_f32_16x16x32_bf16 v[54:57], v[168:171], v[184:187], v[54:57]
	v_mfma_f32_16x16x32_bf16 v[50:53], v[176:179], v[184:187], v[50:53]
	v_mfma_f32_16x16x32_bf16 v[34:37], v[176:179], v[192:195], v[34:37]
	v_mfma_f32_16x16x32_bf16 v[38:41], v[168:171], v[192:195], v[38:41]
	v_mfma_f32_16x16x32_bf16 v[22:25], v[168:171], v[206:209], v[22:25]
	v_mfma_f32_16x16x32_bf16 v[18:21], v[176:179], v[206:209], v[18:21]
	v_mfma_f32_16x16x32_bf16 v[2:5], v[176:179], v[220:223], v[2:5]
	v_mfma_f32_16x16x32_bf16 v[6:9], v[168:171], v[220:223], v[6:9]
	v_mfma_f32_16x16x32_bf16 v[54:57], v[172:175], v[188:191], v[54:57]
	v_mfma_f32_16x16x32_bf16 v[50:53], v[180:183], v[188:191], v[50:53]
	v_mfma_f32_16x16x32_bf16 v[34:37], v[180:183], v[196:199], v[34:37]
	v_mfma_f32_16x16x32_bf16 v[38:41], v[172:175], v[196:199], v[38:41]
	v_mfma_f32_16x16x32_bf16 v[22:25], v[172:175], v[212:215], v[22:25]
	v_mfma_f32_16x16x32_bf16 v[18:21], v[180:183], v[212:215], v[18:21]
	v_mfma_f32_16x16x32_bf16 v[2:5], v[180:183], v[224:227], v[2:5]
	v_mfma_f32_16x16x32_bf16 v[6:9], v[172:175], v[224:227], v[6:9]
	s_barrier
	s_setprio 0
	s_add_i32 s43, s43, 2
	s_add_u32 s41, s41, 0x100000
	s_addc_u32 s42, s42, 0
	s_add_u32 s20, s20, 0x200000
	s_addc_u32 s21, s21, 0
	s_cmp_gt_u32 s43, 61
	s_cbranch_scc0 .LBB0_1217
	s_and_b64 vcc, exec, s[8:9]
	s_cbranch_vccz .LBB0_1220
	s_barrier

.LBB0_1670:
	ds_read_b128 v[148:151], v143
	ds_read_b128 v[152:155], v143 offset:1024
	ds_read_b128 v[156:159], v143 offset:2048
	ds_read_b128 v[160:163], v143 offset:3072
	ds_read_b128 v[164:167], v144
	ds_read_b128 v[168:171], v144 offset:1024
	ds_read_b128 v[172:175], v144 offset:2048
	ds_read_b128 v[176:179], v144 offset:3072
	s_add_u32 s10, s6, 0x4000
	s_addc_u32 s11, s7, 0
	s_cmp_eq_u32 s28, 60
	s_cselect_b32 s18, s14, s10
	s_cselect_b32 s19, s15, s11
	s_cselect_b32 s16, s4, s26
	s_cselect_b32 s17, s5, s27
	s_add_u32 s10, s18, 0x8000
	s_addc_u32 s11, s19, 0
	s_mov_b32 m0, s29
	ds_read_b128 v[180:183], v145
	ds_read_b128 v[184:187], v145 offset:1024
	ds_read_b128 v[188:191], v145 offset:2048
	ds_read_b128 v[192:195], v145 offset:3072
	ds_read_b128 v[196:199], v145 offset:4096
	ds_read_b128 v[206:209], v145 offset:5120
	ds_read_b128 v[212:215], v145 offset:6144
	ds_read_b128 v[220:223], v145 offset:7168
	global_load_lds_dwordx4 v138, s[6:7]
	s_mov_b32 m0, s30
	s_nop 0
	global_load_lds_dwordx4 v140, s[6:7]
	s_waitcnt vmcnt(8)
	s_waitcnt lgkmcnt(0)
	s_setprio 1
	s_barrier
	v_mfma_f32_16x16x32_bf16 v[126:129], v[148:151], v[180:183], v[126:129]
	v_mfma_f32_16x16x32_bf16 v[122:125], v[156:159], v[180:183], v[122:125]
	v_mfma_f32_16x16x32_bf16 v[110:113], v[156:159], v[188:191], v[110:113]
	v_mfma_f32_16x16x32_bf16 v[118:121], v[148:151], v[188:191], v[118:121]
	v_mfma_f32_16x16x32_bf16 v[102:105], v[148:151], v[196:199], v[102:105]
	v_mfma_f32_16x16x32_bf16 v[94:97], v[156:159], v[196:199], v[94:97]
	v_mfma_f32_16x16x32_bf16 v[78:81], v[156:159], v[212:215], v[78:81]
	v_mfma_f32_16x16x32_bf16 v[86:89], v[148:151], v[212:215], v[86:89]
	v_mfma_f32_16x16x32_bf16 v[126:129], v[152:155], v[184:187], v[126:129]
	v_mfma_f32_16x16x32_bf16 v[122:125], v[160:163], v[184:187], v[122:125]
	v_mfma_f32_16x16x32_bf16 v[110:113], v[160:163], v[192:195], v[110:113]
	v_mfma_f32_16x16x32_bf16 v[118:121], v[152:155], v[192:195], v[118:121]
	v_mfma_f32_16x16x32_bf16 v[102:105], v[152:155], v[206:209], v[102:105]
	v_mfma_f32_16x16x32_bf16 v[94:97], v[160:163], v[206:209], v[94:97]
	v_mfma_f32_16x16x32_bf16 v[78:81], v[160:163], v[220:223], v[78:81]
	v_mfma_f32_16x16x32_bf16 v[86:89], v[152:155], v[220:223], v[86:89]
	s_setprio 0
	s_setprio 1
	v_mfma_f32_16x16x32_bf16 v[114:117], v[164:167], v[180:183], v[114:117]
	v_mfma_f32_16x16x32_bf16 v[106:109], v[172:175], v[180:183], v[106:109]
	v_mfma_f32_16x16x32_bf16 v[90:93], v[172:175], v[188:191], v[90:93]
	v_mfma_f32_16x16x32_bf16 v[98:101], v[164:167], v[188:191], v[98:101]
	v_mfma_f32_16x16x32_bf16 v[82:85], v[164:167], v[196:199], v[82:85]
	v_mfma_f32_16x16x32_bf16 v[74:77], v[172:175], v[196:199], v[74:77]
	v_mfma_f32_16x16x32_bf16 v[66:69], v[172:175], v[212:215], v[66:69]
	v_mfma_f32_16x16x32_bf16 v[70:73], v[164:167], v[212:215], v[70:73]
	v_mfma_f32_16x16x32_bf16 v[114:117], v[168:171], v[184:187], v[114:117]
	v_mfma_f32_16x16x32_bf16 v[106:109], v[176:179], v[184:187], v[106:109]
	v_mfma_f32_16x16x32_bf16 v[90:93], v[176:179], v[192:195], v[90:93]
	v_mfma_f32_16x16x32_bf16 v[98:101], v[168:171], v[192:195], v[98:101]
	v_mfma_f32_16x16x32_bf16 v[82:85], v[168:171], v[206:209], v[82:85]
	v_mfma_f32_16x16x32_bf16 v[74:77], v[176:179], v[206:209], v[74:77]
	v_mfma_f32_16x16x32_bf16 v[66:69], v[176:179], v[220:223], v[66:69]
	v_mfma_f32_16x16x32_bf16 v[70:73], v[168:171], v[220:223], v[70:73]
	s_barrier
	s_setprio 0
	s_mov_b32 m0, s31
	s_add_u32 s40, s16, 0x4000
	ds_read_b128 v[180:183], v145 offset:16384
	ds_read_b128 v[184:187], v145 offset:17408
	ds_read_b128 v[188:191], v145 offset:18432
	ds_read_b128 v[192:195], v145 offset:19456
	ds_read_b128 v[196:199], v145 offset:20480
	ds_read_b128 v[206:209], v145 offset:21504
	ds_read_b128 v[212:215], v145 offset:22528
	ds_read_b128 v[220:223], v145 offset:23552
	global_load_lds_dwordx4 v134, s[16:17]
	s_mov_b32 m0, s33
	s_addc_u32 s41, s17, 0
	global_load_lds_dwordx4 v130, s[16:17]
	s_mov_b32 m0, s34
	s_nop 0
	global_load_lds_dwordx4 v134, s[40:41]
	s_mov_b32 m0, s35
	s_nop 0
	global_load_lds_dwordx4 v130, s[40:41]
	s_mov_b32 m0, s1
	s_nop 0
	global_load_lds_dwordx4 v136, s[18:19]
	s_mov_b32 m0, s3
	s_nop 0
	global_load_lds_dwordx4 v132, s[18:19]
	s_waitcnt vmcnt(8)
	s_waitcnt lgkmcnt(0)
	s_setprio 1
	s_barrier
	v_mfma_f32_16x16x32_bf16 v[62:65], v[148:151], v[180:183], v[62:65]
	v_mfma_f32_16x16x32_bf16 v[58:61], v[156:159], v[180:183], v[58:61]
	v_mfma_f32_16x16x32_bf16 v[46:49], v[156:159], v[188:191], v[46:49]
	v_mfma_f32_16x16x32_bf16 v[54:57], v[148:151], v[188:191], v[54:57]
	v_mfma_f32_16x16x32_bf16 v[38:41], v[148:151], v[196:199], v[38:41]
	v_mfma_f32_16x16x32_bf16 v[30:33], v[156:159], v[196:199], v[30:33]
	v_mfma_f32_16x16x32_bf16 v[14:17], v[156:159], v[212:215], v[14:17]
	v_mfma_f32_16x16x32_bf16 v[22:25], v[148:151], v[212:215], v[22:25]
	v_mfma_f32_16x16x32_bf16 v[62:65], v[152:155], v[184:187], v[62:65]
	v_mfma_f32_16x16x32_bf16 v[58:61], v[160:163], v[184:187], v[58:61]
	v_mfma_f32_16x16x32_bf16 v[46:49], v[160:163], v[192:195], v[46:49]
	v_mfma_f32_16x16x32_bf16 v[54:57], v[152:155], v[192:195], v[54:57]
	v_mfma_f32_16x16x32_bf16 v[38:41], v[152:155], v[206:209], v[38:41]
	v_mfma_f32_16x16x32_bf16 v[30:33], v[160:163], v[206:209], v[30:33]
	v_mfma_f32_16x16x32_bf16 v[14:17], v[160:163], v[220:223], v[14:17]
	v_mfma_f32_16x16x32_bf16 v[22:25], v[152:155], v[220:223], v[22:25]
	s_setprio 0
	s_setprio 1
	v_mfma_f32_16x16x32_bf16 v[50:53], v[164:167], v[180:183], v[50:53]
	v_mfma_f32_16x16x32_bf16 v[42:45], v[172:175], v[180:183], v[42:45]
	v_mfma_f32_16x16x32_bf16 v[26:29], v[172:175], v[188:191], v[26:29]
	v_mfma_f32_16x16x32_bf16 v[34:37], v[164:167], v[188:191], v[34:37]
	v_mfma_f32_16x16x32_bf16 v[18:21], v[164:167], v[196:199], v[18:21]
	v_mfma_f32_16x16x32_bf16 v[10:13], v[172:175], v[196:199], v[10:13]
	v_mfma_f32_16x16x32_bf16 v[2:5], v[172:175], v[212:215], v[2:5]
	v_mfma_f32_16x16x32_bf16 v[6:9], v[164:167], v[212:215], v[6:9]
	v_mfma_f32_16x16x32_bf16 v[50:53], v[168:171], v[184:187], v[50:53]
	v_mfma_f32_16x16x32_bf16 v[42:45], v[176:179], v[184:187], v[42:45]
	v_mfma_f32_16x16x32_bf16 v[26:29], v[176:179], v[192:195], v[26:29]
	v_mfma_f32_16x16x32_bf16 v[34:37], v[168:171], v[192:195], v[34:37]
	v_mfma_f32_16x16x32_bf16 v[18:21], v[168:171], v[206:209], v[18:21]
	v_mfma_f32_16x16x32_bf16 v[10:13], v[176:179], v[206:209], v[10:13]
	v_mfma_f32_16x16x32_bf16 v[2:5], v[176:179], v[220:223], v[2:5]
	v_mfma_f32_16x16x32_bf16 v[6:9], v[168:171], v[220:223], v[6:9]
	s_barrier
	s_setprio 0
	ds_read_b128 v[148:151], v146
	ds_read_b128 v[152:155], v146 offset:1024
	ds_read_b128 v[156:159], v146 offset:2048
	ds_read_b128 v[160:163], v146 offset:3072
	ds_read_b128 v[164:167], v147
	ds_read_b128 v[168:171], v147 offset:1024
	ds_read_b128 v[172:175], v147 offset:2048
	ds_read_b128 v[176:179], v147 offset:3072
	s_add_u32 s18, s18, 0x4000
	s_addc_u32 s19, s19, 0
	s_mov_b32 m0, s20
	ds_read_b128 v[180:183], v145 offset:32768
	ds_read_b128 v[184:187], v145 offset:33792
	ds_read_b128 v[188:191], v145 offset:34816
	ds_read_b128 v[192:195], v145 offset:35840
	ds_read_b128 v[196:199], v145 offset:36864
	ds_read_b128 v[206:209], v145 offset:37888
	ds_read_b128 v[212:215], v145 offset:38912
	ds_read_b128 v[220:223], v145 offset:39936
	global_load_lds_dwordx4 v136, s[18:19]
	s_mov_b32 m0, s21
	s_nop 0
	global_load_lds_dwordx4 v132, s[18:19]
	s_waitcnt vmcnt(8)
	s_waitcnt lgkmcnt(0)
	s_setprio 1
	s_barrier
	v_mfma_f32_16x16x32_bf16 v[126:129], v[148:151], v[180:183], v[126:129]
	v_mfma_f32_16x16x32_bf16 v[122:125], v[156:159], v[180:183], v[122:125]
	v_mfma_f32_16x16x32_bf16 v[110:113], v[156:159], v[188:191], v[110:113]
	v_mfma_f32_16x16x32_bf16 v[118:121], v[148:151], v[188:191], v[118:121]
	v_mfma_f32_16x16x32_bf16 v[102:105], v[148:151], v[196:199], v[102:105]
	v_mfma_f32_16x16x32_bf16 v[94:97], v[156:159], v[196:199], v[94:97]
	v_mfma_f32_16x16x32_bf16 v[78:81], v[156:159], v[212:215], v[78:81]
	v_mfma_f32_16x16x32_bf16 v[86:89], v[148:151], v[212:215], v[86:89]
	v_mfma_f32_16x16x32_bf16 v[126:129], v[152:155], v[184:187], v[126:129]
	v_mfma_f32_16x16x32_bf16 v[122:125], v[160:163], v[184:187], v[122:125]
	v_mfma_f32_16x16x32_bf16 v[110:113], v[160:163], v[192:195], v[110:113]
	v_mfma_f32_16x16x32_bf16 v[118:121], v[152:155], v[192:195], v[118:121]
	v_mfma_f32_16x16x32_bf16 v[102:105], v[152:155], v[206:209], v[102:105]
	v_mfma_f32_16x16x32_bf16 v[94:97], v[160:163], v[206:209], v[94:97]
	v_mfma_f32_16x16x32_bf16 v[78:81], v[160:163], v[220:223], v[78:81]
	v_mfma_f32_16x16x32_bf16 v[86:89], v[152:155], v[220:223], v[86:89]
	s_setprio 0
	s_setprio 1
	v_mfma_f32_16x16x32_bf16 v[114:117], v[164:167], v[180:183], v[114:117]
	v_mfma_f32_16x16x32_bf16 v[106:109], v[172:175], v[180:183], v[106:109]
	v_mfma_f32_16x16x32_bf16 v[90:93], v[172:175], v[188:191], v[90:93]
	v_mfma_f32_16x16x32_bf16 v[98:101], v[164:167], v[188:191], v[98:101]
	v_mfma_f32_16x16x32_bf16 v[82:85], v[164:167], v[196:199], v[82:85]
	v_mfma_f32_16x16x32_bf16 v[74:77], v[172:175], v[196:199], v[74:77]
	v_mfma_f32_16x16x32_bf16 v[66:69], v[172:175], v[212:215], v[66:69]
	v_mfma_f32_16x16x32_bf16 v[70:73], v[164:167], v[212:215], v[70:73]
	v_mfma_f32_16x16x32_bf16 v[114:117], v[168:171], v[184:187], v[114:117]
	v_mfma_f32_16x16x32_bf16 v[106:109], v[176:179], v[184:187], v[106:109]
	v_mfma_f32_16x16x32_bf16 v[90:93], v[176:179], v[192:195], v[90:93]
	v_mfma_f32_16x16x32_bf16 v[98:101], v[168:171], v[192:195], v[98:101]
	v_mfma_f32_16x16x32_bf16 v[82:85], v[168:171], v[206:209], v[82:85]
	v_mfma_f32_16x16x32_bf16 v[74:77], v[176:179], v[206:209], v[74:77]
	v_mfma_f32_16x16x32_bf16 v[66:69], v[176:179], v[220:223], v[66:69]
	v_mfma_f32_16x16x32_bf16 v[70:73], v[168:171], v[220:223], v[70:73]
	s_barrier
	s_setprio 0
	s_add_u32 s18, s16, 0x20000
	s_addc_u32 s19, s17, 0
	s_mov_b32 m0, s36
	s_add_u32 s16, s16, 0x24000
	ds_read_b128 v[180:183], v145 offset:49152
	ds_read_b128 v[184:187], v145 offset:50176
	ds_read_b128 v[188:191], v145 offset:51200
	ds_read_b128 v[192:195], v145 offset:52224
	ds_read_b128 v[196:199], v145 offset:53248
	ds_read_b128 v[206:209], v145 offset:54272
	ds_read_b128 v[212:215], v145 offset:55296
	ds_read_b128 v[220:223], v145 offset:56320
	global_load_lds_dwordx4 v134, s[18:19]
	s_mov_b32 m0, s37
	s_addc_u32 s17, s17, 0
	global_load_lds_dwordx4 v130, s[18:19]
	s_mov_b32 m0, s38
	s_nop 0
	global_load_lds_dwordx4 v134, s[16:17]
	s_mov_b32 m0, s39
	s_nop 0
	global_load_lds_dwordx4 v130, s[16:17]
	s_mov_b32 m0, s24
	s_nop 0
	global_load_lds_dwordx4 v136, s[10:11]
	s_mov_b32 m0, s25
	s_nop 0
	global_load_lds_dwordx4 v132, s[10:11]
	s_waitcnt vmcnt(8)
	s_waitcnt lgkmcnt(0)
	s_setprio 1
	s_barrier
	v_mfma_f32_16x16x32_bf16 v[62:65], v[148:151], v[180:183], v[62:65]
	v_mfma_f32_16x16x32_bf16 v[58:61], v[156:159], v[180:183], v[58:61]
	v_mfma_f32_16x16x32_bf16 v[46:49], v[156:159], v[188:191], v[46:49]
	v_mfma_f32_16x16x32_bf16 v[54:57], v[148:151], v[188:191], v[54:57]
	v_mfma_f32_16x16x32_bf16 v[38:41], v[148:151], v[196:199], v[38:41]
	v_mfma_f32_16x16x32_bf16 v[30:33], v[156:159], v[196:199], v[30:33]
	v_mfma_f32_16x16x32_bf16 v[14:17], v[156:159], v[212:215], v[14:17]
	v_mfma_f32_16x16x32_bf16 v[22:25], v[148:151], v[212:215], v[22:25]
	v_mfma_f32_16x16x32_bf16 v[62:65], v[152:155], v[184:187], v[62:65]
	v_mfma_f32_16x16x32_bf16 v[58:61], v[160:163], v[184:187], v[58:61]
	v_mfma_f32_16x16x32_bf16 v[46:49], v[160:163], v[192:195], v[46:49]
	v_mfma_f32_16x16x32_bf16 v[54:57], v[152:155], v[192:195], v[54:57]
	v_mfma_f32_16x16x32_bf16 v[38:41], v[152:155], v[206:209], v[38:41]
	v_mfma_f32_16x16x32_bf16 v[30:33], v[160:163], v[206:209], v[30:33]
	v_mfma_f32_16x16x32_bf16 v[14:17], v[160:163], v[220:223], v[14:17]
	v_mfma_f32_16x16x32_bf16 v[22:25], v[152:155], v[220:223], v[22:25]
	s_setprio 0
	s_setprio 1
	v_mfma_f32_16x16x32_bf16 v[50:53], v[164:167], v[180:183], v[50:53]
	v_mfma_f32_16x16x32_bf16 v[42:45], v[172:175], v[180:183], v[42:45]
	v_mfma_f32_16x16x32_bf16 v[26:29], v[172:175], v[188:191], v[26:29]
	v_mfma_f32_16x16x32_bf16 v[34:37], v[164:167], v[188:191], v[34:37]
	v_mfma_f32_16x16x32_bf16 v[18:21], v[164:167], v[196:199], v[18:21]
	v_mfma_f32_16x16x32_bf16 v[10:13], v[172:175], v[196:199], v[10:13]
	v_mfma_f32_16x16x32_bf16 v[2:5], v[172:175], v[212:215], v[2:5]
	v_mfma_f32_16x16x32_bf16 v[6:9], v[164:167], v[212:215], v[6:9]
	v_mfma_f32_16x16x32_bf16 v[50:53], v[168:171], v[184:187], v[50:53]
	v_mfma_f32_16x16x32_bf16 v[42:45], v[176:179], v[184:187], v[42:45]
	v_mfma_f32_16x16x32_bf16 v[26:29], v[176:179], v[192:195], v[26:29]
	v_mfma_f32_16x16x32_bf16 v[34:37], v[168:171], v[192:195], v[34:37]
	v_mfma_f32_16x16x32_bf16 v[18:21], v[168:171], v[206:209], v[18:21]
	v_mfma_f32_16x16x32_bf16 v[10:13], v[176:179], v[206:209], v[10:13]
	v_mfma_f32_16x16x32_bf16 v[2:5], v[176:179], v[220:223], v[2:5]
	v_mfma_f32_16x16x32_bf16 v[6:9], v[168:171], v[220:223], v[6:9]
	s_barrier
	s_setprio 0
	s_add_i32 s28, s28, 2
	s_add_u32 s26, s26, 0x40000
	s_addc_u32 s27, s27, 0
	s_add_u32 s6, s6, 0x10000
	s_addc_u32 s7, s7, 0
	s_cmp_gt_u32 s28, 61
	s_cbranch_scc0 .LBB0_1670
	s_lshl_b32 s1, s2, 8
	v_and_or_b32 v132, v142, 15, s22
	v_lshrrev_b32_e32 v130, 1, v142
	v_and_or_b32 v130, v130, 24, s1
	v_ashrrev_i32_e32 v133, 31, v132
	v_or_b32_e32 v134, s23, v130
	v_lshlrev_b64 v[130:131], 11, v[132:133]
	v_lshl_add_u64 v[130:131], s[8:9], 0, v[130:131]
	v_lshlrev_b32_e32 v134, 1, v134
	v_mov_b32_e32 v135, 0
	v_lshl_add_u64 v[130:131], v[130:131], 0, v[134:135]
	v_cvt_pk_bf16_f32 v126, v126, v127
	v_cvt_pk_bf16_f32 v127, v128, v129
	v_cvt_pk_bf16_f32 v128, v122, v123
	v_cvt_pk_bf16_f32 v129, v124, v125
	global_store_dwordx4 v[130:131], v[126:129], off
	v_cvt_pk_bf16_f32 v114, v114, v115
	v_cvt_pk_bf16_f32 v115, v116, v117
	v_cvt_pk_bf16_f32 v116, v106, v107
	v_or_b32_e32 v106, 16, v132
	v_ashrrev_i32_e32 v107, 31, v106
	v_lshlrev_b64 v[106:107], 11, v[106:107]
	v_lshl_add_u64 v[106:107], s[8:9], 0, v[106:107]
	v_cvt_pk_bf16_f32 v117, v108, v109
	global_store_dwordx4 v[130:131], v[114:117], off offset:256
	s_mov_b32 s1, 0x40000
	s_mov_b64 s[2:3], 0x40000
	v_lshl_add_u64 v[114:115], v[106:107], 0, v[134:135]
	v_cvt_pk_bf16_f32 v106, v118, v119
	v_cvt_pk_bf16_f32 v107, v120, v121
	v_cvt_pk_bf16_f32 v108, v110, v111
	v_cvt_pk_bf16_f32 v109, v112, v113
	global_store_dwordx4 v[114:115], v[106:109], off
	v_cvt_pk_bf16_f32 v98, v98, v99
	v_cvt_pk_bf16_f32 v99, v100, v101
	v_cvt_pk_bf16_f32 v100, v90, v91
	v_or_b32_e32 v90, 32, v132
	v_ashrrev_i32_e32 v91, 31, v90
	v_lshlrev_b64 v[90:91], 11, v[90:91]
	v_lshl_add_u64 v[90:91], s[8:9], 0, v[90:91]
	v_cvt_pk_bf16_f32 v101, v92, v93
	global_store_dwordx4 v[114:115], v[98:101], off offset:256
	s_cmpk_lt_u32 s0, 0x100
	s_nop 0
	v_lshl_add_u64 v[98:99], v[90:91], 0, v[134:135]
	v_cvt_pk_bf16_f32 v90, v102, v103
	v_cvt_pk_bf16_f32 v91, v104, v105
	v_cvt_pk_bf16_f32 v92, v94, v95
	v_cvt_pk_bf16_f32 v93, v96, v97
	global_store_dwordx4 v[98:99], v[90:93], off
	v_cvt_pk_bf16_f32 v82, v82, v83
	v_cvt_pk_bf16_f32 v83, v84, v85
	v_cvt_pk_bf16_f32 v84, v74, v75
	v_or_b32_e32 v74, 48, v132
	v_ashrrev_i32_e32 v75, 31, v74
	v_lshlrev_b64 v[74:75], 11, v[74:75]
	v_lshl_add_u64 v[74:75], s[8:9], 0, v[74:75]
	v_cvt_pk_bf16_f32 v85, v76, v77
	global_store_dwordx4 v[98:99], v[82:85], off offset:256
	s_nop 1
	v_lshl_add_u64 v[82:83], v[74:75], 0, v[134:135]
	v_cvt_pk_bf16_f32 v74, v86, v87
	v_cvt_pk_bf16_f32 v75, v88, v89
	v_cvt_pk_bf16_f32 v76, v78, v79
	v_cvt_pk_bf16_f32 v77, v80, v81
	global_store_dwordx4 v[82:83], v[74:77], off
	v_cvt_pk_bf16_f32 v70, v70, v71
	v_cvt_pk_bf16_f32 v71, v72, v73
	v_cvt_pk_bf16_f32 v72, v66, v67
	v_cvt_pk_bf16_f32 v73, v68, v69
	global_store_dwordx4 v[82:83], v[70:73], off offset:256
	v_cvt_pk_bf16_f32 v62, v62, v63
	v_cvt_pk_bf16_f32 v63, v64, v65
	v_cvt_pk_bf16_f32 v64, v58, v59
	v_add_co_u32_e32 v58, vcc, s1, v130
	v_lshl_add_u64 v[66:67], v[130:131], 0, s[2:3]
	s_nop 0
	v_addc_co_u32_e32 v59, vcc, 0, v131, vcc
	s_mov_b32 s1, 0x48000
	v_cvt_pk_bf16_f32 v65, v60, v61
	global_store_dwordx4 v[58:59], v[62:65], off
	v_cvt_pk_bf16_f32 v50, v50, v51
	v_cvt_pk_bf16_f32 v51, v52, v53
	v_cvt_pk_bf16_f32 v52, v42, v43
	v_cvt_pk_bf16_f32 v53, v44, v45
	global_store_dwordx4 v[66:67], v[50:53], off offset:256
	s_mov_b64 s[2:3], 0x48000
	v_cvt_pk_bf16_f32 v42, v54, v55
	v_cvt_pk_bf16_f32 v43, v56, v57
	v_cvt_pk_bf16_f32 v44, v46, v47
	v_add_co_u32_e32 v46, vcc, s1, v130
	v_lshl_add_u64 v[50:51], v[130:131], 0, s[2:3]
	s_nop 0
	v_addc_co_u32_e32 v47, vcc, 0, v131, vcc
	s_mov_b32 s1, 0x50000
	v_cvt_pk_bf16_f32 v45, v48, v49
	global_store_dwordx4 v[46:47], v[42:45], off
	v_cvt_pk_bf16_f32 v34, v34, v35
	v_cvt_pk_bf16_f32 v35, v36, v37
	v_cvt_pk_bf16_f32 v36, v26, v27
	v_cvt_pk_bf16_f32 v37, v28, v29
	global_store_dwordx4 v[50:51], v[34:37], off offset:256
	s_mov_b64 s[2:3], 0x50000
	v_cvt_pk_bf16_f32 v26, v38, v39
	v_cvt_pk_bf16_f32 v27, v40, v41
	v_cvt_pk_bf16_f32 v28, v30, v31
	v_add_co_u32_e32 v30, vcc, s1, v130
	v_lshl_add_u64 v[34:35], v[130:131], 0, s[2:3]
	s_nop 0
	v_addc_co_u32_e32 v31, vcc, 0, v131, vcc
	s_mov_b32 s1, 0x58000
	v_cvt_pk_bf16_f32 v29, v32, v33
	global_store_dwordx4 v[30:31], v[26:29], off
	v_cvt_pk_bf16_f32 v18, v18, v19
	v_cvt_pk_bf16_f32 v19, v20, v21
	v_cvt_pk_bf16_f32 v20, v10, v11
	v_cvt_pk_bf16_f32 v21, v12, v13
	global_store_dwordx4 v[34:35], v[18:21], off offset:256
	s_mov_b64 s[2:3], 0x58000
	v_cvt_pk_bf16_f32 v10, v22, v23
	v_cvt_pk_bf16_f32 v11, v24, v25
	v_cvt_pk_bf16_f32 v12, v14, v15
	v_add_co_u32_e32 v14, vcc, s1, v130
	v_lshl_add_u64 v[18:19], v[130:131], 0, s[2:3]
	s_nop 0
	v_addc_co_u32_e32 v15, vcc, 0, v131, vcc
	v_cvt_pk_bf16_f32 v13, v16, v17
	global_store_dwordx4 v[14:15], v[10:13], off
	v_cvt_pk_bf16_f32 v6, v6, v7
	v_cvt_pk_bf16_f32 v7, v8, v9
	v_cvt_pk_bf16_f32 v8, v2, v3
	v_cvt_pk_bf16_f32 v9, v4, v5
	global_store_dwordx4 v[18:19], v[6:9], off offset:256
	s_waitcnt vmcnt(0)
	s_cbranch_scc0 .LBB0_1673
	s_barrier

.LBB0_1691:
	ds_read_b128 v[142:145], v150
	ds_read_b128 v[154:157], v150 offset:1024
	ds_read_b128 v[158:161], v150 offset:2048
	ds_read_b128 v[162:165], v150 offset:3072
	ds_read_b128 v[166:169], v151
	ds_read_b128 v[170:173], v151 offset:1024
	ds_read_b128 v[174:177], v151 offset:2048
	ds_read_b128 v[178:181], v151 offset:3072
	s_add_u32 s24, s22, 0xfc000
	s_addc_u32 s25, s23, 0
	s_cmp_eq_u32 s46, 60
	s_cselect_b32 s28, s17, s24
	s_cselect_b32 s29, s11, s25
	s_cselect_b32 s26, s43, s44
	s_cselect_b32 s27, s7, s45
	s_add_u32 s24, s28, 0x100000
	s_addc_u32 s25, s29, 0
	s_add_i32 m0, s30, 0xc000
	ds_read_b128 v[182:185], v152
	ds_read_b128 v[186:189], v152 offset:1024
	ds_read_b128 v[190:193], v152 offset:2048
	ds_read_b128 v[194:197], v152 offset:3072
	ds_read_b128 v[206:209], v152 offset:4096
	ds_read_b128 v[212:215], v152 offset:5120
	ds_read_b128 v[220:223], v152 offset:6144
	ds_read_b128 v[224:227], v152 offset:7168
	global_load_lds_dwordx4 v138, s[22:23]
	s_add_i32 m0, s30, 0xe000
	s_nop 0
	global_load_lds_dwordx4 v140, s[22:23]
	s_waitcnt vmcnt(8)
	s_waitcnt lgkmcnt(0)
	s_setprio 1
	s_barrier
	v_mfma_f32_16x16x32_bf16 v[126:129], v[142:145], v[182:185], v[126:129]
	v_mfma_f32_16x16x32_bf16 v[122:125], v[158:161], v[182:185], v[122:125]
	v_mfma_f32_16x16x32_bf16 v[106:109], v[158:161], v[190:193], v[106:109]
	v_mfma_f32_16x16x32_bf16 v[110:113], v[142:145], v[190:193], v[110:113]
	v_mfma_f32_16x16x32_bf16 v[94:97], v[142:145], v[206:209], v[94:97]
	v_mfma_f32_16x16x32_bf16 v[90:93], v[158:161], v[206:209], v[90:93]
	v_mfma_f32_16x16x32_bf16 v[74:77], v[158:161], v[220:223], v[74:77]
	v_mfma_f32_16x16x32_bf16 v[78:81], v[142:145], v[220:223], v[78:81]
	v_mfma_f32_16x16x32_bf16 v[126:129], v[154:157], v[186:189], v[126:129]
	v_mfma_f32_16x16x32_bf16 v[122:125], v[162:165], v[186:189], v[122:125]
	v_mfma_f32_16x16x32_bf16 v[106:109], v[162:165], v[194:197], v[106:109]
	v_mfma_f32_16x16x32_bf16 v[110:113], v[154:157], v[194:197], v[110:113]
	v_mfma_f32_16x16x32_bf16 v[94:97], v[154:157], v[212:215], v[94:97]
	v_mfma_f32_16x16x32_bf16 v[90:93], v[162:165], v[212:215], v[90:93]
	v_mfma_f32_16x16x32_bf16 v[74:77], v[162:165], v[224:227], v[74:77]
	v_mfma_f32_16x16x32_bf16 v[78:81], v[154:157], v[224:227], v[78:81]
	s_setprio 0
	s_setprio 1
	v_mfma_f32_16x16x32_bf16 v[118:121], v[166:169], v[182:185], v[118:121]
	v_mfma_f32_16x16x32_bf16 v[114:117], v[174:177], v[182:185], v[114:117]
	v_mfma_f32_16x16x32_bf16 v[98:101], v[174:177], v[190:193], v[98:101]
	v_mfma_f32_16x16x32_bf16 v[102:105], v[166:169], v[190:193], v[102:105]
	v_mfma_f32_16x16x32_bf16 v[86:89], v[166:169], v[206:209], v[86:89]
	v_mfma_f32_16x16x32_bf16 v[82:85], v[174:177], v[206:209], v[82:85]
	v_mfma_f32_16x16x32_bf16 v[66:69], v[174:177], v[220:223], v[66:69]
	v_mfma_f32_16x16x32_bf16 v[70:73], v[166:169], v[220:223], v[70:73]
	v_mfma_f32_16x16x32_bf16 v[118:121], v[170:173], v[186:189], v[118:121]
	v_mfma_f32_16x16x32_bf16 v[114:117], v[178:181], v[186:189], v[114:117]
	v_mfma_f32_16x16x32_bf16 v[98:101], v[178:181], v[194:197], v[98:101]
	v_mfma_f32_16x16x32_bf16 v[102:105], v[170:173], v[194:197], v[102:105]
	v_mfma_f32_16x16x32_bf16 v[86:89], v[170:173], v[212:215], v[86:89]
	v_mfma_f32_16x16x32_bf16 v[82:85], v[178:181], v[212:215], v[82:85]
	v_mfma_f32_16x16x32_bf16 v[66:69], v[178:181], v[224:227], v[66:69]
	v_mfma_f32_16x16x32_bf16 v[70:73], v[170:173], v[224:227], v[70:73]
	s_barrier
	s_setprio 0
	s_add_i32 s47, s40, s1
	s_mov_b32 m0, s47
	ds_read_b128 v[182:185], v152 offset:16384
	ds_read_b128 v[186:189], v152 offset:17408
	ds_read_b128 v[190:193], v152 offset:18432
	ds_read_b128 v[194:197], v152 offset:19456
	ds_read_b128 v[206:209], v152 offset:20480
	ds_read_b128 v[212:215], v152 offset:21504
	ds_read_b128 v[220:223], v152 offset:22528
	ds_read_b128 v[224:227], v152 offset:23552
	global_load_lds_dwordx4 v132, s[26:27]
	s_add_i32 m0, s47, 0x2000
	s_add_u32 s48, s26, 0x4000
	s_addc_u32 s49, s27, 0
	s_add_i32 s47, s41, s1
	global_load_lds_dwordx4 v136, s[26:27]
	s_mov_b32 m0, s47
	s_nop 0
	global_load_lds_dwordx4 v132, s[48:49]
	s_add_i32 m0, s47, 0x2000
	s_nop 0
	global_load_lds_dwordx4 v136, s[48:49]
	s_mov_b32 m0, s30
	s_nop 0
	global_load_lds_dwordx4 v130, s[28:29]
	s_mov_b32 m0, s31
	s_nop 0
	global_load_lds_dwordx4 v134, s[28:29]
	s_waitcnt vmcnt(8)
	s_waitcnt lgkmcnt(0)
	s_setprio 1
	s_barrier
	v_mfma_f32_16x16x32_bf16 v[62:65], v[142:145], v[182:185], v[62:65]
	v_mfma_f32_16x16x32_bf16 v[58:61], v[158:161], v[182:185], v[58:61]
	v_mfma_f32_16x16x32_bf16 v[42:45], v[158:161], v[190:193], v[42:45]
	v_mfma_f32_16x16x32_bf16 v[46:49], v[142:145], v[190:193], v[46:49]
	v_mfma_f32_16x16x32_bf16 v[30:33], v[142:145], v[206:209], v[30:33]
	v_mfma_f32_16x16x32_bf16 v[26:29], v[158:161], v[206:209], v[26:29]
	v_mfma_f32_16x16x32_bf16 v[10:13], v[158:161], v[220:223], v[10:13]
	v_mfma_f32_16x16x32_bf16 v[14:17], v[142:145], v[220:223], v[14:17]
	v_mfma_f32_16x16x32_bf16 v[62:65], v[154:157], v[186:189], v[62:65]
	v_mfma_f32_16x16x32_bf16 v[58:61], v[162:165], v[186:189], v[58:61]
	v_mfma_f32_16x16x32_bf16 v[42:45], v[162:165], v[194:197], v[42:45]
	v_mfma_f32_16x16x32_bf16 v[46:49], v[154:157], v[194:197], v[46:49]
	v_mfma_f32_16x16x32_bf16 v[30:33], v[154:157], v[212:215], v[30:33]
	v_mfma_f32_16x16x32_bf16 v[26:29], v[162:165], v[212:215], v[26:29]
	v_mfma_f32_16x16x32_bf16 v[10:13], v[162:165], v[224:227], v[10:13]
	v_mfma_f32_16x16x32_bf16 v[14:17], v[154:157], v[224:227], v[14:17]
	s_setprio 0
	s_setprio 1
	v_mfma_f32_16x16x32_bf16 v[54:57], v[166:169], v[182:185], v[54:57]
	v_mfma_f32_16x16x32_bf16 v[50:53], v[174:177], v[182:185], v[50:53]
	v_mfma_f32_16x16x32_bf16 v[34:37], v[174:177], v[190:193], v[34:37]
	v_mfma_f32_16x16x32_bf16 v[38:41], v[166:169], v[190:193], v[38:41]
	v_mfma_f32_16x16x32_bf16 v[22:25], v[166:169], v[206:209], v[22:25]
	v_mfma_f32_16x16x32_bf16 v[18:21], v[174:177], v[206:209], v[18:21]
	v_mfma_f32_16x16x32_bf16 v[2:5], v[174:177], v[220:223], v[2:5]
	v_mfma_f32_16x16x32_bf16 v[6:9], v[166:169], v[220:223], v[6:9]
	v_mfma_f32_16x16x32_bf16 v[54:57], v[170:173], v[186:189], v[54:57]
	v_mfma_f32_16x16x32_bf16 v[50:53], v[178:181], v[186:189], v[50:53]
	v_mfma_f32_16x16x32_bf16 v[34:37], v[178:181], v[194:197], v[34:37]
	v_mfma_f32_16x16x32_bf16 v[38:41], v[170:173], v[194:197], v[38:41]
	v_mfma_f32_16x16x32_bf16 v[22:25], v[170:173], v[212:215], v[22:25]
	v_mfma_f32_16x16x32_bf16 v[18:21], v[178:181], v[212:215], v[18:21]
	v_mfma_f32_16x16x32_bf16 v[2:5], v[178:181], v[224:227], v[2:5]
	v_mfma_f32_16x16x32_bf16 v[6:9], v[170:173], v[224:227], v[6:9]
	s_barrier
	s_setprio 0
	s_add_i32 s47, 0, 0x18000
	v_add_u32_e32 v146, s47, v149
	s_add_i32 s48, 0, 0x1c000
	ds_read_b128 v[142:145], v146
	ds_read_b128 v[154:157], v146 offset:1024
	ds_read_b128 v[158:161], v146 offset:2048
	ds_read_b128 v[162:165], v146 offset:3072
	v_add_u32_e32 v146, s48, v149
	ds_read_b128 v[166:169], v146
	ds_read_b128 v[170:173], v146 offset:1024
	ds_read_b128 v[174:177], v146 offset:2048
	ds_read_b128 v[178:181], v146 offset:3072
	s_add_u32 s28, s28, 0x4000
	s_addc_u32 s29, s29, 0
	s_mov_b32 m0, s33
	ds_read_b128 v[182:185], v152 offset:32768
	ds_read_b128 v[186:189], v152 offset:33792
	ds_read_b128 v[190:193], v152 offset:34816
	ds_read_b128 v[194:197], v152 offset:35840
	ds_read_b128 v[206:209], v152 offset:36864
	ds_read_b128 v[212:215], v152 offset:37888
	ds_read_b128 v[220:223], v152 offset:38912
	ds_read_b128 v[224:227], v152 offset:39936
	global_load_lds_dwordx4 v130, s[28:29]
	s_mov_b32 m0, s34
	s_nop 0
	global_load_lds_dwordx4 v134, s[28:29]
	s_waitcnt vmcnt(8)
	s_waitcnt lgkmcnt(0)
	s_setprio 1
	s_barrier
	v_mfma_f32_16x16x32_bf16 v[126:129], v[142:145], v[182:185], v[126:129]
	v_mfma_f32_16x16x32_bf16 v[122:125], v[158:161], v[182:185], v[122:125]
	v_mfma_f32_16x16x32_bf16 v[106:109], v[158:161], v[190:193], v[106:109]
	v_mfma_f32_16x16x32_bf16 v[110:113], v[142:145], v[190:193], v[110:113]
	v_mfma_f32_16x16x32_bf16 v[94:97], v[142:145], v[206:209], v[94:97]
	v_mfma_f32_16x16x32_bf16 v[90:93], v[158:161], v[206:209], v[90:93]
	v_mfma_f32_16x16x32_bf16 v[74:77], v[158:161], v[220:223], v[74:77]
	v_mfma_f32_16x16x32_bf16 v[78:81], v[142:145], v[220:223], v[78:81]
	v_mfma_f32_16x16x32_bf16 v[126:129], v[154:157], v[186:189], v[126:129]
	v_mfma_f32_16x16x32_bf16 v[122:125], v[162:165], v[186:189], v[122:125]
	v_mfma_f32_16x16x32_bf16 v[106:109], v[162:165], v[194:197], v[106:109]
	v_mfma_f32_16x16x32_bf16 v[110:113], v[154:157], v[194:197], v[110:113]
	v_mfma_f32_16x16x32_bf16 v[94:97], v[154:157], v[212:215], v[94:97]
	v_mfma_f32_16x16x32_bf16 v[90:93], v[162:165], v[212:215], v[90:93]
	v_mfma_f32_16x16x32_bf16 v[74:77], v[162:165], v[224:227], v[74:77]
	v_mfma_f32_16x16x32_bf16 v[78:81], v[154:157], v[224:227], v[78:81]
	s_setprio 0
	s_setprio 1
	v_mfma_f32_16x16x32_bf16 v[118:121], v[166:169], v[182:185], v[118:121]
	v_mfma_f32_16x16x32_bf16 v[114:117], v[174:177], v[182:185], v[114:117]
	v_mfma_f32_16x16x32_bf16 v[98:101], v[174:177], v[190:193], v[98:101]
	v_mfma_f32_16x16x32_bf16 v[102:105], v[166:169], v[190:193], v[102:105]
	v_mfma_f32_16x16x32_bf16 v[86:89], v[166:169], v[206:209], v[86:89]
	v_mfma_f32_16x16x32_bf16 v[82:85], v[174:177], v[206:209], v[82:85]
	v_mfma_f32_16x16x32_bf16 v[66:69], v[174:177], v[220:223], v[66:69]
	v_mfma_f32_16x16x32_bf16 v[70:73], v[166:169], v[220:223], v[70:73]
	v_mfma_f32_16x16x32_bf16 v[118:121], v[170:173], v[186:189], v[118:121]
	v_mfma_f32_16x16x32_bf16 v[114:117], v[178:181], v[186:189], v[114:117]
	v_mfma_f32_16x16x32_bf16 v[98:101], v[178:181], v[194:197], v[98:101]
	v_mfma_f32_16x16x32_bf16 v[102:105], v[170:173], v[194:197], v[102:105]
	v_mfma_f32_16x16x32_bf16 v[86:89], v[170:173], v[212:215], v[86:89]
	v_mfma_f32_16x16x32_bf16 v[82:85], v[178:181], v[212:215], v[82:85]
	v_mfma_f32_16x16x32_bf16 v[66:69], v[178:181], v[224:227], v[66:69]
	v_mfma_f32_16x16x32_bf16 v[70:73], v[170:173], v[224:227], v[70:73]
	s_barrier
	s_setprio 0
	s_add_u32 s28, s26, 0x10000
	s_addc_u32 s29, s27, 0
	s_add_i32 s47, s47, s1
	s_mov_b32 m0, s47
	ds_read_b128 v[182:185], v152 offset:49152
	ds_read_b128 v[186:189], v152 offset:50176
	ds_read_b128 v[190:193], v152 offset:51200
	ds_read_b128 v[194:197], v152 offset:52224
	ds_read_b128 v[206:209], v152 offset:53248
	ds_read_b128 v[212:215], v152 offset:54272
	ds_read_b128 v[220:223], v152 offset:55296
	ds_read_b128 v[224:227], v152 offset:56320
	global_load_lds_dwordx4 v132, s[28:29]
	s_add_i32 m0, s47, 0x2000
	s_add_u32 s26, s26, 0x14000
	s_addc_u32 s27, s27, 0
	global_load_lds_dwordx4 v136, s[28:29]
	s_add_i32 s28, s48, s1
	s_mov_b32 m0, s28
	s_nop 0
	global_load_lds_dwordx4 v132, s[26:27]
	s_add_i32 m0, s28, 0x2000
	s_nop 0
	global_load_lds_dwordx4 v136, s[26:27]
	s_mov_b32 m0, s38
	s_nop 0
	global_load_lds_dwordx4 v130, s[24:25]
	s_mov_b32 m0, s39
	s_nop 0
	global_load_lds_dwordx4 v134, s[24:25]
	s_waitcnt vmcnt(8)
	s_waitcnt lgkmcnt(0)
	s_setprio 1
	s_barrier
	v_mfma_f32_16x16x32_bf16 v[62:65], v[142:145], v[182:185], v[62:65]
	v_mfma_f32_16x16x32_bf16 v[58:61], v[158:161], v[182:185], v[58:61]
	v_mfma_f32_16x16x32_bf16 v[42:45], v[158:161], v[190:193], v[42:45]
	v_mfma_f32_16x16x32_bf16 v[46:49], v[142:145], v[190:193], v[46:49]
	v_mfma_f32_16x16x32_bf16 v[30:33], v[142:145], v[206:209], v[30:33]
	v_mfma_f32_16x16x32_bf16 v[26:29], v[158:161], v[206:209], v[26:29]
	v_mfma_f32_16x16x32_bf16 v[10:13], v[158:161], v[220:223], v[10:13]
	v_mfma_f32_16x16x32_bf16 v[14:17], v[142:145], v[220:223], v[14:17]
	v_mfma_f32_16x16x32_bf16 v[62:65], v[154:157], v[186:189], v[62:65]
	v_mfma_f32_16x16x32_bf16 v[58:61], v[162:165], v[186:189], v[58:61]
	v_mfma_f32_16x16x32_bf16 v[42:45], v[162:165], v[194:197], v[42:45]
	v_mfma_f32_16x16x32_bf16 v[46:49], v[154:157], v[194:197], v[46:49]
	v_mfma_f32_16x16x32_bf16 v[30:33], v[154:157], v[212:215], v[30:33]
	v_mfma_f32_16x16x32_bf16 v[26:29], v[162:165], v[212:215], v[26:29]
	v_mfma_f32_16x16x32_bf16 v[10:13], v[162:165], v[224:227], v[10:13]
	v_mfma_f32_16x16x32_bf16 v[14:17], v[154:157], v[224:227], v[14:17]
	s_setprio 0
	s_setprio 1
	v_mfma_f32_16x16x32_bf16 v[54:57], v[166:169], v[182:185], v[54:57]
	v_mfma_f32_16x16x32_bf16 v[50:53], v[174:177], v[182:185], v[50:53]
	v_mfma_f32_16x16x32_bf16 v[34:37], v[174:177], v[190:193], v[34:37]
	v_mfma_f32_16x16x32_bf16 v[38:41], v[166:169], v[190:193], v[38:41]
	v_mfma_f32_16x16x32_bf16 v[22:25], v[166:169], v[206:209], v[22:25]
	v_mfma_f32_16x16x32_bf16 v[18:21], v[174:177], v[206:209], v[18:21]
	v_mfma_f32_16x16x32_bf16 v[2:5], v[174:177], v[220:223], v[2:5]
	v_mfma_f32_16x16x32_bf16 v[6:9], v[166:169], v[220:223], v[6:9]
	v_mfma_f32_16x16x32_bf16 v[54:57], v[170:173], v[186:189], v[54:57]
	v_mfma_f32_16x16x32_bf16 v[50:53], v[178:181], v[186:189], v[50:53]
	v_mfma_f32_16x16x32_bf16 v[34:37], v[178:181], v[194:197], v[34:37]
	v_mfma_f32_16x16x32_bf16 v[38:41], v[170:173], v[194:197], v[38:41]
	v_mfma_f32_16x16x32_bf16 v[22:25], v[170:173], v[212:215], v[22:25]
	v_mfma_f32_16x16x32_bf16 v[18:21], v[178:181], v[212:215], v[18:21]
	v_mfma_f32_16x16x32_bf16 v[2:5], v[178:181], v[224:227], v[2:5]
	v_mfma_f32_16x16x32_bf16 v[6:9], v[170:173], v[224:227], v[6:9]
	s_barrier
	s_setprio 0
	s_add_i32 s46, s46, 2
	s_add_u32 s44, s44, 0x20000
	s_addc_u32 s45, s45, 0
	s_add_u32 s22, s22, 0x200000
	s_addc_u32 s23, s23, 0
	s_cmp_gt_u32 s46, 61
	s_cbranch_scc0 .LBB0_1691
	s_lshl_b32 s7, s10, 8
	v_mov_b32_e32 v144, v147
	s_add_i32 s7, s7, s36
	v_cndmask_b32_e64 v145, 0, 1, s[2:3]
	v_and_or_b32 v142, v144, 15, s7
	v_ashrrev_i32_e32 v143, 31, v142
	v_mov_b32_e32 v146, 0x3e0293ee
	v_cmp_ne_u32_e64 s[10:11], 1, v145
	s_andn2_b64 vcc, exec, s[2:3]
	v_mov_b32_e32 v148, 0x3e0293ee
	s_cbranch_vccnz .LBB0_1694
	v_readlane_b32 s22, v245, 16
	v_readlane_b32 s23, v245, 17
	s_nop 1
	v_lshl_add_u64 v[154:155], v[142:143], 2, s[22:23]
	global_load_dword v145, v[154:155], off
	s_waitcnt vmcnt(0)
	v_mul_f32_e32 v148, 0x3e0293ee, v145

.LBB0_1718:
	ds_read_b128 v[152:155], v147
	ds_read_b128 v[156:159], v147 offset:1024
	ds_read_b128 v[160:163], v147 offset:2048
	ds_read_b128 v[164:167], v147 offset:3072
	ds_read_b128 v[168:171], v148
	ds_read_b128 v[172:175], v148 offset:1024
	ds_read_b128 v[176:179], v148 offset:2048
	ds_read_b128 v[180:183], v148 offset:3072
	s_add_u32 s18, s16, 0x4000
	s_addc_u32 s19, s17, 0
	s_cmp_eq_u32 s50, 60
	s_cselect_b32 s22, s14, s18
	s_cselect_b32 s23, s15, s19
	s_cselect_b32 s20, s47, s48
	s_cselect_b32 s21, s46, s49
	s_add_u32 s18, s22, 0x8000
	s_addc_u32 s19, s23, 0
	s_mov_b32 m0, s31
	ds_read_b128 v[184:187], v149
	ds_read_b128 v[188:191], v149 offset:1024
	ds_read_b128 v[192:195], v149 offset:2048
	ds_read_b128 v[196:199], v149 offset:3072
	ds_read_b128 v[206:209], v149 offset:4096
	ds_read_b128 v[212:215], v149 offset:5120
	ds_read_b128 v[220:223], v149 offset:6144
	ds_read_b128 v[224:227], v149 offset:7168
	global_load_lds_dwordx4 v140, s[16:17]
	s_mov_b32 m0, s33
	s_nop 0
	global_load_lds_dwordx4 v142, s[16:17]
	s_waitcnt vmcnt(8)
	s_waitcnt lgkmcnt(0)
	s_setprio 1
	s_barrier
	v_mfma_f32_16x16x32_bf16 v[126:129], v[152:155], v[184:187], v[126:129]
	v_mfma_f32_16x16x32_bf16 v[122:125], v[160:163], v[184:187], v[122:125]
	v_mfma_f32_16x16x32_bf16 v[110:113], v[160:163], v[192:195], v[110:113]
	v_mfma_f32_16x16x32_bf16 v[118:121], v[152:155], v[192:195], v[118:121]
	v_mfma_f32_16x16x32_bf16 v[102:105], v[152:155], v[206:209], v[102:105]
	v_mfma_f32_16x16x32_bf16 v[94:97], v[160:163], v[206:209], v[94:97]
	v_mfma_f32_16x16x32_bf16 v[78:81], v[160:163], v[220:223], v[78:81]
	v_mfma_f32_16x16x32_bf16 v[86:89], v[152:155], v[220:223], v[86:89]
	v_mfma_f32_16x16x32_bf16 v[126:129], v[156:159], v[188:191], v[126:129]
	v_mfma_f32_16x16x32_bf16 v[122:125], v[164:167], v[188:191], v[122:125]
	v_mfma_f32_16x16x32_bf16 v[110:113], v[164:167], v[196:199], v[110:113]
	v_mfma_f32_16x16x32_bf16 v[118:121], v[156:159], v[196:199], v[118:121]
	v_mfma_f32_16x16x32_bf16 v[102:105], v[156:159], v[212:215], v[102:105]
	v_mfma_f32_16x16x32_bf16 v[94:97], v[164:167], v[212:215], v[94:97]
	v_mfma_f32_16x16x32_bf16 v[78:81], v[164:167], v[224:227], v[78:81]
	v_mfma_f32_16x16x32_bf16 v[86:89], v[156:159], v[224:227], v[86:89]
	s_setprio 0
	s_setprio 1
	v_mfma_f32_16x16x32_bf16 v[114:117], v[168:171], v[184:187], v[114:117]
	v_mfma_f32_16x16x32_bf16 v[106:109], v[176:179], v[184:187], v[106:109]
	v_mfma_f32_16x16x32_bf16 v[90:93], v[176:179], v[192:195], v[90:93]
	v_mfma_f32_16x16x32_bf16 v[98:101], v[168:171], v[192:195], v[98:101]
	v_mfma_f32_16x16x32_bf16 v[82:85], v[168:171], v[206:209], v[82:85]
	v_mfma_f32_16x16x32_bf16 v[74:77], v[176:179], v[206:209], v[74:77]
	v_mfma_f32_16x16x32_bf16 v[66:69], v[176:179], v[220:223], v[66:69]
	v_mfma_f32_16x16x32_bf16 v[70:73], v[168:171], v[220:223], v[70:73]
	v_mfma_f32_16x16x32_bf16 v[114:117], v[172:175], v[188:191], v[114:117]
	v_mfma_f32_16x16x32_bf16 v[106:109], v[180:183], v[188:191], v[106:109]
	v_mfma_f32_16x16x32_bf16 v[90:93], v[180:183], v[196:199], v[90:93]
	v_mfma_f32_16x16x32_bf16 v[98:101], v[172:175], v[196:199], v[98:101]
	v_mfma_f32_16x16x32_bf16 v[82:85], v[172:175], v[212:215], v[82:85]
	v_mfma_f32_16x16x32_bf16 v[74:77], v[180:183], v[212:215], v[74:77]
	v_mfma_f32_16x16x32_bf16 v[66:69], v[180:183], v[224:227], v[66:69]
	v_mfma_f32_16x16x32_bf16 v[70:73], v[172:175], v[224:227], v[70:73]
	s_barrier
	s_setprio 0
	s_mov_b32 m0, s36
	s_add_u32 s52, s20, 0x4000
	ds_read_b128 v[184:187], v149 offset:16384
	ds_read_b128 v[188:191], v149 offset:17408
	ds_read_b128 v[192:195], v149 offset:18432
	ds_read_b128 v[196:199], v149 offset:19456
	ds_read_b128 v[206:209], v149 offset:20480
	ds_read_b128 v[212:215], v149 offset:21504
	ds_read_b128 v[220:223], v149 offset:22528
	ds_read_b128 v[224:227], v149 offset:23552
	global_load_lds_dwordx4 v134, s[20:21]
	s_mov_b32 m0, s37
	s_addc_u32 s53, s21, 0
	global_load_lds_dwordx4 v130, s[20:21]
	s_mov_b32 m0, s38
	s_nop 0
	global_load_lds_dwordx4 v134, s[52:53]
	s_mov_b32 m0, s39
	s_nop 0
	global_load_lds_dwordx4 v130, s[52:53]
	s_mov_b32 m0, s1
	s_nop 0
	global_load_lds_dwordx4 v136, s[22:23]
	s_mov_b32 m0, s24
	s_nop 0
	global_load_lds_dwordx4 v132, s[22:23]
	s_waitcnt vmcnt(8)
	s_waitcnt lgkmcnt(0)
	s_setprio 1
	s_barrier
	v_mfma_f32_16x16x32_bf16 v[62:65], v[152:155], v[184:187], v[62:65]
	v_mfma_f32_16x16x32_bf16 v[58:61], v[160:163], v[184:187], v[58:61]
	v_mfma_f32_16x16x32_bf16 v[46:49], v[160:163], v[192:195], v[46:49]
	v_mfma_f32_16x16x32_bf16 v[54:57], v[152:155], v[192:195], v[54:57]
	v_mfma_f32_16x16x32_bf16 v[38:41], v[152:155], v[206:209], v[38:41]
	v_mfma_f32_16x16x32_bf16 v[30:33], v[160:163], v[206:209], v[30:33]
	v_mfma_f32_16x16x32_bf16 v[14:17], v[160:163], v[220:223], v[14:17]
	v_mfma_f32_16x16x32_bf16 v[22:25], v[152:155], v[220:223], v[22:25]
	v_mfma_f32_16x16x32_bf16 v[62:65], v[156:159], v[188:191], v[62:65]
	v_mfma_f32_16x16x32_bf16 v[58:61], v[164:167], v[188:191], v[58:61]
	v_mfma_f32_16x16x32_bf16 v[46:49], v[164:167], v[196:199], v[46:49]
	v_mfma_f32_16x16x32_bf16 v[54:57], v[156:159], v[196:199], v[54:57]
	v_mfma_f32_16x16x32_bf16 v[38:41], v[156:159], v[212:215], v[38:41]
	v_mfma_f32_16x16x32_bf16 v[30:33], v[164:167], v[212:215], v[30:33]
	v_mfma_f32_16x16x32_bf16 v[14:17], v[164:167], v[224:227], v[14:17]
	v_mfma_f32_16x16x32_bf16 v[22:25], v[156:159], v[224:227], v[22:25]
	s_setprio 0
	s_setprio 1
	v_mfma_f32_16x16x32_bf16 v[50:53], v[168:171], v[184:187], v[50:53]
	v_mfma_f32_16x16x32_bf16 v[42:45], v[176:179], v[184:187], v[42:45]
	v_mfma_f32_16x16x32_bf16 v[26:29], v[176:179], v[192:195], v[26:29]
	v_mfma_f32_16x16x32_bf16 v[34:37], v[168:171], v[192:195], v[34:37]
	v_mfma_f32_16x16x32_bf16 v[18:21], v[168:171], v[206:209], v[18:21]
	v_mfma_f32_16x16x32_bf16 v[10:13], v[176:179], v[206:209], v[10:13]
	v_mfma_f32_16x16x32_bf16 v[2:5], v[176:179], v[220:223], v[2:5]
	v_mfma_f32_16x16x32_bf16 v[6:9], v[168:171], v[220:223], v[6:9]
	v_mfma_f32_16x16x32_bf16 v[50:53], v[172:175], v[188:191], v[50:53]
	v_mfma_f32_16x16x32_bf16 v[42:45], v[180:183], v[188:191], v[42:45]
	v_mfma_f32_16x16x32_bf16 v[26:29], v[180:183], v[196:199], v[26:29]
	v_mfma_f32_16x16x32_bf16 v[34:37], v[172:175], v[196:199], v[34:37]
	v_mfma_f32_16x16x32_bf16 v[18:21], v[172:175], v[212:215], v[18:21]
	v_mfma_f32_16x16x32_bf16 v[10:13], v[180:183], v[212:215], v[10:13]
	v_mfma_f32_16x16x32_bf16 v[2:5], v[180:183], v[224:227], v[2:5]
	v_mfma_f32_16x16x32_bf16 v[6:9], v[172:175], v[224:227], v[6:9]
	s_barrier
	s_setprio 0
	ds_read_b128 v[152:155], v150
	ds_read_b128 v[156:159], v150 offset:1024
	ds_read_b128 v[160:163], v150 offset:2048
	ds_read_b128 v[164:167], v150 offset:3072
	ds_read_b128 v[168:171], v151
	ds_read_b128 v[172:175], v151 offset:1024
	ds_read_b128 v[176:179], v151 offset:2048
	ds_read_b128 v[180:183], v151 offset:3072
	s_add_u32 s22, s22, 0x4000
	s_addc_u32 s23, s23, 0
	s_mov_b32 m0, s25
	ds_read_b128 v[184:187], v149 offset:32768
	ds_read_b128 v[188:191], v149 offset:33792
	ds_read_b128 v[192:195], v149 offset:34816
	ds_read_b128 v[196:199], v149 offset:35840
	ds_read_b128 v[206:209], v149 offset:36864
	ds_read_b128 v[212:215], v149 offset:37888
	ds_read_b128 v[220:223], v149 offset:38912
	ds_read_b128 v[224:227], v149 offset:39936
	global_load_lds_dwordx4 v136, s[22:23]
	s_mov_b32 m0, s26
	s_nop 0
	global_load_lds_dwordx4 v132, s[22:23]
	s_waitcnt vmcnt(8)
	s_waitcnt lgkmcnt(0)
	s_setprio 1
	s_barrier
	v_mfma_f32_16x16x32_bf16 v[126:129], v[152:155], v[184:187], v[126:129]
	v_mfma_f32_16x16x32_bf16 v[122:125], v[160:163], v[184:187], v[122:125]
	v_mfma_f32_16x16x32_bf16 v[110:113], v[160:163], v[192:195], v[110:113]
	v_mfma_f32_16x16x32_bf16 v[118:121], v[152:155], v[192:195], v[118:121]
	v_mfma_f32_16x16x32_bf16 v[102:105], v[152:155], v[206:209], v[102:105]
	v_mfma_f32_16x16x32_bf16 v[94:97], v[160:163], v[206:209], v[94:97]
	v_mfma_f32_16x16x32_bf16 v[78:81], v[160:163], v[220:223], v[78:81]
	v_mfma_f32_16x16x32_bf16 v[86:89], v[152:155], v[220:223], v[86:89]
	v_mfma_f32_16x16x32_bf16 v[126:129], v[156:159], v[188:191], v[126:129]
	v_mfma_f32_16x16x32_bf16 v[122:125], v[164:167], v[188:191], v[122:125]
	v_mfma_f32_16x16x32_bf16 v[110:113], v[164:167], v[196:199], v[110:113]
	v_mfma_f32_16x16x32_bf16 v[118:121], v[156:159], v[196:199], v[118:121]
	v_mfma_f32_16x16x32_bf16 v[102:105], v[156:159], v[212:215], v[102:105]
	v_mfma_f32_16x16x32_bf16 v[94:97], v[164:167], v[212:215], v[94:97]
	v_mfma_f32_16x16x32_bf16 v[78:81], v[164:167], v[224:227], v[78:81]
	v_mfma_f32_16x16x32_bf16 v[86:89], v[156:159], v[224:227], v[86:89]
	s_setprio 0
	s_setprio 1
	v_mfma_f32_16x16x32_bf16 v[114:117], v[168:171], v[184:187], v[114:117]
	v_mfma_f32_16x16x32_bf16 v[106:109], v[176:179], v[184:187], v[106:109]
	v_mfma_f32_16x16x32_bf16 v[90:93], v[176:179], v[192:195], v[90:93]
	v_mfma_f32_16x16x32_bf16 v[98:101], v[168:171], v[192:195], v[98:101]
	v_mfma_f32_16x16x32_bf16 v[82:85], v[168:171], v[206:209], v[82:85]
	v_mfma_f32_16x16x32_bf16 v[74:77], v[176:179], v[206:209], v[74:77]
	v_mfma_f32_16x16x32_bf16 v[66:69], v[176:179], v[220:223], v[66:69]
	v_mfma_f32_16x16x32_bf16 v[70:73], v[168:171], v[220:223], v[70:73]
	v_mfma_f32_16x16x32_bf16 v[114:117], v[172:175], v[188:191], v[114:117]
	v_mfma_f32_16x16x32_bf16 v[106:109], v[180:183], v[188:191], v[106:109]
	v_mfma_f32_16x16x32_bf16 v[90:93], v[180:183], v[196:199], v[90:93]
	v_mfma_f32_16x16x32_bf16 v[98:101], v[172:175], v[196:199], v[98:101]
	v_mfma_f32_16x16x32_bf16 v[82:85], v[172:175], v[212:215], v[82:85]
	v_mfma_f32_16x16x32_bf16 v[74:77], v[180:183], v[212:215], v[74:77]
	v_mfma_f32_16x16x32_bf16 v[66:69], v[180:183], v[224:227], v[66:69]
	v_mfma_f32_16x16x32_bf16 v[70:73], v[172:175], v[224:227], v[70:73]
	s_barrier
	s_setprio 0
	s_add_u32 s22, s20, 0x20000
	s_addc_u32 s23, s21, 0
	s_mov_b32 m0, s40
	s_add_u32 s20, s20, 0x24000
	ds_read_b128 v[184:187], v149 offset:49152
	ds_read_b128 v[188:191], v149 offset:50176
	ds_read_b128 v[192:195], v149 offset:51200
	ds_read_b128 v[196:199], v149 offset:52224
	ds_read_b128 v[206:209], v149 offset:53248
	ds_read_b128 v[212:215], v149 offset:54272
	ds_read_b128 v[220:223], v149 offset:55296
	ds_read_b128 v[224:227], v149 offset:56320
	global_load_lds_dwordx4 v134, s[22:23]
	s_mov_b32 m0, s41
	s_addc_u32 s21, s21, 0
	global_load_lds_dwordx4 v130, s[22:23]
	s_mov_b32 m0, s42
	s_nop 0
	global_load_lds_dwordx4 v134, s[20:21]
	s_mov_b32 m0, s43
	s_nop 0
	global_load_lds_dwordx4 v130, s[20:21]
	s_mov_b32 m0, s29
	s_nop 0
	global_load_lds_dwordx4 v136, s[18:19]
	s_mov_b32 m0, s30
	s_nop 0
	global_load_lds_dwordx4 v132, s[18:19]
	s_waitcnt vmcnt(8)
	s_waitcnt lgkmcnt(0)
	s_setprio 1
	s_barrier
	v_mfma_f32_16x16x32_bf16 v[62:65], v[152:155], v[184:187], v[62:65]
	v_mfma_f32_16x16x32_bf16 v[58:61], v[160:163], v[184:187], v[58:61]
	v_mfma_f32_16x16x32_bf16 v[46:49], v[160:163], v[192:195], v[46:49]
	v_mfma_f32_16x16x32_bf16 v[54:57], v[152:155], v[192:195], v[54:57]
	v_mfma_f32_16x16x32_bf16 v[38:41], v[152:155], v[206:209], v[38:41]
	v_mfma_f32_16x16x32_bf16 v[30:33], v[160:163], v[206:209], v[30:33]
	v_mfma_f32_16x16x32_bf16 v[14:17], v[160:163], v[220:223], v[14:17]
	v_mfma_f32_16x16x32_bf16 v[22:25], v[152:155], v[220:223], v[22:25]
	v_mfma_f32_16x16x32_bf16 v[62:65], v[156:159], v[188:191], v[62:65]
	v_mfma_f32_16x16x32_bf16 v[58:61], v[164:167], v[188:191], v[58:61]
	v_mfma_f32_16x16x32_bf16 v[46:49], v[164:167], v[196:199], v[46:49]
	v_mfma_f32_16x16x32_bf16 v[54:57], v[156:159], v[196:199], v[54:57]
	v_mfma_f32_16x16x32_bf16 v[38:41], v[156:159], v[212:215], v[38:41]
	v_mfma_f32_16x16x32_bf16 v[30:33], v[164:167], v[212:215], v[30:33]
	v_mfma_f32_16x16x32_bf16 v[14:17], v[164:167], v[224:227], v[14:17]
	v_mfma_f32_16x16x32_bf16 v[22:25], v[156:159], v[224:227], v[22:25]
	s_setprio 0
	s_setprio 1
	v_mfma_f32_16x16x32_bf16 v[50:53], v[168:171], v[184:187], v[50:53]
	v_mfma_f32_16x16x32_bf16 v[42:45], v[176:179], v[184:187], v[42:45]
	v_mfma_f32_16x16x32_bf16 v[26:29], v[176:179], v[192:195], v[26:29]
	v_mfma_f32_16x16x32_bf16 v[34:37], v[168:171], v[192:195], v[34:37]
	v_mfma_f32_16x16x32_bf16 v[18:21], v[168:171], v[206:209], v[18:21]
	v_mfma_f32_16x16x32_bf16 v[10:13], v[176:179], v[206:209], v[10:13]
	v_mfma_f32_16x16x32_bf16 v[2:5], v[176:179], v[220:223], v[2:5]
	v_mfma_f32_16x16x32_bf16 v[6:9], v[168:171], v[220:223], v[6:9]
	v_mfma_f32_16x16x32_bf16 v[50:53], v[172:175], v[188:191], v[50:53]
	v_mfma_f32_16x16x32_bf16 v[42:45], v[180:183], v[188:191], v[42:45]
	v_mfma_f32_16x16x32_bf16 v[26:29], v[180:183], v[196:199], v[26:29]
	v_mfma_f32_16x16x32_bf16 v[34:37], v[172:175], v[196:199], v[34:37]
	v_mfma_f32_16x16x32_bf16 v[18:21], v[172:175], v[212:215], v[18:21]
	v_mfma_f32_16x16x32_bf16 v[10:13], v[180:183], v[212:215], v[10:13]
	v_mfma_f32_16x16x32_bf16 v[2:5], v[180:183], v[224:227], v[2:5]
	v_mfma_f32_16x16x32_bf16 v[6:9], v[172:175], v[224:227], v[6:9]
	s_barrier
	s_setprio 0
	s_add_i32 s50, s50, 2
	s_add_u32 s48, s48, 0x40000
	s_addc_u32 s49, s49, 0
	s_add_u32 s16, s16, 0x10000
	s_addc_u32 s17, s17, 0
	s_cmp_gt_u32 s50, 61
	s_cbranch_scc0 .LBB0_1718
	v_mov_b32_e32 v138, v146
	s_lshl_b32 s16, s45, 8
	v_and_or_b32 v152, v138, 15, s27
	v_lshrrev_b32_e32 v138, 1, v138
	v_and_or_b32 v138, v138, 24, s16
	v_ashrrev_i32_e32 v153, 31, v152
	v_or_b32_e32 v138, s28, v138
	v_lshlrev_b64 v[144:145], 11, v[152:153]
	v_lshl_add_u64 v[144:145], s[8:9], 0, v[144:145]
	v_lshlrev_b64 v[154:155], 1, v[138:139]
	v_lshl_add_u64 v[144:145], v[144:145], 0, v[154:155]
	v_cvt_pk_bf16_f32 v126, v126, v127
	v_cvt_pk_bf16_f32 v127, v128, v129
	v_cvt_pk_bf16_f32 v128, v122, v123
	v_cvt_pk_bf16_f32 v129, v124, v125
	global_store_dwordx4 v[144:145], v[126:129], off
	v_cvt_pk_bf16_f32 v114, v114, v115
	v_cvt_pk_bf16_f32 v115, v116, v117
	v_cvt_pk_bf16_f32 v116, v106, v107
	v_or_b32_e32 v106, 16, v152
	v_ashrrev_i32_e32 v107, 31, v106
	v_lshlrev_b64 v[106:107], 11, v[106:107]
	v_lshl_add_u64 v[106:107], s[8:9], 0, v[106:107]
	v_cvt_pk_bf16_f32 v117, v108, v109
	global_store_dwordx4 v[144:145], v[114:117], off offset:256
	s_mov_b64 s[16:17], 0x40000
	s_cmp_eq_u32 s44, 4
	v_lshl_add_u64 v[114:115], v[106:107], 0, v[154:155]
	v_cvt_pk_bf16_f32 v106, v118, v119
	v_cvt_pk_bf16_f32 v107, v120, v121
	v_cvt_pk_bf16_f32 v108, v110, v111
	v_cvt_pk_bf16_f32 v109, v112, v113
	global_store_dwordx4 v[114:115], v[106:109], off
	v_cvt_pk_bf16_f32 v98, v98, v99
	v_cvt_pk_bf16_f32 v99, v100, v101
	v_cvt_pk_bf16_f32 v100, v90, v91
	v_or_b32_e32 v90, 32, v152
	v_ashrrev_i32_e32 v91, 31, v90
	v_lshlrev_b64 v[90:91], 11, v[90:91]
	v_lshl_add_u64 v[90:91], s[8:9], 0, v[90:91]
	v_cvt_pk_bf16_f32 v101, v92, v93
	global_store_dwordx4 v[114:115], v[98:101], off offset:256
	s_mov_b32 s45, s44
	s_nop 0
	v_lshl_add_u64 v[98:99], v[90:91], 0, v[154:155]
	v_cvt_pk_bf16_f32 v90, v102, v103
	v_cvt_pk_bf16_f32 v91, v104, v105
	v_cvt_pk_bf16_f32 v92, v94, v95
	v_cvt_pk_bf16_f32 v93, v96, v97
	global_store_dwordx4 v[98:99], v[90:93], off
	v_cvt_pk_bf16_f32 v82, v82, v83
	v_cvt_pk_bf16_f32 v83, v84, v85
	v_cvt_pk_bf16_f32 v84, v74, v75
	v_or_b32_e32 v74, 48, v152
	v_ashrrev_i32_e32 v75, 31, v74
	v_lshlrev_b64 v[74:75], 11, v[74:75]
	v_lshl_add_u64 v[74:75], s[8:9], 0, v[74:75]
	v_cvt_pk_bf16_f32 v85, v76, v77
	global_store_dwordx4 v[98:99], v[82:85], off offset:256
	s_nop 1
	v_lshl_add_u64 v[82:83], v[74:75], 0, v[154:155]
	v_cvt_pk_bf16_f32 v74, v86, v87
	v_cvt_pk_bf16_f32 v75, v88, v89
	v_cvt_pk_bf16_f32 v76, v78, v79
	v_cvt_pk_bf16_f32 v77, v80, v81
	global_store_dwordx4 v[82:83], v[74:77], off
	v_cvt_pk_bf16_f32 v70, v70, v71
	v_cvt_pk_bf16_f32 v71, v72, v73
	v_cvt_pk_bf16_f32 v72, v66, v67
	v_lshl_add_u64 v[66:67], v[144:145], 0, s[16:17]
	s_mov_b32 s16, 0x40000
	v_cvt_pk_bf16_f32 v73, v68, v69
	global_store_dwordx4 v[82:83], v[70:73], off offset:256
	v_cvt_pk_bf16_f32 v62, v62, v63
	v_cvt_pk_bf16_f32 v63, v64, v65
	v_cvt_pk_bf16_f32 v64, v58, v59
	v_add_co_u32_e32 v58, vcc, s16, v144
	v_cvt_pk_bf16_f32 v65, v60, v61
	s_mov_b64 s[16:17], 0x48000
	s_nop 0
	v_addc_co_u32_e32 v59, vcc, 0, v145, vcc
	global_store_dwordx4 v[58:59], v[62:65], off
	v_cvt_pk_bf16_f32 v50, v50, v51
	v_cvt_pk_bf16_f32 v51, v52, v53
	v_cvt_pk_bf16_f32 v52, v42, v43
	v_cvt_pk_bf16_f32 v53, v44, v45
	global_store_dwordx4 v[66:67], v[50:53], off offset:256
	v_cvt_pk_bf16_f32 v42, v54, v55
	v_cvt_pk_bf16_f32 v43, v56, v57
	v_cvt_pk_bf16_f32 v44, v46, v47
	v_cvt_pk_bf16_f32 v45, v48, v49
	s_nop 1
	v_lshl_add_u64 v[50:51], v[144:145], 0, s[16:17]
	s_mov_b32 s16, 0x48000
	v_add_co_u32_e32 v46, vcc, s16, v144
	s_mov_b64 s[16:17], s[10:11]
	s_nop 0
	v_addc_co_u32_e32 v47, vcc, 0, v145, vcc
	global_store_dwordx4 v[46:47], v[42:45], off
	v_cvt_pk_bf16_f32 v34, v34, v35
	v_cvt_pk_bf16_f32 v35, v36, v37
	v_cvt_pk_bf16_f32 v36, v26, v27
	v_cvt_pk_bf16_f32 v37, v28, v29
	global_store_dwordx4 v[50:51], v[34:37], off offset:256
	v_cvt_pk_bf16_f32 v26, v38, v39
	v_cvt_pk_bf16_f32 v27, v40, v41
	v_cvt_pk_bf16_f32 v28, v30, v31
	v_add_co_u32_e32 v30, vcc, s34, v144
	s_nop 0
	v_lshl_add_u64 v[34:35], v[144:145], 0, s[4:5]
	v_addc_co_u32_e32 v31, vcc, 0, v145, vcc
	v_cvt_pk_bf16_f32 v29, v32, v33
	global_store_dwordx4 v[30:31], v[26:29], off
	v_cvt_pk_bf16_f32 v18, v18, v19
	v_cvt_pk_bf16_f32 v19, v20, v21
	v_cvt_pk_bf16_f32 v20, v10, v11
	v_cvt_pk_bf16_f32 v21, v12, v13
	global_store_dwordx4 v[34:35], v[18:21], off offset:256
	v_cvt_pk_bf16_f32 v10, v22, v23
	v_cvt_pk_bf16_f32 v11, v24, v25
	v_cvt_pk_bf16_f32 v12, v14, v15
	v_add_co_u32_e32 v14, vcc, s35, v144
	s_nop 0
	v_lshl_add_u64 v[18:19], v[144:145], 0, s[6:7]
	v_addc_co_u32_e32 v15, vcc, 0, v145, vcc
	v_cvt_pk_bf16_f32 v13, v16, v17
	global_store_dwordx4 v[14:15], v[10:13], off
	v_cvt_pk_bf16_f32 v6, v6, v7
	v_cvt_pk_bf16_f32 v7, v8, v9
	v_cvt_pk_bf16_f32 v8, v2, v3
	v_cvt_pk_bf16_f32 v9, v4, v5
	global_store_dwordx4 v[18:19], v[6:9], off offset:256
	s_cbranch_scc0 .LBB0_1717
	s_waitcnt vmcnt(0)
	s_cmpk_gt_u32 s0, 0xff
	s_cbranch_scc1 .LBB0_1722
	s_barrier

.LBB0_2185:
	ds_read_b128 v[146:149], v152
	ds_read_b128 v[156:159], v152 offset:1024
	ds_read_b128 v[160:163], v152 offset:2048
	ds_read_b128 v[164:167], v152 offset:3072
	ds_read_b128 v[168:171], v153
	ds_read_b128 v[172:175], v153 offset:1024
	ds_read_b128 v[176:179], v153 offset:2048
	ds_read_b128 v[180:183], v153 offset:3072
	s_add_u32 s22, s20, 0xfc000
	s_addc_u32 s23, s21, 0
	s_cmp_eq_u32 s44, 4
	s_cselect_b32 s26, s15, s22
	s_cselect_b32 s27, s5, s23
	s_cselect_b32 s24, s41, s42
	s_cselect_b32 s25, s13, s43
	s_add_u32 s22, s26, 0x100000
	s_addc_u32 s23, s27, 0
	s_add_i32 m0, s1, 0xc000
	ds_read_b128 v[184:187], v154
	ds_read_b128 v[188:191], v154 offset:1024
	ds_read_b128 v[192:195], v154 offset:2048
	ds_read_b128 v[196:199], v154 offset:3072
	ds_read_b128 v[206:209], v154 offset:4096
	ds_read_b128 v[212:215], v154 offset:5120
	ds_read_b128 v[220:223], v154 offset:6144
	ds_read_b128 v[224:227], v154 offset:7168
	global_load_lds_dwordx4 v138, s[20:21]
	s_add_i32 m0, s1, 0xe000
	s_nop 0
	global_load_lds_dwordx4 v140, s[20:21]
	s_waitcnt vmcnt(8)
	s_waitcnt lgkmcnt(0)
	s_setprio 1
	s_barrier
	v_mfma_f32_16x16x32_bf16 v[126:129], v[146:149], v[184:187], v[126:129]
	v_mfma_f32_16x16x32_bf16 v[122:125], v[160:163], v[184:187], v[122:125]
	v_mfma_f32_16x16x32_bf16 v[106:109], v[160:163], v[192:195], v[106:109]
	v_mfma_f32_16x16x32_bf16 v[110:113], v[146:149], v[192:195], v[110:113]
	v_mfma_f32_16x16x32_bf16 v[94:97], v[146:149], v[206:209], v[94:97]
	v_mfma_f32_16x16x32_bf16 v[90:93], v[160:163], v[206:209], v[90:93]
	v_mfma_f32_16x16x32_bf16 v[74:77], v[160:163], v[220:223], v[74:77]
	v_mfma_f32_16x16x32_bf16 v[78:81], v[146:149], v[220:223], v[78:81]
	v_mfma_f32_16x16x32_bf16 v[126:129], v[156:159], v[188:191], v[126:129]
	v_mfma_f32_16x16x32_bf16 v[122:125], v[164:167], v[188:191], v[122:125]
	v_mfma_f32_16x16x32_bf16 v[106:109], v[164:167], v[196:199], v[106:109]
	v_mfma_f32_16x16x32_bf16 v[110:113], v[156:159], v[196:199], v[110:113]
	v_mfma_f32_16x16x32_bf16 v[94:97], v[156:159], v[212:215], v[94:97]
	v_mfma_f32_16x16x32_bf16 v[90:93], v[164:167], v[212:215], v[90:93]
	v_mfma_f32_16x16x32_bf16 v[74:77], v[164:167], v[224:227], v[74:77]
	v_mfma_f32_16x16x32_bf16 v[78:81], v[156:159], v[224:227], v[78:81]
	s_setprio 0
	s_setprio 1
	v_mfma_f32_16x16x32_bf16 v[118:121], v[168:171], v[184:187], v[118:121]
	v_mfma_f32_16x16x32_bf16 v[114:117], v[176:179], v[184:187], v[114:117]
	v_mfma_f32_16x16x32_bf16 v[98:101], v[176:179], v[192:195], v[98:101]
	v_mfma_f32_16x16x32_bf16 v[102:105], v[168:171], v[192:195], v[102:105]
	v_mfma_f32_16x16x32_bf16 v[86:89], v[168:171], v[206:209], v[86:89]
	v_mfma_f32_16x16x32_bf16 v[82:85], v[176:179], v[206:209], v[82:85]
	v_mfma_f32_16x16x32_bf16 v[66:69], v[176:179], v[220:223], v[66:69]
	v_mfma_f32_16x16x32_bf16 v[70:73], v[168:171], v[220:223], v[70:73]
	v_mfma_f32_16x16x32_bf16 v[118:121], v[172:175], v[188:191], v[118:121]
	v_mfma_f32_16x16x32_bf16 v[114:117], v[180:183], v[188:191], v[114:117]
	v_mfma_f32_16x16x32_bf16 v[98:101], v[180:183], v[196:199], v[98:101]
	v_mfma_f32_16x16x32_bf16 v[102:105], v[172:175], v[196:199], v[102:105]
	v_mfma_f32_16x16x32_bf16 v[86:89], v[172:175], v[212:215], v[86:89]
	v_mfma_f32_16x16x32_bf16 v[82:85], v[180:183], v[212:215], v[82:85]
	v_mfma_f32_16x16x32_bf16 v[66:69], v[180:183], v[224:227], v[66:69]
	v_mfma_f32_16x16x32_bf16 v[70:73], v[172:175], v[224:227], v[70:73]
	s_barrier
	s_setprio 0
	s_add_i32 s45, s38, s0
	s_mov_b32 m0, s45
	ds_read_b128 v[184:187], v154 offset:16384
	ds_read_b128 v[188:191], v154 offset:17408
	ds_read_b128 v[192:195], v154 offset:18432
	ds_read_b128 v[196:199], v154 offset:19456
	ds_read_b128 v[206:209], v154 offset:20480
	ds_read_b128 v[212:215], v154 offset:21504
	ds_read_b128 v[220:223], v154 offset:22528
	ds_read_b128 v[224:227], v154 offset:23552
	global_load_lds_dwordx4 v132, s[24:25]
	s_add_i32 m0, s45, 0x2000
	s_add_u32 s46, s24, 0x4000
	s_addc_u32 s47, s25, 0
	s_add_i32 s45, s39, s0
	global_load_lds_dwordx4 v136, s[24:25]
	s_mov_b32 m0, s45
	s_nop 0
	global_load_lds_dwordx4 v132, s[46:47]
	s_add_i32 m0, s45, 0x2000
	s_nop 0
	global_load_lds_dwordx4 v136, s[46:47]
	s_mov_b32 m0, s1
	s_nop 0
	global_load_lds_dwordx4 v130, s[26:27]
	s_mov_b32 m0, s28
	s_nop 0
	global_load_lds_dwordx4 v134, s[26:27]
	s_waitcnt vmcnt(8)
	s_waitcnt lgkmcnt(0)
	s_setprio 1
	s_barrier
	v_mfma_f32_16x16x32_bf16 v[62:65], v[146:149], v[184:187], v[62:65]
	v_mfma_f32_16x16x32_bf16 v[58:61], v[160:163], v[184:187], v[58:61]
	v_mfma_f32_16x16x32_bf16 v[42:45], v[160:163], v[192:195], v[42:45]
	v_mfma_f32_16x16x32_bf16 v[46:49], v[146:149], v[192:195], v[46:49]
	v_mfma_f32_16x16x32_bf16 v[30:33], v[146:149], v[206:209], v[30:33]
	v_mfma_f32_16x16x32_bf16 v[26:29], v[160:163], v[206:209], v[26:29]
	v_mfma_f32_16x16x32_bf16 v[10:13], v[160:163], v[220:223], v[10:13]
	v_mfma_f32_16x16x32_bf16 v[14:17], v[146:149], v[220:223], v[14:17]
	v_mfma_f32_16x16x32_bf16 v[62:65], v[156:159], v[188:191], v[62:65]
	v_mfma_f32_16x16x32_bf16 v[58:61], v[164:167], v[188:191], v[58:61]
	v_mfma_f32_16x16x32_bf16 v[42:45], v[164:167], v[196:199], v[42:45]
	v_mfma_f32_16x16x32_bf16 v[46:49], v[156:159], v[196:199], v[46:49]
	v_mfma_f32_16x16x32_bf16 v[30:33], v[156:159], v[212:215], v[30:33]
	v_mfma_f32_16x16x32_bf16 v[26:29], v[164:167], v[212:215], v[26:29]
	v_mfma_f32_16x16x32_bf16 v[10:13], v[164:167], v[224:227], v[10:13]
	v_mfma_f32_16x16x32_bf16 v[14:17], v[156:159], v[224:227], v[14:17]
	s_setprio 0
	s_setprio 1
	v_mfma_f32_16x16x32_bf16 v[54:57], v[168:171], v[184:187], v[54:57]
	v_mfma_f32_16x16x32_bf16 v[50:53], v[176:179], v[184:187], v[50:53]
	v_mfma_f32_16x16x32_bf16 v[34:37], v[176:179], v[192:195], v[34:37]
	v_mfma_f32_16x16x32_bf16 v[38:41], v[168:171], v[192:195], v[38:41]
	v_mfma_f32_16x16x32_bf16 v[22:25], v[168:171], v[206:209], v[22:25]
	v_mfma_f32_16x16x32_bf16 v[18:21], v[176:179], v[206:209], v[18:21]
	v_mfma_f32_16x16x32_bf16 v[2:5], v[176:179], v[220:223], v[2:5]
	v_mfma_f32_16x16x32_bf16 v[6:9], v[168:171], v[220:223], v[6:9]
	v_mfma_f32_16x16x32_bf16 v[54:57], v[172:175], v[188:191], v[54:57]
	v_mfma_f32_16x16x32_bf16 v[50:53], v[180:183], v[188:191], v[50:53]
	v_mfma_f32_16x16x32_bf16 v[34:37], v[180:183], v[196:199], v[34:37]
	v_mfma_f32_16x16x32_bf16 v[38:41], v[172:175], v[196:199], v[38:41]
	v_mfma_f32_16x16x32_bf16 v[22:25], v[172:175], v[212:215], v[22:25]
	v_mfma_f32_16x16x32_bf16 v[18:21], v[180:183], v[212:215], v[18:21]
	v_mfma_f32_16x16x32_bf16 v[2:5], v[180:183], v[224:227], v[2:5]
	v_mfma_f32_16x16x32_bf16 v[6:9], v[172:175], v[224:227], v[6:9]
	s_barrier
	s_setprio 0
	s_add_i32 s45, 0, 0x18000
	v_add_u32_e32 v155, s45, v151
	s_add_i32 s46, 0, 0x1c000
	ds_read_b128 v[146:149], v155
	ds_read_b128 v[156:159], v155 offset:1024
	ds_read_b128 v[160:163], v155 offset:2048
	ds_read_b128 v[164:167], v155 offset:3072
	v_add_u32_e32 v155, s46, v151
	ds_read_b128 v[168:171], v155
	ds_read_b128 v[172:175], v155 offset:1024
	ds_read_b128 v[176:179], v155 offset:2048
	ds_read_b128 v[180:183], v155 offset:3072
	s_add_u32 s26, s26, 0x4000
	s_addc_u32 s27, s27, 0
	s_mov_b32 m0, s29
	ds_read_b128 v[184:187], v154 offset:32768
	ds_read_b128 v[188:191], v154 offset:33792
	ds_read_b128 v[192:195], v154 offset:34816
	ds_read_b128 v[196:199], v154 offset:35840
	ds_read_b128 v[206:209], v154 offset:36864
	ds_read_b128 v[212:215], v154 offset:37888
	ds_read_b128 v[220:223], v154 offset:38912
	ds_read_b128 v[224:227], v154 offset:39936
	global_load_lds_dwordx4 v130, s[26:27]
	s_mov_b32 m0, s30
	s_nop 0
	global_load_lds_dwordx4 v134, s[26:27]
	s_waitcnt vmcnt(8)
	s_waitcnt lgkmcnt(0)
	s_setprio 1
	s_barrier
	v_mfma_f32_16x16x32_bf16 v[126:129], v[146:149], v[184:187], v[126:129]
	v_mfma_f32_16x16x32_bf16 v[122:125], v[160:163], v[184:187], v[122:125]
	v_mfma_f32_16x16x32_bf16 v[106:109], v[160:163], v[192:195], v[106:109]
	v_mfma_f32_16x16x32_bf16 v[110:113], v[146:149], v[192:195], v[110:113]
	v_mfma_f32_16x16x32_bf16 v[94:97], v[146:149], v[206:209], v[94:97]
	v_mfma_f32_16x16x32_bf16 v[90:93], v[160:163], v[206:209], v[90:93]
	v_mfma_f32_16x16x32_bf16 v[74:77], v[160:163], v[220:223], v[74:77]
	v_mfma_f32_16x16x32_bf16 v[78:81], v[146:149], v[220:223], v[78:81]
	v_mfma_f32_16x16x32_bf16 v[126:129], v[156:159], v[188:191], v[126:129]
	v_mfma_f32_16x16x32_bf16 v[122:125], v[164:167], v[188:191], v[122:125]
	v_mfma_f32_16x16x32_bf16 v[106:109], v[164:167], v[196:199], v[106:109]
	v_mfma_f32_16x16x32_bf16 v[110:113], v[156:159], v[196:199], v[110:113]
	v_mfma_f32_16x16x32_bf16 v[94:97], v[156:159], v[212:215], v[94:97]
	v_mfma_f32_16x16x32_bf16 v[90:93], v[164:167], v[212:215], v[90:93]
	v_mfma_f32_16x16x32_bf16 v[74:77], v[164:167], v[224:227], v[74:77]
	v_mfma_f32_16x16x32_bf16 v[78:81], v[156:159], v[224:227], v[78:81]
	s_setprio 0
	s_setprio 1
	v_mfma_f32_16x16x32_bf16 v[118:121], v[168:171], v[184:187], v[118:121]
	v_mfma_f32_16x16x32_bf16 v[114:117], v[176:179], v[184:187], v[114:117]
	v_mfma_f32_16x16x32_bf16 v[98:101], v[176:179], v[192:195], v[98:101]
	v_mfma_f32_16x16x32_bf16 v[102:105], v[168:171], v[192:195], v[102:105]
	v_mfma_f32_16x16x32_bf16 v[86:89], v[168:171], v[206:209], v[86:89]
	v_mfma_f32_16x16x32_bf16 v[82:85], v[176:179], v[206:209], v[82:85]
	v_mfma_f32_16x16x32_bf16 v[66:69], v[176:179], v[220:223], v[66:69]
	v_mfma_f32_16x16x32_bf16 v[70:73], v[168:171], v[220:223], v[70:73]
	v_mfma_f32_16x16x32_bf16 v[118:121], v[172:175], v[188:191], v[118:121]
	v_mfma_f32_16x16x32_bf16 v[114:117], v[180:183], v[188:191], v[114:117]
	v_mfma_f32_16x16x32_bf16 v[98:101], v[180:183], v[196:199], v[98:101]
	v_mfma_f32_16x16x32_bf16 v[102:105], v[172:175], v[196:199], v[102:105]
	v_mfma_f32_16x16x32_bf16 v[86:89], v[172:175], v[212:215], v[86:89]
	v_mfma_f32_16x16x32_bf16 v[82:85], v[180:183], v[212:215], v[82:85]
	v_mfma_f32_16x16x32_bf16 v[66:69], v[180:183], v[224:227], v[66:69]
	v_mfma_f32_16x16x32_bf16 v[70:73], v[172:175], v[224:227], v[70:73]
	s_barrier
	s_setprio 0
	s_add_u32 s26, s24, 0x80000
	s_addc_u32 s27, s25, 0
	s_add_i32 s45, s45, s0
	s_mov_b32 m0, s45
	ds_read_b128 v[184:187], v154 offset:49152
	ds_read_b128 v[188:191], v154 offset:50176
	ds_read_b128 v[192:195], v154 offset:51200
	ds_read_b128 v[196:199], v154 offset:52224
	ds_read_b128 v[206:209], v154 offset:53248
	ds_read_b128 v[212:215], v154 offset:54272
	ds_read_b128 v[220:223], v154 offset:55296
	ds_read_b128 v[224:227], v154 offset:56320
	global_load_lds_dwordx4 v132, s[26:27]
	s_add_i32 m0, s45, 0x2000
	s_add_u32 s24, s24, 0x84000
	s_addc_u32 s25, s25, 0
	global_load_lds_dwordx4 v136, s[26:27]
	s_add_i32 s26, s46, s0
	s_mov_b32 m0, s26
	s_nop 0
	global_load_lds_dwordx4 v132, s[24:25]
	s_add_i32 m0, s26, 0x2000
	s_nop 0
	global_load_lds_dwordx4 v136, s[24:25]
	s_mov_b32 m0, s36
	s_nop 0
	global_load_lds_dwordx4 v130, s[22:23]
	s_mov_b32 m0, s37
	s_nop 0
	global_load_lds_dwordx4 v134, s[22:23]
	s_waitcnt vmcnt(8)
	s_waitcnt lgkmcnt(0)
	s_setprio 1
	s_barrier
	v_mfma_f32_16x16x32_bf16 v[62:65], v[146:149], v[184:187], v[62:65]
	v_mfma_f32_16x16x32_bf16 v[58:61], v[160:163], v[184:187], v[58:61]
	v_mfma_f32_16x16x32_bf16 v[42:45], v[160:163], v[192:195], v[42:45]
	v_mfma_f32_16x16x32_bf16 v[46:49], v[146:149], v[192:195], v[46:49]
	v_mfma_f32_16x16x32_bf16 v[30:33], v[146:149], v[206:209], v[30:33]
	v_mfma_f32_16x16x32_bf16 v[26:29], v[160:163], v[206:209], v[26:29]
	v_mfma_f32_16x16x32_bf16 v[10:13], v[160:163], v[220:223], v[10:13]
	v_mfma_f32_16x16x32_bf16 v[14:17], v[146:149], v[220:223], v[14:17]
	v_mfma_f32_16x16x32_bf16 v[62:65], v[156:159], v[188:191], v[62:65]
	v_mfma_f32_16x16x32_bf16 v[58:61], v[164:167], v[188:191], v[58:61]
	v_mfma_f32_16x16x32_bf16 v[42:45], v[164:167], v[196:199], v[42:45]
	v_mfma_f32_16x16x32_bf16 v[46:49], v[156:159], v[196:199], v[46:49]
	v_mfma_f32_16x16x32_bf16 v[30:33], v[156:159], v[212:215], v[30:33]
	v_mfma_f32_16x16x32_bf16 v[26:29], v[164:167], v[212:215], v[26:29]
	v_mfma_f32_16x16x32_bf16 v[10:13], v[164:167], v[224:227], v[10:13]
	v_mfma_f32_16x16x32_bf16 v[14:17], v[156:159], v[224:227], v[14:17]
	s_setprio 0
	s_setprio 1
	v_mfma_f32_16x16x32_bf16 v[54:57], v[168:171], v[184:187], v[54:57]
	v_mfma_f32_16x16x32_bf16 v[50:53], v[176:179], v[184:187], v[50:53]
	v_mfma_f32_16x16x32_bf16 v[34:37], v[176:179], v[192:195], v[34:37]
	v_mfma_f32_16x16x32_bf16 v[38:41], v[168:171], v[192:195], v[38:41]
	v_mfma_f32_16x16x32_bf16 v[22:25], v[168:171], v[206:209], v[22:25]
	v_mfma_f32_16x16x32_bf16 v[18:21], v[176:179], v[206:209], v[18:21]
	v_mfma_f32_16x16x32_bf16 v[2:5], v[176:179], v[220:223], v[2:5]
	v_mfma_f32_16x16x32_bf16 v[6:9], v[168:171], v[220:223], v[6:9]
	v_mfma_f32_16x16x32_bf16 v[54:57], v[172:175], v[188:191], v[54:57]
	v_mfma_f32_16x16x32_bf16 v[50:53], v[180:183], v[188:191], v[50:53]
	v_mfma_f32_16x16x32_bf16 v[34:37], v[180:183], v[196:199], v[34:37]
	v_mfma_f32_16x16x32_bf16 v[38:41], v[172:175], v[196:199], v[38:41]
	v_mfma_f32_16x16x32_bf16 v[22:25], v[172:175], v[212:215], v[22:25]
	v_mfma_f32_16x16x32_bf16 v[18:21], v[180:183], v[212:215], v[18:21]
	v_mfma_f32_16x16x32_bf16 v[2:5], v[180:183], v[224:227], v[2:5]
	v_mfma_f32_16x16x32_bf16 v[6:9], v[172:175], v[224:227], v[6:9]
	s_barrier
	s_setprio 0
	s_add_i32 s44, s44, 2
	s_add_u32 s42, s42, 0x100000
	s_addc_u32 s43, s43, 0
	s_add_u32 s20, s20, 0x200000
	s_addc_u32 s21, s21, 0
	s_cmp_gt_u32 s44, 5
	s_cbranch_scc0 .LBB0_2185
	s_and_b64 vcc, exec, s[8:9]
	s_cbranch_vccz .LBB0_2188
	s_barrier

.LBB0_2480:
	ds_read_b128 v[18:21], v182
	ds_read_b128 v[22:25], v182 offset:1024
	ds_read_b128 v[26:29], v182 offset:2048
	ds_read_b128 v[30:33], v182 offset:3072
	ds_read_b128 v[2:5], v183
	ds_read_b128 v[6:9], v183 offset:1024
	ds_read_b128 v[10:13], v183 offset:2048
	ds_read_b128 v[14:17], v183 offset:3072
	s_add_u32 s26, s24, 0xfc000
	s_addc_u32 s27, s25, 0
	s_cmp_eq_u32 s48, 28
	s_cselect_b32 s30, s17, s26
	s_cselect_b32 s31, s5, s27
	s_cselect_b32 s28, s23, s46
	s_cselect_b32 s29, s15, s47
	s_add_u32 s26, s30, 0x100000
	s_addc_u32 s27, s31, 0
	s_add_i32 m0, s34, 0xc000
	ds_read_b128 v[186:189], v184
	ds_read_b128 v[190:193], v184 offset:1024
	ds_read_b128 v[220:223], v184 offset:2048
	ds_read_b128 v[224:227], v184 offset:3072
	ds_read_b128 v[228:231], v184 offset:4096
	ds_read_b128 v[232:235], v184 offset:5120
	ds_read_b128 v[236:239], v184 offset:6144
	ds_read_b128 v[240:243], v184 offset:7168
	global_load_lds_dwordx4 v172, s[24:25]
	s_add_i32 m0, s34, 0xe000
	s_nop 0
	global_load_lds_dwordx4 v174, s[24:25]
	s_waitcnt vmcnt(8)
	s_waitcnt lgkmcnt(0)
	s_setprio 1
	s_barrier
	v_mfma_f32_16x16x128_f8f6f4 v[158:161], v[18:25], v[186:193], v[158:161]
	v_mfma_f32_16x16x128_f8f6f4 v[154:157], v[26:33], v[186:193], v[154:157]
	v_mfma_f32_16x16x128_f8f6f4 v[138:141], v[26:33], v[220:227], v[138:141]
	v_mfma_f32_16x16x128_f8f6f4 v[142:145], v[18:25], v[220:227], v[142:145]
	v_mfma_f32_16x16x128_f8f6f4 v[126:129], v[18:25], v[228:235], v[126:129]
	v_mfma_f32_16x16x128_f8f6f4 v[122:125], v[26:33], v[228:235], v[122:125]
	v_mfma_f32_16x16x128_f8f6f4 v[106:109], v[26:33], v[236:243], v[106:109]
	v_mfma_f32_16x16x128_f8f6f4 v[110:113], v[18:25], v[236:243], v[110:113]
	s_setprio 0
	s_setprio 1
	v_mfma_f32_16x16x128_f8f6f4 v[150:153], v[2:9], v[186:193], v[150:153]
	v_mfma_f32_16x16x128_f8f6f4 v[146:149], v[10:17], v[186:193], v[146:149]
	v_mfma_f32_16x16x128_f8f6f4 v[130:133], v[10:17], v[220:227], v[130:133]
	v_mfma_f32_16x16x128_f8f6f4 v[134:137], v[2:9], v[220:227], v[134:137]
	v_mfma_f32_16x16x128_f8f6f4 v[118:121], v[2:9], v[228:235], v[118:121]
	v_mfma_f32_16x16x128_f8f6f4 v[114:117], v[10:17], v[228:235], v[114:117]
	v_mfma_f32_16x16x128_f8f6f4 v[98:101], v[10:17], v[236:243], v[98:101]
	v_mfma_f32_16x16x128_f8f6f4 v[102:105], v[2:9], v[236:243], v[102:105]
	s_barrier
	s_setprio 0
	s_add_i32 s49, s42, s0
	s_mov_b32 m0, s49
	ds_read_b128 v[186:189], v184 offset:16384
	ds_read_b128 v[190:193], v184 offset:17408
	ds_read_b128 v[220:223], v184 offset:18432
	ds_read_b128 v[224:227], v184 offset:19456
	ds_read_b128 v[228:231], v184 offset:20480
	ds_read_b128 v[232:235], v184 offset:21504
	ds_read_b128 v[236:239], v184 offset:22528
	ds_read_b128 v[240:243], v184 offset:23552
	global_load_lds_dwordx4 v166, s[28:29]
	s_add_i32 m0, s49, 0x2000
	s_add_u32 s50, s28, 0x4000
	s_addc_u32 s51, s29, 0
	s_add_i32 s49, s43, s0
	global_load_lds_dwordx4 v162, s[28:29]
	s_mov_b32 m0, s49
	s_nop 0
	global_load_lds_dwordx4 v166, s[50:51]
	s_add_i32 m0, s49, 0x2000
	s_nop 0
	global_load_lds_dwordx4 v162, s[50:51]
	s_mov_b32 m0, s34
	s_nop 0
	global_load_lds_dwordx4 v168, s[30:31]
	s_mov_b32 m0, s35
	s_nop 0
	global_load_lds_dwordx4 v164, s[30:31]
	s_waitcnt vmcnt(8)
	s_waitcnt lgkmcnt(0)
	s_setprio 1
	s_barrier
	v_mfma_f32_16x16x128_f8f6f4 v[94:97], v[18:25], v[186:193], v[94:97]
	v_mfma_f32_16x16x128_f8f6f4 v[90:93], v[26:33], v[186:193], v[90:93]
	v_mfma_f32_16x16x128_f8f6f4 v[74:77], v[26:33], v[220:227], v[74:77]
	v_mfma_f32_16x16x128_f8f6f4 v[78:81], v[18:25], v[220:227], v[78:81]
	v_mfma_f32_16x16x128_f8f6f4 v[62:65], v[18:25], v[228:235], v[62:65]
	v_mfma_f32_16x16x128_f8f6f4 v[58:61], v[26:33], v[228:235], v[58:61]
	v_mfma_f32_16x16x128_f8f6f4 v[42:45], v[26:33], v[236:243], v[42:45]
	v_mfma_f32_16x16x128_f8f6f4 v[46:49], v[18:25], v[236:243], v[46:49]
	s_setprio 0
	s_setprio 1
	v_mfma_f32_16x16x128_f8f6f4 v[86:89], v[2:9], v[186:193], v[86:89]
	v_mfma_f32_16x16x128_f8f6f4 v[82:85], v[10:17], v[186:193], v[82:85]
	v_mfma_f32_16x16x128_f8f6f4 v[66:69], v[10:17], v[220:227], v[66:69]
	v_mfma_f32_16x16x128_f8f6f4 v[70:73], v[2:9], v[220:227], v[70:73]
	v_mfma_f32_16x16x128_f8f6f4 v[54:57], v[2:9], v[228:235], v[54:57]
	v_mfma_f32_16x16x128_f8f6f4 v[50:53], v[10:17], v[228:235], v[50:53]
	v_mfma_f32_16x16x128_f8f6f4 v[34:37], v[10:17], v[236:243], v[34:37]
	v_mfma_f32_16x16x128_f8f6f4 v[38:41], v[2:9], v[236:243], v[38:41]
	s_barrier
	s_setprio 0
	s_add_i32 s49, 0, 0x18000
	s_add_i32 s50, 0, 0x1c000
	v_add_u32_e32 v14, s49, v181
	v_add_u32_e32 v30, s50, v181
	ds_read_b128 v[2:5], v14
	ds_read_b128 v[6:9], v14 offset:1024
	ds_read_b128 v[10:13], v14 offset:2048
	ds_read_b128 v[14:17], v14 offset:3072
	ds_read_b128 v[18:21], v30
	ds_read_b128 v[22:25], v30 offset:1024
	ds_read_b128 v[26:29], v30 offset:2048
	ds_read_b128 v[30:33], v30 offset:3072
	s_add_u32 s30, s30, 0x4000
	s_addc_u32 s31, s31, 0
	s_mov_b32 m0, s36
	ds_read_b128 v[186:189], v184 offset:32768
	ds_read_b128 v[190:193], v184 offset:33792
	ds_read_b128 v[220:223], v184 offset:34816
	ds_read_b128 v[224:227], v184 offset:35840
	ds_read_b128 v[228:231], v184 offset:36864
	ds_read_b128 v[232:235], v184 offset:37888
	ds_read_b128 v[236:239], v184 offset:38912
	ds_read_b128 v[240:243], v184 offset:39936
	global_load_lds_dwordx4 v168, s[30:31]
	s_mov_b32 m0, s37
	s_nop 0
	global_load_lds_dwordx4 v164, s[30:31]
	s_waitcnt vmcnt(8)
	s_waitcnt lgkmcnt(0)
	s_setprio 1
	s_barrier
	v_mfma_f32_16x16x128_f8f6f4 v[158:161], v[2:9], v[186:193], v[158:161]
	v_mfma_f32_16x16x128_f8f6f4 v[154:157], v[10:17], v[186:193], v[154:157]
	v_mfma_f32_16x16x128_f8f6f4 v[138:141], v[10:17], v[220:227], v[138:141]
	v_mfma_f32_16x16x128_f8f6f4 v[142:145], v[2:9], v[220:227], v[142:145]
	v_mfma_f32_16x16x128_f8f6f4 v[126:129], v[2:9], v[228:235], v[126:129]
	v_mfma_f32_16x16x128_f8f6f4 v[122:125], v[10:17], v[228:235], v[122:125]
	v_mfma_f32_16x16x128_f8f6f4 v[106:109], v[10:17], v[236:243], v[106:109]
	v_mfma_f32_16x16x128_f8f6f4 v[110:113], v[2:9], v[236:243], v[110:113]
	s_setprio 0
	s_setprio 1
	v_mfma_f32_16x16x128_f8f6f4 v[150:153], v[18:25], v[186:193], v[150:153]
	v_mfma_f32_16x16x128_f8f6f4 v[146:149], v[26:33], v[186:193], v[146:149]
	v_mfma_f32_16x16x128_f8f6f4 v[130:133], v[26:33], v[220:227], v[130:133]
	v_mfma_f32_16x16x128_f8f6f4 v[134:137], v[18:25], v[220:227], v[134:137]
	v_mfma_f32_16x16x128_f8f6f4 v[118:121], v[18:25], v[228:235], v[118:121]
	v_mfma_f32_16x16x128_f8f6f4 v[114:117], v[26:33], v[228:235], v[114:117]
	v_mfma_f32_16x16x128_f8f6f4 v[98:101], v[26:33], v[236:243], v[98:101]
	v_mfma_f32_16x16x128_f8f6f4 v[102:105], v[18:25], v[236:243], v[102:105]
	s_barrier
	s_setprio 0
	s_add_u32 s30, s28, 0x380000
	s_addc_u32 s31, s29, 0
	s_add_i32 s49, s49, s0
	s_mov_b32 m0, s49
	ds_read_b128 v[186:189], v184 offset:49152
	ds_read_b128 v[190:193], v184 offset:50176
	ds_read_b128 v[220:223], v184 offset:51200
	ds_read_b128 v[224:227], v184 offset:52224
	ds_read_b128 v[228:231], v184 offset:53248
	ds_read_b128 v[232:235], v184 offset:54272
	ds_read_b128 v[236:239], v184 offset:55296
	ds_read_b128 v[240:243], v184 offset:56320
	global_load_lds_dwordx4 v166, s[30:31]
	s_add_i32 m0, s49, 0x2000
	s_add_u32 s28, s28, 0x384000
	s_addc_u32 s29, s29, 0
	global_load_lds_dwordx4 v162, s[30:31]
	s_add_i32 s30, s50, s0
	s_mov_b32 m0, s30
	s_nop 0
	global_load_lds_dwordx4 v166, s[28:29]
	s_add_i32 m0, s30, 0x2000
	s_nop 0
	global_load_lds_dwordx4 v162, s[28:29]
	s_mov_b32 m0, s40
	s_nop 0
	global_load_lds_dwordx4 v168, s[26:27]
	s_mov_b32 m0, s41
	s_nop 0
	global_load_lds_dwordx4 v164, s[26:27]
	s_waitcnt vmcnt(8)
	s_waitcnt lgkmcnt(0)
	s_setprio 1
	s_barrier
	v_mfma_f32_16x16x128_f8f6f4 v[94:97], v[2:9], v[186:193], v[94:97]
	v_mfma_f32_16x16x128_f8f6f4 v[90:93], v[10:17], v[186:193], v[90:93]
	v_mfma_f32_16x16x128_f8f6f4 v[74:77], v[10:17], v[220:227], v[74:77]
	v_mfma_f32_16x16x128_f8f6f4 v[78:81], v[2:9], v[220:227], v[78:81]
	v_mfma_f32_16x16x128_f8f6f4 v[62:65], v[2:9], v[228:235], v[62:65]
	v_mfma_f32_16x16x128_f8f6f4 v[58:61], v[10:17], v[228:235], v[58:61]
	v_mfma_f32_16x16x128_f8f6f4 v[42:45], v[10:17], v[236:243], v[42:45]
	v_mfma_f32_16x16x128_f8f6f4 v[46:49], v[2:9], v[236:243], v[46:49]
	s_setprio 0
	s_setprio 1
	v_mfma_f32_16x16x128_f8f6f4 v[86:89], v[18:25], v[186:193], v[86:89]
	v_mfma_f32_16x16x128_f8f6f4 v[82:85], v[26:33], v[186:193], v[82:85]
	v_mfma_f32_16x16x128_f8f6f4 v[66:69], v[26:33], v[220:227], v[66:69]
	v_mfma_f32_16x16x128_f8f6f4 v[70:73], v[18:25], v[220:227], v[70:73]
	v_mfma_f32_16x16x128_f8f6f4 v[54:57], v[18:25], v[228:235], v[54:57]
	v_mfma_f32_16x16x128_f8f6f4 v[50:53], v[26:33], v[228:235], v[50:53]
	v_mfma_f32_16x16x128_f8f6f4 v[34:37], v[26:33], v[236:243], v[34:37]
	v_mfma_f32_16x16x128_f8f6f4 v[38:41], v[18:25], v[236:243], v[38:41]
	s_barrier
	s_setprio 0
	s_add_i32 s48, s48, 2
	s_add_u32 s46, s46, 0x700000
	s_addc_u32 s47, s47, 0
	s_add_u32 s24, s24, 0x200000
	s_addc_u32 s25, s25, 0
	s_cmp_gt_u32 s48, 29
	s_cbranch_scc0 .LBB0_2480
	s_and_b64 vcc, exec, s[8:9]
	s_cbranch_vccz .LBB0_2483
	s_barrier

.LBB0_2714:
	ds_read_b128 v[18:21], v180
	ds_read_b128 v[22:25], v180 offset:1024
	ds_read_b128 v[26:29], v180 offset:2048
	ds_read_b128 v[30:33], v180 offset:3072
	s_waitcnt lgkmcnt(0)
	ds_read_b128 v[2:5], v181
	ds_read_b128 v[6:9], v181 offset:1024
	ds_read_b128 v[10:13], v181 offset:2048
	ds_read_b128 v[14:17], v181 offset:3072
	s_add_u32 s24, s22, 0xfc000
	s_addc_u32 s25, s23, 0
	s_cmpk_eq_i32 s44, 0x6c
	s_cselect_b32 s28, s17, s24
	s_cselect_b32 s29, s5, s25
	s_cselect_b32 s26, s41, s42
	s_cselect_b32 s27, s15, s43
	s_add_u32 s24, s28, 0x100000
	s_addc_u32 s25, s29, 0
	s_add_i32 m0, s1, 0xc000
	ds_read_b128 v[184:187], v182
	ds_read_b128 v[188:191], v182 offset:1024
	ds_read_b128 v[192:195], v182 offset:2048
	ds_read_b128 v[196:199], v182 offset:3072
	ds_read_b128 v[220:223], v182 offset:4096
	ds_read_b128 v[224:227], v182 offset:5120
	ds_read_b128 v[228:231], v182 offset:6144
	ds_read_b128 v[232:235], v182 offset:7168
	global_load_lds_dwordx4 v170, s[22:23]
	s_add_i32 m0, s1, 0xe000
	s_nop 0
	global_load_lds_dwordx4 v172, s[22:23]
	s_waitcnt vmcnt(8)
	s_waitcnt lgkmcnt(0)
	s_setprio 1
	s_barrier
	v_mfma_f32_16x16x128_f8f6f4 v[158:161], v[18:25], v[184:191], v[158:161]
	v_mfma_f32_16x16x128_f8f6f4 v[154:157], v[26:33], v[184:191], v[154:157]
	v_mfma_f32_16x16x128_f8f6f4 v[138:141], v[26:33], v[192:199], v[138:141]
	v_mfma_f32_16x16x128_f8f6f4 v[142:145], v[18:25], v[192:199], v[142:145]
	v_mfma_f32_16x16x128_f8f6f4 v[126:129], v[18:25], v[220:227], v[126:129]
	v_mfma_f32_16x16x128_f8f6f4 v[122:125], v[26:33], v[220:227], v[122:125]
	v_mfma_f32_16x16x128_f8f6f4 v[106:109], v[26:33], v[228:235], v[106:109]
	v_mfma_f32_16x16x128_f8f6f4 v[110:113], v[18:25], v[228:235], v[110:113]
	s_setprio 0
	s_setprio 1
	v_mfma_f32_16x16x128_f8f6f4 v[150:153], v[2:9], v[184:191], v[150:153]
	v_mfma_f32_16x16x128_f8f6f4 v[146:149], v[10:17], v[184:191], v[146:149]
	v_mfma_f32_16x16x128_f8f6f4 v[130:133], v[10:17], v[192:199], v[130:133]
	v_mfma_f32_16x16x128_f8f6f4 v[134:137], v[2:9], v[192:199], v[134:137]
	v_mfma_f32_16x16x128_f8f6f4 v[118:121], v[2:9], v[220:227], v[118:121]
	v_mfma_f32_16x16x128_f8f6f4 v[114:117], v[10:17], v[220:227], v[114:117]
	v_mfma_f32_16x16x128_f8f6f4 v[98:101], v[10:17], v[228:235], v[98:101]
	v_mfma_f32_16x16x128_f8f6f4 v[102:105], v[2:9], v[228:235], v[102:105]
	s_barrier
	s_setprio 0
	s_add_i32 s45, s38, s0
	s_mov_b32 m0, s45
	ds_read_b128 v[184:187], v182 offset:16384
	ds_read_b128 v[188:191], v182 offset:17408
	ds_read_b128 v[192:195], v182 offset:18432
	ds_read_b128 v[196:199], v182 offset:19456
	ds_read_b128 v[220:223], v182 offset:20480
	ds_read_b128 v[224:227], v182 offset:21504
	ds_read_b128 v[228:231], v182 offset:22528
	ds_read_b128 v[232:235], v182 offset:23552
	global_load_lds_dwordx4 v164, s[26:27]
	s_add_i32 m0, s45, 0x2000
	s_add_u32 s46, s26, 0x4000
	s_addc_u32 s47, s27, 0
	s_add_i32 s45, s39, s0
	global_load_lds_dwordx4 v168, s[26:27]
	s_mov_b32 m0, s45
	s_nop 0
	global_load_lds_dwordx4 v164, s[46:47]
	s_add_i32 m0, s45, 0x2000
	s_nop 0
	global_load_lds_dwordx4 v168, s[46:47]
	s_mov_b32 m0, s1
	s_nop 0
	global_load_lds_dwordx4 v162, s[28:29]
	s_mov_b32 m0, s13
	s_nop 0
	global_load_lds_dwordx4 v166, s[28:29]
	s_waitcnt vmcnt(8)
	s_waitcnt lgkmcnt(0)
	s_setprio 1
	s_barrier
	v_mfma_f32_16x16x128_f8f6f4 v[94:97], v[18:25], v[184:191], v[94:97]
	v_mfma_f32_16x16x128_f8f6f4 v[90:93], v[26:33], v[184:191], v[90:93]
	v_mfma_f32_16x16x128_f8f6f4 v[74:77], v[26:33], v[192:199], v[74:77]
	v_mfma_f32_16x16x128_f8f6f4 v[78:81], v[18:25], v[192:199], v[78:81]
	v_mfma_f32_16x16x128_f8f6f4 v[62:65], v[18:25], v[220:227], v[62:65]
	v_mfma_f32_16x16x128_f8f6f4 v[58:61], v[26:33], v[220:227], v[58:61]
	v_mfma_f32_16x16x128_f8f6f4 v[42:45], v[26:33], v[228:235], v[42:45]
	v_mfma_f32_16x16x128_f8f6f4 v[46:49], v[18:25], v[228:235], v[46:49]
	s_setprio 0
	s_setprio 1
	v_mfma_f32_16x16x128_f8f6f4 v[86:89], v[2:9], v[184:191], v[86:89]
	v_mfma_f32_16x16x128_f8f6f4 v[82:85], v[10:17], v[184:191], v[82:85]
	v_mfma_f32_16x16x128_f8f6f4 v[66:69], v[10:17], v[192:199], v[66:69]
	v_mfma_f32_16x16x128_f8f6f4 v[70:73], v[2:9], v[192:199], v[70:73]
	v_mfma_f32_16x16x128_f8f6f4 v[54:57], v[2:9], v[220:227], v[54:57]
	v_mfma_f32_16x16x128_f8f6f4 v[50:53], v[10:17], v[220:227], v[50:53]
	v_mfma_f32_16x16x128_f8f6f4 v[34:37], v[10:17], v[228:235], v[34:37]
	v_mfma_f32_16x16x128_f8f6f4 v[38:41], v[2:9], v[228:235], v[38:41]
	s_barrier
	s_setprio 0
	s_add_i32 s45, 0, 0x18000
	s_add_i32 s46, 0, 0x1c000
	v_add_u32_e32 v14, s45, v179
	v_add_u32_e32 v30, s46, v179
	ds_read_b128 v[2:5], v14
	ds_read_b128 v[6:9], v14 offset:1024
	ds_read_b128 v[10:13], v14 offset:2048
	ds_read_b128 v[14:17], v14 offset:3072
	ds_read_b128 v[18:21], v30
	ds_read_b128 v[22:25], v30 offset:1024
	ds_read_b128 v[26:29], v30 offset:2048
	ds_read_b128 v[30:33], v30 offset:3072
	s_add_u32 s28, s28, 0x4000
	s_addc_u32 s29, s29, 0
	s_mov_b32 m0, s30
	ds_read_b128 v[184:187], v182 offset:32768
	ds_read_b128 v[188:191], v182 offset:33792
	ds_read_b128 v[192:195], v182 offset:34816
	ds_read_b128 v[196:199], v182 offset:35840
	ds_read_b128 v[220:223], v182 offset:36864
	ds_read_b128 v[224:227], v182 offset:37888
	ds_read_b128 v[228:231], v182 offset:38912
	ds_read_b128 v[232:235], v182 offset:39936
	global_load_lds_dwordx4 v162, s[28:29]
	s_mov_b32 m0, s31
	s_nop 0
	global_load_lds_dwordx4 v166, s[28:29]
	s_waitcnt vmcnt(8)
	s_waitcnt lgkmcnt(0)
	s_setprio 1
	s_barrier
	v_mfma_f32_16x16x128_f8f6f4 v[158:161], v[2:9], v[184:191], v[158:161]
	v_mfma_f32_16x16x128_f8f6f4 v[154:157], v[10:17], v[184:191], v[154:157]
	v_mfma_f32_16x16x128_f8f6f4 v[138:141], v[10:17], v[192:199], v[138:141]
	v_mfma_f32_16x16x128_f8f6f4 v[142:145], v[2:9], v[192:199], v[142:145]
	v_mfma_f32_16x16x128_f8f6f4 v[126:129], v[2:9], v[220:227], v[126:129]
	v_mfma_f32_16x16x128_f8f6f4 v[122:125], v[10:17], v[220:227], v[122:125]
	v_mfma_f32_16x16x128_f8f6f4 v[106:109], v[10:17], v[228:235], v[106:109]
	v_mfma_f32_16x16x128_f8f6f4 v[110:113], v[2:9], v[228:235], v[110:113]
	s_setprio 0
	s_setprio 1
	v_mfma_f32_16x16x128_f8f6f4 v[150:153], v[18:25], v[184:191], v[150:153]
	v_mfma_f32_16x16x128_f8f6f4 v[146:149], v[26:33], v[184:191], v[146:149]
	v_mfma_f32_16x16x128_f8f6f4 v[130:133], v[26:33], v[192:199], v[130:133]
	v_mfma_f32_16x16x128_f8f6f4 v[134:137], v[18:25], v[192:199], v[134:137]
	v_mfma_f32_16x16x128_f8f6f4 v[118:121], v[18:25], v[220:227], v[118:121]
	v_mfma_f32_16x16x128_f8f6f4 v[114:117], v[26:33], v[220:227], v[114:117]
	v_mfma_f32_16x16x128_f8f6f4 v[98:101], v[26:33], v[228:235], v[98:101]
	v_mfma_f32_16x16x128_f8f6f4 v[102:105], v[18:25], v[228:235], v[102:105]
	s_barrier
	s_setprio 0
	s_add_u32 s28, s26, 0x80000
	s_addc_u32 s29, s27, 0
	s_add_i32 s45, s45, s0
	s_mov_b32 m0, s45
	ds_read_b128 v[184:187], v182 offset:49152
	ds_read_b128 v[188:191], v182 offset:50176
	ds_read_b128 v[192:195], v182 offset:51200
	ds_read_b128 v[196:199], v182 offset:52224
	ds_read_b128 v[220:223], v182 offset:53248
	ds_read_b128 v[224:227], v182 offset:54272
	ds_read_b128 v[228:231], v182 offset:55296
	ds_read_b128 v[232:235], v182 offset:56320
	global_load_lds_dwordx4 v164, s[28:29]
	s_add_i32 m0, s45, 0x2000
	s_add_u32 s26, s26, 0x84000
	s_addc_u32 s27, s27, 0
	global_load_lds_dwordx4 v168, s[28:29]
	s_add_i32 s28, s46, s0
	s_mov_b32 m0, s28
	s_nop 0
	global_load_lds_dwordx4 v164, s[26:27]
	s_add_i32 m0, s28, 0x2000
	s_nop 0
	global_load_lds_dwordx4 v168, s[26:27]
	s_mov_b32 m0, s36
	s_nop 0
	global_load_lds_dwordx4 v162, s[24:25]
	s_mov_b32 m0, s37
	s_nop 0
	global_load_lds_dwordx4 v166, s[24:25]
	s_waitcnt vmcnt(8)
	s_waitcnt lgkmcnt(0)
	s_setprio 1
	s_barrier
	v_mfma_f32_16x16x128_f8f6f4 v[94:97], v[2:9], v[184:191], v[94:97]
	v_mfma_f32_16x16x128_f8f6f4 v[90:93], v[10:17], v[184:191], v[90:93]
	v_mfma_f32_16x16x128_f8f6f4 v[74:77], v[10:17], v[192:199], v[74:77]
	v_mfma_f32_16x16x128_f8f6f4 v[78:81], v[2:9], v[192:199], v[78:81]
	v_mfma_f32_16x16x128_f8f6f4 v[62:65], v[2:9], v[220:227], v[62:65]
	v_mfma_f32_16x16x128_f8f6f4 v[58:61], v[10:17], v[220:227], v[58:61]
	v_mfma_f32_16x16x128_f8f6f4 v[42:45], v[10:17], v[228:235], v[42:45]
	v_mfma_f32_16x16x128_f8f6f4 v[46:49], v[2:9], v[228:235], v[46:49]
	s_setprio 0
	s_setprio 1
	v_mfma_f32_16x16x128_f8f6f4 v[86:89], v[18:25], v[184:191], v[86:89]
	v_mfma_f32_16x16x128_f8f6f4 v[82:85], v[26:33], v[184:191], v[82:85]
	v_mfma_f32_16x16x128_f8f6f4 v[66:69], v[26:33], v[192:199], v[66:69]
	v_mfma_f32_16x16x128_f8f6f4 v[70:73], v[18:25], v[192:199], v[70:73]
	v_mfma_f32_16x16x128_f8f6f4 v[54:57], v[18:25], v[220:227], v[54:57]
	v_mfma_f32_16x16x128_f8f6f4 v[50:53], v[26:33], v[220:227], v[50:53]
	v_mfma_f32_16x16x128_f8f6f4 v[34:37], v[26:33], v[228:235], v[34:37]
	v_mfma_f32_16x16x128_f8f6f4 v[38:41], v[18:25], v[228:235], v[38:41]
	s_barrier
	s_setprio 0
	s_add_i32 s44, s44, 2
	s_add_u32 s42, s42, 0x100000
	s_addc_u32 s43, s43, 0
	s_add_u32 s22, s22, 0x200000
	s_addc_u32 s23, s23, 0
	s_cmpk_gt_u32 s44, 0x6d
	s_cbranch_scc0 .LBB0_2714
	s_and_b64 vcc, exec, s[10:11]
	s_cbranch_vccz .LBB0_2717
	s_barrier
